# GEMM K-loops: LDS-DMA switched to SGPR-base + 32-bit VGPR offset form, 150 64-bit address VALU adds deleted (+0x80 via scratch SGPR pair); on top of softmax trim
# speedup vs baseline: 1.0042x; 1.0042x over previous
.LBB0_35:
	s_add_u32 s0, s8, 0xfff80080
	s_addc_u32 s1, s9, -1
	s_add_i32 s2, 0, 0x10000
	v_add_u32_e32 v138, s2, v182
	ds_read_b128 v[154:157], v138
	ds_read_b128 v[158:161], v138 offset:1024
	ds_read_b128 v[162:165], v138 offset:2048
	ds_read_b128 v[166:169], v138 offset:3072
	s_cmp_eq_u32 s15, 28
	s_cselect_b32 s65, s67, s1
	s_cselect_b32 s64, s66, s0
	s_cselect_b32 s1, s45, s13
	s_cselect_b32 s0, s44, s11
	s_add_i32 m0, s17, 0xc000
	ds_read_b128 v[170:173], v183
	ds_read_b128 v[174:177], v183 offset:1024
	ds_read_b128 v[178:181], v183 offset:2048
	ds_read_b128 v[184:187], v183 offset:3072
	ds_read_b128 v[188:191], v183 offset:4096
	ds_read_b128 v[192:195], v183 offset:5120
	ds_read_b128 v[196:199], v183 offset:6144
	ds_read_b128 v[200:203], v183 offset:7168
	global_load_lds_dwordx4 v136, s[8:9]
	s_add_i32 m0, s17, 0xe000
	s_nop 0
	global_load_lds_dwordx4 v134, s[8:9]
	s_waitcnt lgkmcnt(8)
	s_barrier
	s_waitcnt lgkmcnt(0)
	s_setprio 1
	s_waitcnt lgkmcnt(0)
	v_mfma_f32_16x16x32_bf16 v[124:127], v[154:157], v[170:173], v[124:127]
	v_mfma_f32_16x16x32_bf16 v[92:95], v[162:165], v[170:173], v[92:95]
	v_mfma_f32_16x16x32_bf16 v[120:123], v[154:157], v[178:181], v[120:123]
	v_mfma_f32_16x16x32_bf16 v[88:91], v[162:165], v[178:181], v[88:91]
	v_mfma_f32_16x16x32_bf16 v[116:119], v[154:157], v[188:191], v[116:119]
	v_mfma_f32_16x16x32_bf16 v[84:87], v[162:165], v[188:191], v[84:87]
	v_mfma_f32_16x16x32_bf16 v[112:115], v[154:157], v[196:199], v[112:115]
	v_mfma_f32_16x16x32_bf16 v[80:83], v[162:165], v[196:199], v[80:83]
	v_mfma_f32_16x16x32_bf16 v[124:127], v[158:161], v[174:177], v[124:127]
	v_mfma_f32_16x16x32_bf16 v[92:95], v[166:169], v[174:177], v[92:95]
	v_mfma_f32_16x16x32_bf16 v[120:123], v[158:161], v[184:187], v[120:123]
	v_mfma_f32_16x16x32_bf16 v[88:91], v[166:169], v[184:187], v[88:91]
	v_mfma_f32_16x16x32_bf16 v[116:119], v[158:161], v[192:195], v[116:119]
	v_mfma_f32_16x16x32_bf16 v[84:87], v[166:169], v[192:195], v[84:87]
	v_mfma_f32_16x16x32_bf16 v[112:115], v[158:161], v[200:203], v[112:115]
	v_mfma_f32_16x16x32_bf16 v[80:83], v[166:169], v[200:203], v[80:83]
	s_setprio 0
	s_barrier
	s_add_i32 s20, 0, 0x14000
	v_add_u32_e32 v138, s20, v182
	s_add_i32 s2, s2, s69
	ds_read_b128 v[204:207], v138
	ds_read_b128 v[208:211], v138 offset:1024
	ds_read_b128 v[228:231], v138 offset:2048
	ds_read_b128 v[232:235], v138 offset:3072
	s_mov_b32 m0, s2
	s_nop 0
	global_load_lds_dwordx4 v140, s[0:1]
	s_add_i32 m0, s2, 0x2000
	s_nop 0
	global_load_lds_dwordx4 v132, s[0:1]
	s_barrier
	s_waitcnt lgkmcnt(0)
	s_setprio 1
	s_waitcnt lgkmcnt(0)
	v_mfma_f32_16x16x32_bf16 v[60:63], v[204:207], v[170:173], v[60:63]
	v_mfma_f32_16x16x32_bf16 v[28:31], v[228:231], v[170:173], v[28:31]
	v_mfma_f32_16x16x32_bf16 v[56:59], v[204:207], v[178:181], v[56:59]
	v_mfma_f32_16x16x32_bf16 v[24:27], v[228:231], v[178:181], v[24:27]
	v_mfma_f32_16x16x32_bf16 v[52:55], v[204:207], v[188:191], v[52:55]
	v_mfma_f32_16x16x32_bf16 v[20:23], v[228:231], v[188:191], v[20:23]
	v_mfma_f32_16x16x32_bf16 v[48:51], v[204:207], v[196:199], v[48:51]
	v_mfma_f32_16x16x32_bf16 v[16:19], v[228:231], v[196:199], v[16:19]
	v_mfma_f32_16x16x32_bf16 v[60:63], v[208:211], v[174:177], v[60:63]
	v_mfma_f32_16x16x32_bf16 v[28:31], v[232:235], v[174:177], v[28:31]
	v_mfma_f32_16x16x32_bf16 v[56:59], v[208:211], v[184:187], v[56:59]
	v_mfma_f32_16x16x32_bf16 v[24:27], v[232:235], v[184:187], v[24:27]
	v_mfma_f32_16x16x32_bf16 v[52:55], v[208:211], v[192:195], v[52:55]
	v_mfma_f32_16x16x32_bf16 v[20:23], v[232:235], v[192:195], v[20:23]
	v_mfma_f32_16x16x32_bf16 v[48:51], v[208:211], v[200:203], v[48:51]
	v_mfma_f32_16x16x32_bf16 v[16:19], v[232:235], v[200:203], v[16:19]
	s_setprio 0
	s_mov_b32 m0, s17
	s_barrier
	ds_read_b128 v[170:173], v183 offset:16384
	ds_read_b128 v[174:177], v183 offset:17408
	ds_read_b128 v[178:181], v183 offset:18432
	ds_read_b128 v[184:187], v183 offset:19456
	ds_read_b128 v[188:191], v183 offset:20480
	ds_read_b128 v[192:195], v183 offset:21504
	ds_read_b128 v[196:199], v183 offset:22528
	ds_read_b128 v[200:203], v183 offset:23552
	global_load_lds_dwordx4 v128, s[64:65]
	s_mov_b32 m0, s71
	s_nop 0
	global_load_lds_dwordx4 v130, s[64:65]
	s_barrier
	s_waitcnt lgkmcnt(0)
	s_setprio 1
	s_waitcnt lgkmcnt(0)
	v_mfma_f32_16x16x32_bf16 v[108:111], v[154:157], v[170:173], v[108:111]
	v_mfma_f32_16x16x32_bf16 v[76:79], v[162:165], v[170:173], v[76:79]
	v_mfma_f32_16x16x32_bf16 v[104:107], v[154:157], v[178:181], v[104:107]
	v_mfma_f32_16x16x32_bf16 v[72:75], v[162:165], v[178:181], v[72:75]
	v_mfma_f32_16x16x32_bf16 v[100:103], v[154:157], v[188:191], v[100:103]
	v_mfma_f32_16x16x32_bf16 v[68:71], v[162:165], v[188:191], v[68:71]
	v_mfma_f32_16x16x32_bf16 v[96:99], v[154:157], v[196:199], v[96:99]
	v_mfma_f32_16x16x32_bf16 v[64:67], v[162:165], v[196:199], v[64:67]
	v_mfma_f32_16x16x32_bf16 v[108:111], v[158:161], v[174:177], v[108:111]
	v_mfma_f32_16x16x32_bf16 v[76:79], v[166:169], v[174:177], v[76:79]
	v_mfma_f32_16x16x32_bf16 v[104:107], v[158:161], v[184:187], v[104:107]
	v_mfma_f32_16x16x32_bf16 v[72:75], v[166:169], v[184:187], v[72:75]
	v_mfma_f32_16x16x32_bf16 v[100:103], v[158:161], v[192:195], v[100:103]
	v_mfma_f32_16x16x32_bf16 v[68:71], v[166:169], v[192:195], v[68:71]
	v_mfma_f32_16x16x32_bf16 v[96:99], v[158:161], v[200:203], v[96:99]
	v_mfma_f32_16x16x32_bf16 v[64:67], v[166:169], v[200:203], v[64:67]
	s_setprio 0
	s_barrier
	s_add_u32 s18, s0, 0x100000
	s_addc_u32 s19, s1, 0
	s_add_i32 s2, s20, s69
	s_mov_b32 m0, s2
	s_nop 0
	global_load_lds_dwordx4 v140, s[18:19]
	s_add_i32 m0, s2, 0x2000
	s_nop 0
	global_load_lds_dwordx4 v132, s[18:19]
	s_waitcnt vmcnt(6)
	s_barrier
	s_setprio 1
	v_mfma_f32_16x16x32_bf16 v[44:47], v[204:207], v[170:173], v[44:47]
	v_mfma_f32_16x16x32_bf16 v[12:15], v[228:231], v[170:173], v[12:15]
	v_mfma_f32_16x16x32_bf16 v[40:43], v[204:207], v[178:181], v[40:43]
	v_mfma_f32_16x16x32_bf16 v[8:11], v[228:231], v[178:181], v[8:11]
	v_mfma_f32_16x16x32_bf16 v[36:39], v[204:207], v[188:191], v[36:39]
	v_mfma_f32_16x16x32_bf16 v[4:7], v[228:231], v[188:191], v[4:7]
	v_mfma_f32_16x16x32_bf16 v[32:35], v[204:207], v[196:199], v[32:35]
	v_mfma_f32_16x16x32_bf16 v[0:3], v[228:231], v[196:199], v[0:3]
	v_mfma_f32_16x16x32_bf16 v[44:47], v[208:211], v[174:177], v[44:47]
	v_mfma_f32_16x16x32_bf16 v[12:15], v[232:235], v[174:177], v[12:15]
	v_mfma_f32_16x16x32_bf16 v[40:43], v[208:211], v[184:187], v[40:43]
	v_mfma_f32_16x16x32_bf16 v[8:11], v[232:235], v[184:187], v[8:11]
	v_mfma_f32_16x16x32_bf16 v[36:39], v[208:211], v[192:195], v[36:39]
	v_mfma_f32_16x16x32_bf16 v[4:7], v[232:235], v[192:195], v[4:7]
	v_mfma_f32_16x16x32_bf16 v[32:35], v[208:211], v[200:203], v[32:35]
	v_mfma_f32_16x16x32_bf16 v[0:3], v[232:235], v[200:203], v[0:3]
	s_setprio 0
	s_add_i32 s2, 0, 0x18000
	v_add_u32_e32 v166, s2, v182
	s_barrier
	ds_read_b128 v[154:157], v166
	ds_read_b128 v[158:161], v166 offset:1024
	ds_read_b128 v[162:165], v166 offset:2048
	ds_read_b128 v[166:169], v166 offset:3072
	s_add_u32 s18, s64, 0x80000
	s_addc_u32 s19, s65, 0
	s_mov_b32 m0, s72
	ds_read_b128 v[170:173], v183 offset:32768
	ds_read_b128 v[174:177], v183 offset:33792
	ds_read_b128 v[178:181], v183 offset:34816
	ds_read_b128 v[184:187], v183 offset:35840
	ds_read_b128 v[188:191], v183 offset:36864
	ds_read_b128 v[192:195], v183 offset:37888
	ds_read_b128 v[196:199], v183 offset:38912
	ds_read_b128 v[200:203], v183 offset:39936
	global_load_lds_dwordx4 v128, s[18:19]
	s_mov_b32 m0, s73
	s_nop 0
	global_load_lds_dwordx4 v130, s[18:19]
	s_waitcnt lgkmcnt(8)
	s_barrier
	s_waitcnt lgkmcnt(0)
	s_setprio 1
	s_waitcnt lgkmcnt(0)
	v_mfma_f32_16x16x32_bf16 v[124:127], v[154:157], v[170:173], v[124:127]
	v_mfma_f32_16x16x32_bf16 v[92:95], v[162:165], v[170:173], v[92:95]
	v_mfma_f32_16x16x32_bf16 v[120:123], v[154:157], v[178:181], v[120:123]
	v_mfma_f32_16x16x32_bf16 v[88:91], v[162:165], v[178:181], v[88:91]
	v_mfma_f32_16x16x32_bf16 v[116:119], v[154:157], v[188:191], v[116:119]
	v_mfma_f32_16x16x32_bf16 v[84:87], v[162:165], v[188:191], v[84:87]
	v_mfma_f32_16x16x32_bf16 v[112:115], v[154:157], v[196:199], v[112:115]
	v_mfma_f32_16x16x32_bf16 v[80:83], v[162:165], v[196:199], v[80:83]
	v_mfma_f32_16x16x32_bf16 v[124:127], v[158:161], v[174:177], v[124:127]
	v_mfma_f32_16x16x32_bf16 v[92:95], v[166:169], v[174:177], v[92:95]
	v_mfma_f32_16x16x32_bf16 v[120:123], v[158:161], v[184:187], v[120:123]
	v_mfma_f32_16x16x32_bf16 v[88:91], v[166:169], v[184:187], v[88:91]
	v_mfma_f32_16x16x32_bf16 v[116:119], v[158:161], v[192:195], v[116:119]
	v_mfma_f32_16x16x32_bf16 v[84:87], v[166:169], v[192:195], v[84:87]
	v_mfma_f32_16x16x32_bf16 v[112:115], v[158:161], v[200:203], v[112:115]
	v_mfma_f32_16x16x32_bf16 v[80:83], v[166:169], v[200:203], v[80:83]
	s_setprio 0
	s_barrier
	s_add_i32 s18, 0, 0x1c000
	s_add_i32 s2, s2, s69
	v_add_u32_e32 v232, s18, v182
	s_mov_b32 m0, s2
	ds_read_b128 v[204:207], v232
	ds_read_b128 v[208:211], v232 offset:1024
	ds_read_b128 v[228:231], v232 offset:2048
	ds_read_b128 v[232:235], v232 offset:3072
	s_add_u32 s100, s0, 0x80
	s_addc_u32 s101, s1, 0
	global_load_lds_dwordx4 v140, s[100:101]
	s_add_i32 m0, s2, 0x2000
	s_nop 0
	global_load_lds_dwordx4 v132, s[100:101]
	s_barrier
	s_waitcnt lgkmcnt(0)
	s_setprio 1
	s_waitcnt lgkmcnt(0)
	v_mfma_f32_16x16x32_bf16 v[60:63], v[204:207], v[170:173], v[60:63]
	v_mfma_f32_16x16x32_bf16 v[28:31], v[228:231], v[170:173], v[28:31]
	v_mfma_f32_16x16x32_bf16 v[56:59], v[204:207], v[178:181], v[56:59]
	v_mfma_f32_16x16x32_bf16 v[24:27], v[228:231], v[178:181], v[24:27]
	v_mfma_f32_16x16x32_bf16 v[52:55], v[204:207], v[188:191], v[52:55]
	v_mfma_f32_16x16x32_bf16 v[20:23], v[228:231], v[188:191], v[20:23]
	v_mfma_f32_16x16x32_bf16 v[48:51], v[204:207], v[196:199], v[48:51]
	v_mfma_f32_16x16x32_bf16 v[16:19], v[228:231], v[196:199], v[16:19]
	v_mfma_f32_16x16x32_bf16 v[60:63], v[208:211], v[174:177], v[60:63]
	v_mfma_f32_16x16x32_bf16 v[28:31], v[232:235], v[174:177], v[28:31]
	v_mfma_f32_16x16x32_bf16 v[56:59], v[208:211], v[184:187], v[56:59]
	v_mfma_f32_16x16x32_bf16 v[24:27], v[232:235], v[184:187], v[24:27]
	v_mfma_f32_16x16x32_bf16 v[52:55], v[208:211], v[192:195], v[52:55]
	v_mfma_f32_16x16x32_bf16 v[20:23], v[232:235], v[192:195], v[20:23]
	v_mfma_f32_16x16x32_bf16 v[48:51], v[208:211], v[200:203], v[48:51]
	v_mfma_f32_16x16x32_bf16 v[16:19], v[232:235], v[200:203], v[16:19]
	s_setprio 0
	s_mov_b32 m0, s77
	s_barrier
	ds_read_b128 v[170:173], v183 offset:49152
	ds_read_b128 v[174:177], v183 offset:50176
	ds_read_b128 v[178:181], v183 offset:51200
	ds_read_b128 v[184:187], v183 offset:52224
	ds_read_b128 v[188:191], v183 offset:53248
	ds_read_b128 v[192:195], v183 offset:54272
	ds_read_b128 v[196:199], v183 offset:55296
	ds_read_b128 v[200:203], v183 offset:56320
	s_add_u32 s100, s64, 0x80
	s_addc_u32 s101, s65, 0
	global_load_lds_dwordx4 v128, s[100:101]
	s_mov_b32 m0, s80
	s_nop 0
	global_load_lds_dwordx4 v130, s[100:101]
	s_barrier
	s_waitcnt lgkmcnt(0)
	s_setprio 1
	s_waitcnt lgkmcnt(0)
	v_mfma_f32_16x16x32_bf16 v[108:111], v[154:157], v[170:173], v[108:111]
	v_mfma_f32_16x16x32_bf16 v[76:79], v[162:165], v[170:173], v[76:79]
	v_mfma_f32_16x16x32_bf16 v[104:107], v[154:157], v[178:181], v[104:107]
	v_mfma_f32_16x16x32_bf16 v[72:75], v[162:165], v[178:181], v[72:75]
	v_mfma_f32_16x16x32_bf16 v[100:103], v[154:157], v[188:191], v[100:103]
	v_mfma_f32_16x16x32_bf16 v[68:71], v[162:165], v[188:191], v[68:71]
	v_mfma_f32_16x16x32_bf16 v[96:99], v[154:157], v[196:199], v[96:99]
	v_mfma_f32_16x16x32_bf16 v[64:67], v[162:165], v[196:199], v[64:67]
	v_mfma_f32_16x16x32_bf16 v[108:111], v[158:161], v[174:177], v[108:111]
	v_mfma_f32_16x16x32_bf16 v[76:79], v[166:169], v[174:177], v[76:79]
	v_mfma_f32_16x16x32_bf16 v[104:107], v[158:161], v[184:187], v[104:107]
	v_mfma_f32_16x16x32_bf16 v[72:75], v[166:169], v[184:187], v[72:75]
	v_mfma_f32_16x16x32_bf16 v[100:103], v[158:161], v[192:195], v[100:103]
	v_mfma_f32_16x16x32_bf16 v[68:71], v[166:169], v[192:195], v[68:71]
	v_mfma_f32_16x16x32_bf16 v[96:99], v[158:161], v[200:203], v[96:99]
	v_mfma_f32_16x16x32_bf16 v[64:67], v[166:169], v[200:203], v[64:67]
	s_setprio 0
	s_barrier
	s_add_u32 s0, s0, 0x100080
	s_addc_u32 s1, s1, 0
	s_add_i32 s2, s18, s69
	s_mov_b32 m0, s2
	s_nop 0
	global_load_lds_dwordx4 v140, s[0:1]
	s_add_i32 m0, s2, 0x2000
	s_nop 0
	global_load_lds_dwordx4 v132, s[0:1]
	s_waitcnt vmcnt(6)
	s_barrier
	s_setprio 1
	v_mfma_f32_16x16x32_bf16 v[44:47], v[204:207], v[170:173], v[44:47]
	v_mfma_f32_16x16x32_bf16 v[12:15], v[228:231], v[170:173], v[12:15]
	v_mfma_f32_16x16x32_bf16 v[40:43], v[204:207], v[178:181], v[40:43]
	v_mfma_f32_16x16x32_bf16 v[8:11], v[228:231], v[178:181], v[8:11]
	v_mfma_f32_16x16x32_bf16 v[36:39], v[204:207], v[188:191], v[36:39]
	v_mfma_f32_16x16x32_bf16 v[4:7], v[228:231], v[188:191], v[4:7]
	v_mfma_f32_16x16x32_bf16 v[32:35], v[204:207], v[196:199], v[32:35]
	v_mfma_f32_16x16x32_bf16 v[0:3], v[228:231], v[196:199], v[0:3]
	v_mfma_f32_16x16x32_bf16 v[44:47], v[208:211], v[174:177], v[44:47]
	v_mfma_f32_16x16x32_bf16 v[12:15], v[232:235], v[174:177], v[12:15]
	v_mfma_f32_16x16x32_bf16 v[40:43], v[208:211], v[184:187], v[40:43]
	v_mfma_f32_16x16x32_bf16 v[8:11], v[232:235], v[184:187], v[8:11]
	v_mfma_f32_16x16x32_bf16 v[36:39], v[208:211], v[192:195], v[36:39]
	v_mfma_f32_16x16x32_bf16 v[4:7], v[232:235], v[192:195], v[4:7]
	v_mfma_f32_16x16x32_bf16 v[32:35], v[208:211], v[200:203], v[32:35]
	v_mfma_f32_16x16x32_bf16 v[0:3], v[232:235], v[200:203], v[0:3]
	s_setprio 0
	s_add_i32 s15, s15, 2
	s_add_u32 s11, s11, 0x100
	s_addc_u32 s13, s13, 0
	s_add_u32 s8, s8, 0x100
	s_addc_u32 s9, s9, 0
	s_cmp_gt_u32 s15, 29
	s_barrier
	s_cbranch_scc0 .LBB0_35
	v_mbcnt_lo_u32_b32 v170, -1, 0
	v_mbcnt_hi_u32_b32 v170, -1, v170
	s_lshl_b32 s0, s16, 8
	v_ashrrev_i32_e32 v138, 2, v170
	v_and_b32_e32 v138, -4, v138
	s_or_b32 s0, s0, s75
	v_add_u32_e32 v138, s0, v138
	s_lshl_b32 s0, s88, 10
	s_ashr_i32 s1, s0, 31
	s_lshl_b32 s13, s88, 12
	s_lshl_b32 s15, s88, 11
	s_addk_i32 s13, 0x1000
	s_lshl_b64 s[0:1], s[0:1], 2
	v_and_or_b32 v154, v170, 15, s74
	s_add_u32 s0, s49, s0
	v_ashrrev_i32_e32 v139, 31, v138
	v_lshl_add_u32 v184, s10, 8, v154
	s_addc_u32 s1, s76, s1
	v_lshlrev_b64 v[172:173], 2, v[138:139]
	v_add_u32_e32 v156, s15, v184
	v_lshl_add_u64 v[160:161], s[0:1], 0, v[172:173]
	v_ashrrev_i32_e32 v157, 31, v156
	flat_load_dwordx4 v[162:165], v[160:161]
	v_lshlrev_b64 v[154:155], 12, v[156:157]
	v_lshl_add_u64 v[154:155], s[26:27], 0, v[154:155]
	v_lshl_add_u64 v[158:159], v[154:155], 0, v[172:173]
	flat_load_dwordx4 v[166:169], v[158:159] nt
	s_mov_b32 s0, 0x3c800000
	v_and_b32_e32 v155, 1, v170
	v_add_u32_e32 v156, s15, v156
	v_cmp_eq_u32_e64 s[8:9], 0, v155
	v_ashrrev_i32_e32 v157, 31, v156
	v_lshlrev_b64 v[156:157], 11, v[156:157]
	v_sub_u32_e32 v154, s13, v184
	v_lshl_add_u64 v[156:157], s[24:25], 0, v[156:157]
	v_cmp_ne_u32_e32 vcc, 0, v184
	v_lshl_add_u64 v[156:157], v[138:139], 1, v[156:157]
	s_waitcnt vmcnt(0) lgkmcnt(0)
	v_pk_mul_f32 v[164:165], v[164:165], s[0:1] op_sel_hi:[1,0]
	v_pk_mul_f32 v[162:163], v[162:163], s[0:1] op_sel_hi:[1,0]
	v_xor_b32_e32 v170, 0x80000000, v164
	v_xor_b32_e32 v171, 0x80000000, v165
	v_xor_b32_e32 v174, 0x80000000, v162
	v_xor_b32_e32 v175, 0x80000000, v163
	v_cndmask_b32_e64 v177, v171, v165, s[8:9]
	v_cndmask_b32_e64 v176, v170, v164, s[8:9]
	v_cndmask_b32_e64 v179, v175, v163, s[8:9]
	v_cndmask_b32_e64 v178, v174, v162, s[8:9]
	v_pk_add_f32 v[162:163], v[168:169], v[176:177]
	v_pk_add_f32 v[164:165], v[166:167], v[178:179]
	v_sub_f32_e32 v155, v162, v126
	v_sub_f32_e32 v167, v163, v127
	v_sub_f32_e32 v166, v164, v124
	v_cvt_pk_bf16_f32 v167, v155, v167
	v_ashrrev_i32_e32 v155, 31, v154
	v_sub_f32_e32 v168, v165, v125
	v_cvt_pk_bf16_f32 v166, v166, v168
	flat_store_dwordx2 v[156:157], v[166:167]
	s_and_saveexec_b64 s[0:1], vcc
	s_cbranch_execz .LBB0_38
	v_pk_add_f32 v[126:127], v[126:127], v[162:163]
	v_pk_add_f32 v[124:125], v[124:125], v[164:165]
	s_nop 0
	v_cvt_pk_bf16_f32 v124, v124, v125
	v_cvt_pk_bf16_f32 v125, v126, v127
	v_lshlrev_b64 v[126:127], 11, v[154:155]
	v_lshl_add_u64 v[126:127], s[24:25], 0, v[126:127]
	v_lshl_add_u64 v[126:127], v[138:139], 1, v[126:127]
	flat_store_dwordx2 v[126:127], v[124:125]

.LBB0_96:
	s_add_u32 s0, s40, 0xfffc0080
	s_addc_u32 s1, s41, -1
	s_add_i32 s2, 0, 0x10000
	v_add_u32_e32 v138, s2, v154
	ds_read_b128 v[156:159], v138
	ds_read_b128 v[160:163], v138 offset:1024
	ds_read_b128 v[164:167], v138 offset:2048
	ds_read_b128 v[168:171], v138 offset:3072
	s_cmp_eq_u32 s72, 12
	s_cselect_b32 s45, s13, s1
	s_cselect_b32 s44, s12, s0
	s_cselect_b32 s1, s15, s11
	s_cselect_b32 s0, s14, s9
	s_add_i32 m0, s17, 0xc000
	ds_read_b128 v[172:175], v155
	ds_read_b128 v[176:179], v155 offset:1024
	ds_read_b128 v[180:183], v155 offset:2048
	ds_read_b128 v[184:187], v155 offset:3072
	ds_read_b128 v[188:191], v155 offset:4096
	ds_read_b128 v[192:195], v155 offset:5120
	ds_read_b128 v[196:199], v155 offset:6144
	ds_read_b128 v[200:203], v155 offset:7168
	global_load_lds_dwordx4 v136, s[40:41]
	s_add_i32 m0, s17, 0xe000
	s_nop 0
	global_load_lds_dwordx4 v134, s[40:41]
	s_waitcnt lgkmcnt(8)
	s_barrier
	s_waitcnt lgkmcnt(0)
	s_setprio 1
	s_waitcnt lgkmcnt(0)
	v_mfma_f32_16x16x32_bf16 v[124:127], v[156:159], v[172:175], v[124:127]
	v_mfma_f32_16x16x32_bf16 v[120:123], v[164:167], v[172:175], v[120:123]
	v_mfma_f32_16x16x32_bf16 v[116:119], v[156:159], v[180:183], v[116:119]
	v_mfma_f32_16x16x32_bf16 v[108:111], v[164:167], v[180:183], v[108:111]
	v_mfma_f32_16x16x32_bf16 v[100:103], v[156:159], v[188:191], v[100:103]
	v_mfma_f32_16x16x32_bf16 v[92:95], v[164:167], v[188:191], v[92:95]
	v_mfma_f32_16x16x32_bf16 v[84:87], v[156:159], v[196:199], v[84:87]
	v_mfma_f32_16x16x32_bf16 v[76:79], v[164:167], v[196:199], v[76:79]
	v_mfma_f32_16x16x32_bf16 v[124:127], v[160:163], v[176:179], v[124:127]
	v_mfma_f32_16x16x32_bf16 v[120:123], v[168:171], v[176:179], v[120:123]
	v_mfma_f32_16x16x32_bf16 v[116:119], v[160:163], v[184:187], v[116:119]
	v_mfma_f32_16x16x32_bf16 v[108:111], v[168:171], v[184:187], v[108:111]
	v_mfma_f32_16x16x32_bf16 v[100:103], v[160:163], v[192:195], v[100:103]
	v_mfma_f32_16x16x32_bf16 v[92:95], v[168:171], v[192:195], v[92:95]
	v_mfma_f32_16x16x32_bf16 v[84:87], v[160:163], v[200:203], v[84:87]
	v_mfma_f32_16x16x32_bf16 v[76:79], v[168:171], v[200:203], v[76:79]
	s_setprio 0
	s_barrier
	s_add_i32 s30, 0, 0x14000
	v_add_u32_e32 v138, s30, v154
	s_add_i32 s2, s2, s59
	ds_read_b128 v[204:207], v138
	ds_read_b128 v[208:211], v138 offset:1024
	ds_read_b128 v[228:231], v138 offset:2048
	ds_read_b128 v[232:235], v138 offset:3072
	s_mov_b32 m0, s2
	s_nop 0
	global_load_lds_dwordx4 v140, s[0:1]
	s_add_i32 m0, s2, 0x2000
	s_nop 0
	global_load_lds_dwordx4 v132, s[0:1]
	s_barrier
	s_waitcnt lgkmcnt(0)
	s_setprio 1
	s_waitcnt lgkmcnt(0)
	v_mfma_f32_16x16x32_bf16 v[112:115], v[204:207], v[172:175], v[112:115]
	v_mfma_f32_16x16x32_bf16 v[104:107], v[228:231], v[172:175], v[104:107]
	v_mfma_f32_16x16x32_bf16 v[96:99], v[204:207], v[180:183], v[96:99]
	v_mfma_f32_16x16x32_bf16 v[88:91], v[228:231], v[180:183], v[88:91]
	v_mfma_f32_16x16x32_bf16 v[80:83], v[204:207], v[188:191], v[80:83]
	v_mfma_f32_16x16x32_bf16 v[72:75], v[228:231], v[188:191], v[72:75]
	v_mfma_f32_16x16x32_bf16 v[68:71], v[204:207], v[196:199], v[68:71]
	v_mfma_f32_16x16x32_bf16 v[64:67], v[228:231], v[196:199], v[64:67]
	v_mfma_f32_16x16x32_bf16 v[112:115], v[208:211], v[176:179], v[112:115]
	v_mfma_f32_16x16x32_bf16 v[104:107], v[232:235], v[176:179], v[104:107]
	v_mfma_f32_16x16x32_bf16 v[96:99], v[208:211], v[184:187], v[96:99]
	v_mfma_f32_16x16x32_bf16 v[88:91], v[232:235], v[184:187], v[88:91]
	v_mfma_f32_16x16x32_bf16 v[80:83], v[208:211], v[192:195], v[80:83]
	v_mfma_f32_16x16x32_bf16 v[72:75], v[232:235], v[192:195], v[72:75]
	v_mfma_f32_16x16x32_bf16 v[68:71], v[208:211], v[200:203], v[68:71]
	v_mfma_f32_16x16x32_bf16 v[64:67], v[232:235], v[200:203], v[64:67]
	s_setprio 0
	s_mov_b32 m0, s17
	s_barrier
	ds_read_b128 v[172:175], v155 offset:16384
	ds_read_b128 v[176:179], v155 offset:17408
	ds_read_b128 v[180:183], v155 offset:18432
	ds_read_b128 v[184:187], v155 offset:19456
	ds_read_b128 v[188:191], v155 offset:20480
	ds_read_b128 v[192:195], v155 offset:21504
	ds_read_b128 v[196:199], v155 offset:22528
	ds_read_b128 v[200:203], v155 offset:23552
	global_load_lds_dwordx4 v128, s[44:45]
	s_mov_b32 m0, s64
	s_nop 0
	global_load_lds_dwordx4 v130, s[44:45]
	s_barrier
	s_waitcnt lgkmcnt(0)
	s_setprio 1
	s_waitcnt lgkmcnt(0)
	v_mfma_f32_16x16x32_bf16 v[60:63], v[156:159], v[172:175], v[60:63]
	v_mfma_f32_16x16x32_bf16 v[56:59], v[164:167], v[172:175], v[56:59]
	v_mfma_f32_16x16x32_bf16 v[52:55], v[156:159], v[180:183], v[52:55]
	v_mfma_f32_16x16x32_bf16 v[44:47], v[164:167], v[180:183], v[44:47]
	v_mfma_f32_16x16x32_bf16 v[36:39], v[156:159], v[188:191], v[36:39]
	v_mfma_f32_16x16x32_bf16 v[28:31], v[164:167], v[188:191], v[28:31]
	v_mfma_f32_16x16x32_bf16 v[20:23], v[156:159], v[196:199], v[20:23]
	v_mfma_f32_16x16x32_bf16 v[12:15], v[164:167], v[196:199], v[12:15]
	v_mfma_f32_16x16x32_bf16 v[60:63], v[160:163], v[176:179], v[60:63]
	v_mfma_f32_16x16x32_bf16 v[56:59], v[168:171], v[176:179], v[56:59]
	v_mfma_f32_16x16x32_bf16 v[52:55], v[160:163], v[184:187], v[52:55]
	v_mfma_f32_16x16x32_bf16 v[44:47], v[168:171], v[184:187], v[44:47]
	v_mfma_f32_16x16x32_bf16 v[36:39], v[160:163], v[192:195], v[36:39]
	v_mfma_f32_16x16x32_bf16 v[28:31], v[168:171], v[192:195], v[28:31]
	v_mfma_f32_16x16x32_bf16 v[20:23], v[160:163], v[200:203], v[20:23]
	v_mfma_f32_16x16x32_bf16 v[12:15], v[168:171], v[200:203], v[12:15]
	s_setprio 0
	s_barrier
	s_add_u32 s18, s0, 0x40000
	s_addc_u32 s19, s1, 0
	s_add_i32 s2, s30, s59
	s_mov_b32 m0, s2
	s_nop 0
	global_load_lds_dwordx4 v140, s[18:19]
	s_add_i32 m0, s2, 0x2000
	s_nop 0
	global_load_lds_dwordx4 v132, s[18:19]
	s_waitcnt vmcnt(6)
	s_barrier
	s_setprio 1
	v_mfma_f32_16x16x32_bf16 v[48:51], v[204:207], v[172:175], v[48:51]
	v_mfma_f32_16x16x32_bf16 v[40:43], v[228:231], v[172:175], v[40:43]
	v_mfma_f32_16x16x32_bf16 v[32:35], v[204:207], v[180:183], v[32:35]
	v_mfma_f32_16x16x32_bf16 v[24:27], v[228:231], v[180:183], v[24:27]
	v_mfma_f32_16x16x32_bf16 v[16:19], v[204:207], v[188:191], v[16:19]
	v_mfma_f32_16x16x32_bf16 v[8:11], v[228:231], v[188:191], v[8:11]
	v_mfma_f32_16x16x32_bf16 v[4:7], v[204:207], v[196:199], v[4:7]
	v_mfma_f32_16x16x32_bf16 v[0:3], v[228:231], v[196:199], v[0:3]
	v_mfma_f32_16x16x32_bf16 v[48:51], v[208:211], v[176:179], v[48:51]
	v_mfma_f32_16x16x32_bf16 v[40:43], v[232:235], v[176:179], v[40:43]
	v_mfma_f32_16x16x32_bf16 v[32:35], v[208:211], v[184:187], v[32:35]
	v_mfma_f32_16x16x32_bf16 v[24:27], v[232:235], v[184:187], v[24:27]
	v_mfma_f32_16x16x32_bf16 v[16:19], v[208:211], v[192:195], v[16:19]
	v_mfma_f32_16x16x32_bf16 v[8:11], v[232:235], v[192:195], v[8:11]
	v_mfma_f32_16x16x32_bf16 v[4:7], v[208:211], v[200:203], v[4:7]
	v_mfma_f32_16x16x32_bf16 v[0:3], v[232:235], v[200:203], v[0:3]
	s_setprio 0
	s_add_i32 s2, 0, 0x18000
	v_add_u32_e32 v168, s2, v154
	s_barrier
	ds_read_b128 v[156:159], v168
	ds_read_b128 v[160:163], v168 offset:1024
	ds_read_b128 v[164:167], v168 offset:2048
	ds_read_b128 v[168:171], v168 offset:3072
	s_add_u32 s18, s44, 0x40000
	s_addc_u32 s19, s45, 0
	s_mov_b32 m0, s65
	ds_read_b128 v[172:175], v155 offset:32768
	ds_read_b128 v[176:179], v155 offset:33792
	ds_read_b128 v[180:183], v155 offset:34816
	ds_read_b128 v[184:187], v155 offset:35840
	ds_read_b128 v[188:191], v155 offset:36864
	ds_read_b128 v[192:195], v155 offset:37888
	ds_read_b128 v[196:199], v155 offset:38912
	ds_read_b128 v[200:203], v155 offset:39936
	global_load_lds_dwordx4 v128, s[18:19]
	s_mov_b32 m0, s66
	s_nop 0
	global_load_lds_dwordx4 v130, s[18:19]
	s_waitcnt lgkmcnt(8)
	s_barrier
	s_waitcnt lgkmcnt(0)
	s_setprio 1
	s_waitcnt lgkmcnt(0)
	v_mfma_f32_16x16x32_bf16 v[124:127], v[156:159], v[172:175], v[124:127]
	v_mfma_f32_16x16x32_bf16 v[120:123], v[164:167], v[172:175], v[120:123]
	v_mfma_f32_16x16x32_bf16 v[116:119], v[156:159], v[180:183], v[116:119]
	v_mfma_f32_16x16x32_bf16 v[108:111], v[164:167], v[180:183], v[108:111]
	v_mfma_f32_16x16x32_bf16 v[100:103], v[156:159], v[188:191], v[100:103]
	v_mfma_f32_16x16x32_bf16 v[92:95], v[164:167], v[188:191], v[92:95]
	v_mfma_f32_16x16x32_bf16 v[84:87], v[156:159], v[196:199], v[84:87]
	v_mfma_f32_16x16x32_bf16 v[76:79], v[164:167], v[196:199], v[76:79]
	v_mfma_f32_16x16x32_bf16 v[124:127], v[160:163], v[176:179], v[124:127]
	v_mfma_f32_16x16x32_bf16 v[120:123], v[168:171], v[176:179], v[120:123]
	v_mfma_f32_16x16x32_bf16 v[116:119], v[160:163], v[184:187], v[116:119]
	v_mfma_f32_16x16x32_bf16 v[108:111], v[168:171], v[184:187], v[108:111]
	v_mfma_f32_16x16x32_bf16 v[100:103], v[160:163], v[192:195], v[100:103]
	v_mfma_f32_16x16x32_bf16 v[92:95], v[168:171], v[192:195], v[92:95]
	v_mfma_f32_16x16x32_bf16 v[84:87], v[160:163], v[200:203], v[84:87]
	v_mfma_f32_16x16x32_bf16 v[76:79], v[168:171], v[200:203], v[76:79]
	s_setprio 0
	s_barrier
	s_add_i32 s18, 0, 0x1c000
	s_add_i32 s2, s2, s59
	v_add_u32_e32 v232, s18, v154
	s_mov_b32 m0, s2
	ds_read_b128 v[204:207], v232
	ds_read_b128 v[208:211], v232 offset:1024
	ds_read_b128 v[228:231], v232 offset:2048
	ds_read_b128 v[232:235], v232 offset:3072
	s_add_u32 s100, s0, 0x80
	s_addc_u32 s101, s1, 0
	global_load_lds_dwordx4 v140, s[100:101]
	s_add_i32 m0, s2, 0x2000
	s_nop 0
	global_load_lds_dwordx4 v132, s[100:101]
	s_barrier
	s_waitcnt lgkmcnt(0)
	s_setprio 1
	s_waitcnt lgkmcnt(0)
	v_mfma_f32_16x16x32_bf16 v[112:115], v[204:207], v[172:175], v[112:115]
	v_mfma_f32_16x16x32_bf16 v[104:107], v[228:231], v[172:175], v[104:107]
	v_mfma_f32_16x16x32_bf16 v[96:99], v[204:207], v[180:183], v[96:99]
	v_mfma_f32_16x16x32_bf16 v[88:91], v[228:231], v[180:183], v[88:91]
	v_mfma_f32_16x16x32_bf16 v[80:83], v[204:207], v[188:191], v[80:83]
	v_mfma_f32_16x16x32_bf16 v[72:75], v[228:231], v[188:191], v[72:75]
	v_mfma_f32_16x16x32_bf16 v[68:71], v[204:207], v[196:199], v[68:71]
	v_mfma_f32_16x16x32_bf16 v[64:67], v[228:231], v[196:199], v[64:67]
	v_mfma_f32_16x16x32_bf16 v[112:115], v[208:211], v[176:179], v[112:115]
	v_mfma_f32_16x16x32_bf16 v[104:107], v[232:235], v[176:179], v[104:107]
	v_mfma_f32_16x16x32_bf16 v[96:99], v[208:211], v[184:187], v[96:99]
	v_mfma_f32_16x16x32_bf16 v[88:91], v[232:235], v[184:187], v[88:91]
	v_mfma_f32_16x16x32_bf16 v[80:83], v[208:211], v[192:195], v[80:83]
	v_mfma_f32_16x16x32_bf16 v[72:75], v[232:235], v[192:195], v[72:75]
	v_mfma_f32_16x16x32_bf16 v[68:71], v[208:211], v[200:203], v[68:71]
	v_mfma_f32_16x16x32_bf16 v[64:67], v[232:235], v[200:203], v[64:67]
	s_setprio 0
	s_mov_b32 m0, s69
	s_barrier
	ds_read_b128 v[172:175], v155 offset:49152
	ds_read_b128 v[176:179], v155 offset:50176
	ds_read_b128 v[180:183], v155 offset:51200
	ds_read_b128 v[184:187], v155 offset:52224
	ds_read_b128 v[188:191], v155 offset:53248
	ds_read_b128 v[192:195], v155 offset:54272
	ds_read_b128 v[196:199], v155 offset:55296
	ds_read_b128 v[200:203], v155 offset:56320
	s_add_u32 s100, s44, 0x80
	s_addc_u32 s101, s45, 0
	global_load_lds_dwordx4 v128, s[100:101]
	s_mov_b32 m0, s71
	s_nop 0
	global_load_lds_dwordx4 v130, s[100:101]
	s_barrier
	s_waitcnt lgkmcnt(0)
	s_setprio 1
	s_waitcnt lgkmcnt(0)
	v_mfma_f32_16x16x32_bf16 v[60:63], v[156:159], v[172:175], v[60:63]
	v_mfma_f32_16x16x32_bf16 v[56:59], v[164:167], v[172:175], v[56:59]
	v_mfma_f32_16x16x32_bf16 v[52:55], v[156:159], v[180:183], v[52:55]
	v_mfma_f32_16x16x32_bf16 v[44:47], v[164:167], v[180:183], v[44:47]
	v_mfma_f32_16x16x32_bf16 v[36:39], v[156:159], v[188:191], v[36:39]
	v_mfma_f32_16x16x32_bf16 v[28:31], v[164:167], v[188:191], v[28:31]
	v_mfma_f32_16x16x32_bf16 v[20:23], v[156:159], v[196:199], v[20:23]
	v_mfma_f32_16x16x32_bf16 v[12:15], v[164:167], v[196:199], v[12:15]
	v_mfma_f32_16x16x32_bf16 v[60:63], v[160:163], v[176:179], v[60:63]
	v_mfma_f32_16x16x32_bf16 v[56:59], v[168:171], v[176:179], v[56:59]
	v_mfma_f32_16x16x32_bf16 v[52:55], v[160:163], v[184:187], v[52:55]
	v_mfma_f32_16x16x32_bf16 v[44:47], v[168:171], v[184:187], v[44:47]
	v_mfma_f32_16x16x32_bf16 v[36:39], v[160:163], v[192:195], v[36:39]
	v_mfma_f32_16x16x32_bf16 v[28:31], v[168:171], v[192:195], v[28:31]
	v_mfma_f32_16x16x32_bf16 v[20:23], v[160:163], v[200:203], v[20:23]
	v_mfma_f32_16x16x32_bf16 v[12:15], v[168:171], v[200:203], v[12:15]
	s_setprio 0
	s_barrier
	s_add_u32 s0, s0, 0x40080
	s_addc_u32 s1, s1, 0
	s_add_i32 s2, s18, s59
	s_mov_b32 m0, s2
	s_nop 0
	global_load_lds_dwordx4 v140, s[0:1]
	s_add_i32 m0, s2, 0x2000
	s_nop 0
	global_load_lds_dwordx4 v132, s[0:1]
	s_waitcnt vmcnt(6)
	s_barrier
	s_setprio 1
	v_mfma_f32_16x16x32_bf16 v[48:51], v[204:207], v[172:175], v[48:51]
	v_mfma_f32_16x16x32_bf16 v[40:43], v[228:231], v[172:175], v[40:43]
	v_mfma_f32_16x16x32_bf16 v[32:35], v[204:207], v[180:183], v[32:35]
	v_mfma_f32_16x16x32_bf16 v[24:27], v[228:231], v[180:183], v[24:27]
	v_mfma_f32_16x16x32_bf16 v[16:19], v[204:207], v[188:191], v[16:19]
	v_mfma_f32_16x16x32_bf16 v[8:11], v[228:231], v[188:191], v[8:11]
	v_mfma_f32_16x16x32_bf16 v[4:7], v[204:207], v[196:199], v[4:7]
	v_mfma_f32_16x16x32_bf16 v[0:3], v[228:231], v[196:199], v[0:3]
	v_mfma_f32_16x16x32_bf16 v[48:51], v[208:211], v[176:179], v[48:51]
	v_mfma_f32_16x16x32_bf16 v[40:43], v[232:235], v[176:179], v[40:43]
	v_mfma_f32_16x16x32_bf16 v[32:35], v[208:211], v[184:187], v[32:35]
	v_mfma_f32_16x16x32_bf16 v[24:27], v[232:235], v[184:187], v[24:27]
	v_mfma_f32_16x16x32_bf16 v[16:19], v[208:211], v[192:195], v[16:19]
	v_mfma_f32_16x16x32_bf16 v[8:11], v[232:235], v[192:195], v[8:11]
	v_mfma_f32_16x16x32_bf16 v[4:7], v[208:211], v[200:203], v[4:7]
	v_mfma_f32_16x16x32_bf16 v[0:3], v[232:235], v[200:203], v[0:3]
	s_setprio 0
	s_add_i32 s72, s72, 2
	s_add_u32 s9, s9, 0x100
	s_addc_u32 s11, s11, 0
	s_add_u32 s40, s40, 0x100
	s_addc_u32 s41, s41, 0
	s_cmp_gt_u32 s72, 13
	s_barrier
	s_cbranch_scc0 .LBB0_96
	s_lshl_b32 s0, s16, 8
	v_mbcnt_lo_u32_b32 v139, -1, 0
	v_mbcnt_hi_u32_b32 v139, -1, v139
	s_lshl_b32 s1, s21, 8
	v_ashrrev_i32_e32 v138, 1, v139
	s_add_i32 s0, s0, s67
	v_and_b32_e32 v138, -8, v138
	s_or_b32 s1, s1, s68
	v_and_or_b32 v156, v139, 15, s0
	v_add_u32_e32 v138, s1, v138
	v_ashrrev_i32_e32 v157, 31, v156
	v_ashrrev_i32_e32 v139, 31, v138
	v_lshlrev_b64 v[158:159], 11, v[156:157]
	v_lshl_add_u64 v[158:159], s[26:27], 0, v[158:159]
	v_lshlrev_b64 v[160:161], 1, v[138:139]
	v_lshl_add_u64 v[138:139], v[158:159], 0, v[160:161]
	v_cvt_pk_bf16_f32 v60, v60, v61
	v_cvt_pk_bf16_f32 v61, v62, v63
	v_cvt_pk_bf16_f32 v62, v56, v57
	v_add_co_u32_e32 v56, vcc, s31, v138
	v_cvt_pk_bf16_f32 v112, v112, v113
	v_cvt_pk_bf16_f32 v113, v114, v115
	v_cvt_pk_bf16_f32 v114, v104, v105
	v_or_b32_e32 v104, 16, v156
	s_nop 0
	v_addc_co_u32_e32 v57, vcc, 0, v139, vcc
	v_cvt_pk_bf16_f32 v48, v48, v49
	v_cvt_pk_bf16_f32 v49, v50, v51
	v_cvt_pk_bf16_f32 v51, v42, v43
	v_cvt_pk_bf16_f32 v42, v44, v45
	v_add_co_u32_e32 v44, vcc, s42, v138
	v_ashrrev_i32_e32 v105, 31, v104
	v_cvt_pk_bf16_f32 v96, v96, v97
	v_cvt_pk_bf16_f32 v97, v98, v99
	v_cvt_pk_bf16_f32 v98, v88, v89
	v_or_b32_e32 v88, 32, v156
	v_addc_co_u32_e32 v45, vcc, 0, v139, vcc
	v_lshlrev_b64 v[104:105], 11, v[104:105]
	v_ashrrev_i32_e32 v89, 31, v88
	v_cvt_pk_bf16_f32 v80, v80, v81
	v_cvt_pk_bf16_f32 v81, v82, v83
	v_cvt_pk_bf16_f32 v82, v72, v73
	v_or_b32_e32 v72, 48, v156
	s_mov_b64 s[0:1], 0x40000
	v_cvt_pk_bf16_f32 v32, v32, v33
	v_cvt_pk_bf16_f32 v33, v34, v35
	v_cvt_pk_bf16_f32 v35, v26, v27
	v_cvt_pk_bf16_f32 v26, v28, v29
	v_add_co_u32_e32 v28, vcc, s43, v138
	v_lshl_add_u64 v[104:105], s[26:27], 0, v[104:105]
	v_lshlrev_b64 v[88:89], 11, v[88:89]
	v_ashrrev_i32_e32 v73, 31, v72
	v_cvt_pk_bf16_f32 v68, v68, v69
	v_cvt_pk_bf16_f32 v69, v70, v71
	v_cvt_pk_bf16_f32 v70, v64, v65
	v_lshl_add_u64 v[64:65], v[138:139], 0, s[0:1]
	s_mov_b64 s[0:1], 0x48000
	v_addc_co_u32_e32 v29, vcc, 0, v139, vcc
	v_cvt_pk_bf16_f32 v115, v106, v107
	flat_store_dwordx4 v[138:139], v[112:115] offset:256
	v_lshl_add_u64 v[88:89], s[26:27], 0, v[88:89]
	v_lshlrev_b64 v[72:73], 11, v[72:73]
	v_lshl_add_u64 v[112:113], v[104:105], 0, v[160:161]
	v_cvt_pk_bf16_f32 v50, v40, v41
	flat_store_dwordx4 v[64:65], v[48:51] offset:256
	v_cvt_pk_bf16_f32 v16, v16, v17
	v_cvt_pk_bf16_f32 v17, v18, v19
	v_cvt_pk_bf16_f32 v19, v10, v11
	v_cvt_pk_bf16_f32 v10, v12, v13
	v_add_co_u32_e32 v12, vcc, s47, v138
	s_nop 0
	v_lshl_add_u64 v[48:49], v[138:139], 0, s[0:1]
	s_mov_b64 s[0:1], 0x50000
	v_cvt_pk_bf16_f32 v99, v90, v91
	flat_store_dwordx4 v[112:113], v[96:99] offset:256
	v_lshl_add_u64 v[72:73], s[26:27], 0, v[72:73]
	v_cvt_pk_bf16_f32 v34, v24, v25
	flat_store_dwordx4 v[48:49], v[32:35] offset:256
	v_lshl_add_u64 v[96:97], v[88:89], 0, v[160:161]
	v_addc_co_u32_e32 v13, vcc, 0, v139, vcc
	v_lshl_add_u64 v[32:33], v[138:139], 0, s[0:1]
	s_mov_b64 s[0:1], 0x58000
	v_cvt_pk_bf16_f32 v83, v74, v75
	flat_store_dwordx4 v[96:97], v[80:83] offset:256
	v_cvt_pk_bf16_f32 v18, v8, v9
	flat_store_dwordx4 v[32:33], v[16:19] offset:256
	s_and_b64 vcc, exec, s[6:7]
	v_lshl_add_u64 v[80:81], v[72:73], 0, v[160:161]
	v_lshl_add_u64 v[16:17], v[138:139], 0, s[0:1]
	s_mov_b32 s21, s10
	s_mov_b32 s16, s8
	s_mov_b64 s[40:41], s[14:15]
	s_mov_b64 s[0:1], s[12:13]
	v_cvt_pk_bf16_f32 v124, v124, v125
	v_cvt_pk_bf16_f32 v125, v126, v127
	v_cvt_pk_bf16_f32 v126, v120, v121
	v_cvt_pk_bf16_f32 v127, v122, v123
	flat_store_dwordx4 v[138:139], v[124:127]
	v_cvt_pk_bf16_f32 v104, v116, v117
	v_cvt_pk_bf16_f32 v105, v118, v119
	v_cvt_pk_bf16_f32 v106, v108, v109
	v_cvt_pk_bf16_f32 v107, v110, v111
	flat_store_dwordx4 v[112:113], v[104:107]
	v_cvt_pk_bf16_f32 v88, v100, v101
	v_cvt_pk_bf16_f32 v89, v102, v103
	v_cvt_pk_bf16_f32 v90, v92, v93
	v_cvt_pk_bf16_f32 v91, v94, v95
	flat_store_dwordx4 v[96:97], v[88:91]
	v_cvt_pk_bf16_f32 v72, v84, v85
	v_cvt_pk_bf16_f32 v73, v86, v87
	v_cvt_pk_bf16_f32 v74, v76, v77
	v_cvt_pk_bf16_f32 v75, v78, v79
	flat_store_dwordx4 v[80:81], v[72:75]
	v_cvt_pk_bf16_f32 v71, v66, v67
	flat_store_dwordx4 v[80:81], v[68:71] offset:256
	v_cvt_pk_bf16_f32 v63, v58, v59
	flat_store_dwordx4 v[56:57], v[60:63]
	v_cvt_pk_bf16_f32 v40, v52, v53
	v_cvt_pk_bf16_f32 v41, v54, v55
	v_cvt_pk_bf16_f32 v43, v46, v47
	flat_store_dwordx4 v[44:45], v[40:43]
	v_cvt_pk_bf16_f32 v24, v36, v37
	v_cvt_pk_bf16_f32 v25, v38, v39
	v_cvt_pk_bf16_f32 v27, v30, v31
	flat_store_dwordx4 v[28:29], v[24:27]
	v_cvt_pk_bf16_f32 v8, v20, v21
	v_cvt_pk_bf16_f32 v9, v22, v23
	v_cvt_pk_bf16_f32 v11, v14, v15
	flat_store_dwordx4 v[12:13], v[8:11]
	v_cvt_pk_bf16_f32 v4, v4, v5
	v_cvt_pk_bf16_f32 v5, v6, v7
	v_cvt_pk_bf16_f32 v6, v0, v1
	v_cvt_pk_bf16_f32 v7, v2, v3
	flat_store_dwordx4 v[16:17], v[4:7] offset:256
	s_cbranch_vccz .LBB0_89
	s_waitcnt vmcnt(0)
	s_cmpk_gt_u32 s51, 0xff
	s_cbranch_scc1 .LBB0_100
	s_barrier

.LBB0_126:
	s_add_u32 s0, s8, 0xfff80080
	s_addc_u32 s1, s9, -1
	s_add_i32 s2, 0, 0x10000
	v_add_u32_e32 v138, s2, v238
	ds_read_b128 v[154:157], v138
	ds_read_b128 v[158:161], v138 offset:1024
	ds_read_b128 v[162:165], v138 offset:2048
	ds_read_b128 v[166:169], v138 offset:3072
	s_cmp_eq_u32 s20, 28
	s_cselect_b32 s11, s45, s1
	s_cselect_b32 s10, s44, s0
	s_cselect_b32 s1, s67, s15
	s_cselect_b32 s0, s66, s13
	s_add_i32 m0, s17, 0xc000
	ds_read_b128 v[170:173], v239
	ds_read_b128 v[174:177], v239 offset:1024
	ds_read_b128 v[178:181], v239 offset:2048
	ds_read_b128 v[182:185], v239 offset:3072
	ds_read_b128 v[186:189], v239 offset:4096
	ds_read_b128 v[190:193], v239 offset:5120
	ds_read_b128 v[194:197], v239 offset:6144
	ds_read_b128 v[198:201], v239 offset:7168
	global_load_lds_dwordx4 v136, s[8:9]
	s_add_i32 m0, s17, 0xe000
	s_nop 0
	global_load_lds_dwordx4 v134, s[8:9]
	s_waitcnt lgkmcnt(8)
	s_barrier
	s_waitcnt lgkmcnt(0)
	s_setprio 1
	s_waitcnt lgkmcnt(0)
	v_mfma_f32_16x16x32_bf16 v[124:127], v[154:157], v[170:173], v[124:127]
	v_mfma_f32_16x16x32_bf16 v[120:123], v[162:165], v[170:173], v[120:123]
	v_mfma_f32_16x16x32_bf16 v[116:119], v[154:157], v[178:181], v[116:119]
	v_mfma_f32_16x16x32_bf16 v[112:115], v[162:165], v[178:181], v[112:115]
	v_mfma_f32_16x16x32_bf16 v[104:107], v[154:157], v[186:189], v[104:107]
	v_mfma_f32_16x16x32_bf16 v[96:99], v[162:165], v[186:189], v[96:99]
	v_mfma_f32_16x16x32_bf16 v[88:91], v[154:157], v[194:197], v[88:91]
	v_mfma_f32_16x16x32_bf16 v[80:83], v[162:165], v[194:197], v[80:83]
	v_mfma_f32_16x16x32_bf16 v[124:127], v[158:161], v[174:177], v[124:127]
	v_mfma_f32_16x16x32_bf16 v[120:123], v[166:169], v[174:177], v[120:123]
	v_mfma_f32_16x16x32_bf16 v[116:119], v[158:161], v[182:185], v[116:119]
	v_mfma_f32_16x16x32_bf16 v[112:115], v[166:169], v[182:185], v[112:115]
	v_mfma_f32_16x16x32_bf16 v[104:107], v[158:161], v[190:193], v[104:107]
	v_mfma_f32_16x16x32_bf16 v[96:99], v[166:169], v[190:193], v[96:99]
	v_mfma_f32_16x16x32_bf16 v[88:91], v[158:161], v[198:201], v[88:91]
	v_mfma_f32_16x16x32_bf16 v[80:83], v[166:169], v[198:201], v[80:83]
	s_setprio 0
	s_barrier
	s_add_i32 s21, 0, 0x14000
	v_add_u32_e32 v138, s21, v238
	s_add_i32 s2, s2, s58
	ds_read_b128 v[202:205], v138
	ds_read_b128 v[206:209], v138 offset:1024
	ds_read_b128 v[240:243], v138 offset:2048
	ds_read_b128 v[244:247], v138 offset:3072
	s_mov_b32 m0, s2
	s_nop 0
	global_load_lds_dwordx4 v140, s[0:1]
	s_add_i32 m0, s2, 0x2000
	s_nop 0
	global_load_lds_dwordx4 v132, s[0:1]
	s_barrier
	s_waitcnt lgkmcnt(0)
	s_setprio 1
	s_waitcnt lgkmcnt(0)
	v_mfma_f32_16x16x32_bf16 v[108:111], v[202:205], v[170:173], v[108:111]
	v_mfma_f32_16x16x32_bf16 v[100:103], v[240:243], v[170:173], v[100:103]
	v_mfma_f32_16x16x32_bf16 v[92:95], v[202:205], v[178:181], v[92:95]
	v_mfma_f32_16x16x32_bf16 v[84:87], v[240:243], v[178:181], v[84:87]
	v_mfma_f32_16x16x32_bf16 v[76:79], v[202:205], v[186:189], v[76:79]
	v_mfma_f32_16x16x32_bf16 v[72:75], v[240:243], v[186:189], v[72:75]
	v_mfma_f32_16x16x32_bf16 v[68:71], v[202:205], v[194:197], v[68:71]
	v_mfma_f32_16x16x32_bf16 v[64:67], v[240:243], v[194:197], v[64:67]
	v_mfma_f32_16x16x32_bf16 v[108:111], v[206:209], v[174:177], v[108:111]
	v_mfma_f32_16x16x32_bf16 v[100:103], v[244:247], v[174:177], v[100:103]
	v_mfma_f32_16x16x32_bf16 v[92:95], v[206:209], v[182:185], v[92:95]
	v_mfma_f32_16x16x32_bf16 v[84:87], v[244:247], v[182:185], v[84:87]
	v_mfma_f32_16x16x32_bf16 v[76:79], v[206:209], v[190:193], v[76:79]
	v_mfma_f32_16x16x32_bf16 v[72:75], v[244:247], v[190:193], v[72:75]
	v_mfma_f32_16x16x32_bf16 v[68:71], v[206:209], v[198:201], v[68:71]
	v_mfma_f32_16x16x32_bf16 v[64:67], v[244:247], v[198:201], v[64:67]
	s_setprio 0
	s_mov_b32 m0, s17
	v_lshl_add_u64 v[248:249], s[10:11], 0, v[128:129]
	s_barrier
	ds_read_b128 v[170:173], v239 offset:16384
	ds_read_b128 v[174:177], v239 offset:17408
	ds_read_b128 v[178:181], v239 offset:18432
	ds_read_b128 v[182:185], v239 offset:19456
	ds_read_b128 v[186:189], v239 offset:20480
	ds_read_b128 v[190:193], v239 offset:21504
	ds_read_b128 v[194:197], v239 offset:22528
	ds_read_b128 v[198:201], v239 offset:23552
	global_load_lds_dwordx4 v128, s[10:11]
	v_lshl_add_u64 v[250:251], s[10:11], 0, v[130:131]
	s_mov_b32 m0, s59
	s_nop 0
	global_load_lds_dwordx4 v130, s[10:11]
	s_barrier
	s_waitcnt lgkmcnt(0)
	s_setprio 1
	s_waitcnt lgkmcnt(0)
	v_mfma_f32_16x16x32_bf16 v[60:63], v[154:157], v[170:173], v[60:63]
	v_mfma_f32_16x16x32_bf16 v[56:59], v[162:165], v[170:173], v[56:59]
	v_mfma_f32_16x16x32_bf16 v[52:55], v[154:157], v[178:181], v[52:55]
	v_mfma_f32_16x16x32_bf16 v[48:51], v[162:165], v[178:181], v[48:51]
	v_mfma_f32_16x16x32_bf16 v[36:39], v[154:157], v[186:189], v[36:39]
	v_mfma_f32_16x16x32_bf16 v[32:35], v[162:165], v[186:189], v[32:35]
	v_mfma_f32_16x16x32_bf16 v[20:23], v[154:157], v[194:197], v[20:23]
	v_mfma_f32_16x16x32_bf16 v[16:19], v[162:165], v[194:197], v[16:19]
	v_mfma_f32_16x16x32_bf16 v[60:63], v[158:161], v[174:177], v[60:63]
	v_mfma_f32_16x16x32_bf16 v[56:59], v[166:169], v[174:177], v[56:59]
	v_mfma_f32_16x16x32_bf16 v[52:55], v[158:161], v[182:185], v[52:55]
	v_mfma_f32_16x16x32_bf16 v[48:51], v[166:169], v[182:185], v[48:51]
	v_mfma_f32_16x16x32_bf16 v[36:39], v[158:161], v[190:193], v[36:39]
	v_mfma_f32_16x16x32_bf16 v[32:35], v[166:169], v[190:193], v[32:35]
	v_mfma_f32_16x16x32_bf16 v[20:23], v[158:161], v[198:201], v[20:23]
	v_mfma_f32_16x16x32_bf16 v[16:19], v[166:169], v[198:201], v[16:19]
	s_setprio 0
	s_barrier
	s_add_u32 s18, s0, 0x100000
	s_addc_u32 s19, s1, 0
	s_add_i32 s2, s21, s58
	s_mov_b32 m0, s2
	s_nop 0
	global_load_lds_dwordx4 v140, s[18:19]
	s_add_i32 m0, s2, 0x2000
	s_nop 0
	global_load_lds_dwordx4 v132, s[18:19]
	s_waitcnt vmcnt(6)
	s_barrier
	s_setprio 1
	v_mfma_f32_16x16x32_bf16 v[44:47], v[202:205], v[170:173], v[44:47]
	v_mfma_f32_16x16x32_bf16 v[40:43], v[240:243], v[170:173], v[40:43]
	v_mfma_f32_16x16x32_bf16 v[28:31], v[202:205], v[178:181], v[28:31]
	v_mfma_f32_16x16x32_bf16 v[24:27], v[240:243], v[178:181], v[24:27]
	v_mfma_f32_16x16x32_bf16 v[12:15], v[202:205], v[186:189], v[12:15]
	v_mfma_f32_16x16x32_bf16 v[8:11], v[240:243], v[186:189], v[8:11]
	v_mfma_f32_16x16x32_bf16 v[4:7], v[202:205], v[194:197], v[4:7]
	v_mfma_f32_16x16x32_bf16 v[0:3], v[240:243], v[194:197], v[0:3]
	v_mfma_f32_16x16x32_bf16 v[44:47], v[206:209], v[174:177], v[44:47]
	v_mfma_f32_16x16x32_bf16 v[40:43], v[244:247], v[174:177], v[40:43]
	v_mfma_f32_16x16x32_bf16 v[28:31], v[206:209], v[182:185], v[28:31]
	v_mfma_f32_16x16x32_bf16 v[24:27], v[244:247], v[182:185], v[24:27]
	v_mfma_f32_16x16x32_bf16 v[12:15], v[206:209], v[190:193], v[12:15]
	v_mfma_f32_16x16x32_bf16 v[8:11], v[244:247], v[190:193], v[8:11]
	v_mfma_f32_16x16x32_bf16 v[4:7], v[206:209], v[198:201], v[4:7]
	v_mfma_f32_16x16x32_bf16 v[0:3], v[244:247], v[198:201], v[0:3]
	s_setprio 0
	s_add_i32 s2, 0, 0x18000
	v_add_u32_e32 v166, s2, v238
	s_barrier
	ds_read_b128 v[154:157], v166
	ds_read_b128 v[158:161], v166 offset:1024
	ds_read_b128 v[162:165], v166 offset:2048
	ds_read_b128 v[166:169], v166 offset:3072
	s_add_u32 s10, s10, 0x80000
	s_addc_u32 s11, s11, 0
	s_mov_b32 m0, s65
	ds_read_b128 v[170:173], v239 offset:32768
	ds_read_b128 v[174:177], v239 offset:33792
	ds_read_b128 v[178:181], v239 offset:34816
	ds_read_b128 v[182:185], v239 offset:35840
	ds_read_b128 v[186:189], v239 offset:36864
	ds_read_b128 v[190:193], v239 offset:37888
	ds_read_b128 v[194:197], v239 offset:38912
	ds_read_b128 v[198:201], v239 offset:39936
	global_load_lds_dwordx4 v128, s[10:11]
	s_mov_b32 m0, s72
	s_nop 0
	global_load_lds_dwordx4 v130, s[10:11]
	s_waitcnt lgkmcnt(8)
	s_barrier
	s_waitcnt lgkmcnt(0)
	s_setprio 1
	s_waitcnt lgkmcnt(0)
	v_mfma_f32_16x16x32_bf16 v[124:127], v[154:157], v[170:173], v[124:127]
	v_mfma_f32_16x16x32_bf16 v[120:123], v[162:165], v[170:173], v[120:123]
	v_mfma_f32_16x16x32_bf16 v[116:119], v[154:157], v[178:181], v[116:119]
	v_mfma_f32_16x16x32_bf16 v[112:115], v[162:165], v[178:181], v[112:115]
	v_mfma_f32_16x16x32_bf16 v[104:107], v[154:157], v[186:189], v[104:107]
	v_mfma_f32_16x16x32_bf16 v[96:99], v[162:165], v[186:189], v[96:99]
	v_mfma_f32_16x16x32_bf16 v[88:91], v[154:157], v[194:197], v[88:91]
	v_mfma_f32_16x16x32_bf16 v[80:83], v[162:165], v[194:197], v[80:83]
	v_mfma_f32_16x16x32_bf16 v[124:127], v[158:161], v[174:177], v[124:127]
	v_mfma_f32_16x16x32_bf16 v[120:123], v[166:169], v[174:177], v[120:123]
	v_mfma_f32_16x16x32_bf16 v[116:119], v[158:161], v[182:185], v[116:119]
	v_mfma_f32_16x16x32_bf16 v[112:115], v[166:169], v[182:185], v[112:115]
	v_mfma_f32_16x16x32_bf16 v[104:107], v[158:161], v[190:193], v[104:107]
	v_mfma_f32_16x16x32_bf16 v[96:99], v[166:169], v[190:193], v[96:99]
	v_mfma_f32_16x16x32_bf16 v[88:91], v[158:161], v[198:201], v[88:91]
	v_mfma_f32_16x16x32_bf16 v[80:83], v[166:169], v[198:201], v[80:83]
	s_setprio 0
	s_barrier
	s_add_i32 s10, 0, 0x1c000
	s_add_i32 s2, s2, s58
	v_add_u32_e32 v244, s10, v238
	s_mov_b32 m0, s2
	ds_read_b128 v[202:205], v244
	ds_read_b128 v[206:209], v244 offset:1024
	ds_read_b128 v[240:243], v244 offset:2048
	ds_read_b128 v[244:247], v244 offset:3072
	s_add_u32 s100, s0, 0x80
	s_addc_u32 s101, s1, 0
	global_load_lds_dwordx4 v140, s[100:101]
	s_add_i32 m0, s2, 0x2000
	s_nop 0
	global_load_lds_dwordx4 v132, s[100:101]
	s_barrier
	s_waitcnt lgkmcnt(0)
	s_setprio 1
	s_waitcnt lgkmcnt(0)
	v_mfma_f32_16x16x32_bf16 v[108:111], v[202:205], v[170:173], v[108:111]
	v_mfma_f32_16x16x32_bf16 v[100:103], v[240:243], v[170:173], v[100:103]
	v_mfma_f32_16x16x32_bf16 v[92:95], v[202:205], v[178:181], v[92:95]
	v_mfma_f32_16x16x32_bf16 v[84:87], v[240:243], v[178:181], v[84:87]
	v_mfma_f32_16x16x32_bf16 v[76:79], v[202:205], v[186:189], v[76:79]
	v_mfma_f32_16x16x32_bf16 v[72:75], v[240:243], v[186:189], v[72:75]
	v_mfma_f32_16x16x32_bf16 v[68:71], v[202:205], v[194:197], v[68:71]
	v_mfma_f32_16x16x32_bf16 v[64:67], v[240:243], v[194:197], v[64:67]
	v_mfma_f32_16x16x32_bf16 v[108:111], v[206:209], v[174:177], v[108:111]
	v_mfma_f32_16x16x32_bf16 v[100:103], v[244:247], v[174:177], v[100:103]
	v_mfma_f32_16x16x32_bf16 v[92:95], v[206:209], v[182:185], v[92:95]
	v_mfma_f32_16x16x32_bf16 v[84:87], v[244:247], v[182:185], v[84:87]
	v_mfma_f32_16x16x32_bf16 v[76:79], v[206:209], v[190:193], v[76:79]
	v_mfma_f32_16x16x32_bf16 v[72:75], v[244:247], v[190:193], v[72:75]
	v_mfma_f32_16x16x32_bf16 v[68:71], v[206:209], v[198:201], v[68:71]
	v_mfma_f32_16x16x32_bf16 v[64:67], v[244:247], v[198:201], v[64:67]
	s_setprio 0
	s_mov_b32 m0, s75
	v_lshl_add_u64 v[138:139], v[248:249], 0, s[82:83]
	s_barrier
	ds_read_b128 v[170:173], v239 offset:49152
	ds_read_b128 v[174:177], v239 offset:50176
	ds_read_b128 v[178:181], v239 offset:51200
	ds_read_b128 v[182:185], v239 offset:52224
	ds_read_b128 v[186:189], v239 offset:53248
	ds_read_b128 v[190:193], v239 offset:54272
	ds_read_b128 v[194:197], v239 offset:55296
	ds_read_b128 v[198:201], v239 offset:56320
	global_load_lds_dwordx4 v[138:139], off
	v_lshl_add_u64 v[138:139], v[250:251], 0, s[82:83]
	s_mov_b32 m0, s77
	s_nop 0
	global_load_lds_dwordx4 v[138:139], off
	s_barrier
	s_waitcnt lgkmcnt(0)
	s_setprio 1
	s_waitcnt lgkmcnt(0)
	v_mfma_f32_16x16x32_bf16 v[60:63], v[154:157], v[170:173], v[60:63]
	v_mfma_f32_16x16x32_bf16 v[56:59], v[162:165], v[170:173], v[56:59]
	v_mfma_f32_16x16x32_bf16 v[52:55], v[154:157], v[178:181], v[52:55]
	v_mfma_f32_16x16x32_bf16 v[48:51], v[162:165], v[178:181], v[48:51]
	v_mfma_f32_16x16x32_bf16 v[36:39], v[154:157], v[186:189], v[36:39]
	v_mfma_f32_16x16x32_bf16 v[32:35], v[162:165], v[186:189], v[32:35]
	v_mfma_f32_16x16x32_bf16 v[20:23], v[154:157], v[194:197], v[20:23]
	v_mfma_f32_16x16x32_bf16 v[16:19], v[162:165], v[194:197], v[16:19]
	v_mfma_f32_16x16x32_bf16 v[60:63], v[158:161], v[174:177], v[60:63]
	v_mfma_f32_16x16x32_bf16 v[56:59], v[166:169], v[174:177], v[56:59]
	v_mfma_f32_16x16x32_bf16 v[52:55], v[158:161], v[182:185], v[52:55]
	v_mfma_f32_16x16x32_bf16 v[48:51], v[166:169], v[182:185], v[48:51]
	v_mfma_f32_16x16x32_bf16 v[36:39], v[158:161], v[190:193], v[36:39]
	v_mfma_f32_16x16x32_bf16 v[32:35], v[166:169], v[190:193], v[32:35]
	v_mfma_f32_16x16x32_bf16 v[20:23], v[158:161], v[198:201], v[20:23]
	v_mfma_f32_16x16x32_bf16 v[16:19], v[166:169], v[198:201], v[16:19]
	s_setprio 0
	s_barrier
	s_add_u32 s0, s0, 0x100080
	s_addc_u32 s1, s1, 0
	s_add_i32 s2, s10, s58
	s_mov_b32 m0, s2
	s_nop 0
	global_load_lds_dwordx4 v140, s[0:1]
	s_add_i32 m0, s2, 0x2000
	s_nop 0
	global_load_lds_dwordx4 v132, s[0:1]
	s_waitcnt vmcnt(6)
	s_barrier
	s_setprio 1
	v_mfma_f32_16x16x32_bf16 v[44:47], v[202:205], v[170:173], v[44:47]
	v_mfma_f32_16x16x32_bf16 v[40:43], v[240:243], v[170:173], v[40:43]
	v_mfma_f32_16x16x32_bf16 v[28:31], v[202:205], v[178:181], v[28:31]
	v_mfma_f32_16x16x32_bf16 v[24:27], v[240:243], v[178:181], v[24:27]
	v_mfma_f32_16x16x32_bf16 v[12:15], v[202:205], v[186:189], v[12:15]
	v_mfma_f32_16x16x32_bf16 v[8:11], v[240:243], v[186:189], v[8:11]
	v_mfma_f32_16x16x32_bf16 v[4:7], v[202:205], v[194:197], v[4:7]
	v_mfma_f32_16x16x32_bf16 v[0:3], v[240:243], v[194:197], v[0:3]
	v_mfma_f32_16x16x32_bf16 v[44:47], v[206:209], v[174:177], v[44:47]
	v_mfma_f32_16x16x32_bf16 v[40:43], v[244:247], v[174:177], v[40:43]
	v_mfma_f32_16x16x32_bf16 v[28:31], v[206:209], v[182:185], v[28:31]
	v_mfma_f32_16x16x32_bf16 v[24:27], v[244:247], v[182:185], v[24:27]
	v_mfma_f32_16x16x32_bf16 v[12:15], v[206:209], v[190:193], v[12:15]
	v_mfma_f32_16x16x32_bf16 v[8:11], v[244:247], v[190:193], v[8:11]
	v_mfma_f32_16x16x32_bf16 v[4:7], v[206:209], v[198:201], v[4:7]
	v_mfma_f32_16x16x32_bf16 v[0:3], v[244:247], v[198:201], v[0:3]
	s_setprio 0
	s_add_i32 s20, s20, 2
	s_add_u32 s13, s13, 0x100
	s_addc_u32 s15, s15, 0
	s_add_u32 s8, s8, 0x100
	s_addc_u32 s9, s9, 0
	s_cmp_gt_u32 s20, 29
	s_barrier
	s_cbranch_scc0 .LBB0_126
	v_mbcnt_lo_u32_b32 v154, -1, 0
	v_mbcnt_hi_u32_b32 v154, -1, v154
	s_lshl_b32 s0, s16, 8
	v_ashrrev_i32_e32 v138, 2, v154
	s_or_b32 s0, s0, s74
	v_and_b32_e32 v138, -4, v138
	s_lshl_b32 s13, s64, 8
	v_add_u32_e32 v138, s0, v138
	v_and_b32_e32 v240, 15, v154
	s_cmp_gt_i32 s71, 7
	s_mov_b64 s[0:1], -1
	v_ashrrev_i32_e32 v139, 31, v138
	s_cbranch_scc0 .LBB0_145
	s_add_i32 s0, s71, -8
	s_lshl_b32 s52, s0, 10
	s_lshl_b32 s15, s0, 12
	s_lshl_b32 s16, s0, 11
	s_addk_i32 s15, 0x1000
	s_lshl_b64 s[0:1], s[52:53], 2
	v_or_b32_e32 v155, s73, v240
	s_add_u32 s0, s49, s0
	v_add_u32_e32 v206, s13, v155
	s_addc_u32 s1, s76, s1
	v_lshlrev_b64 v[198:199], 2, v[138:139]
	v_add_u32_e32 v156, s16, v206
	v_lshl_add_u64 v[160:161], s[0:1], 0, v[198:199]
	v_ashrrev_i32_e32 v157, 31, v156
	flat_load_dwordx4 v[162:165], v[160:161]
	v_lshlrev_b64 v[158:159], 12, v[156:157]
	v_lshl_add_u64 v[158:159], s[26:27], 0, v[158:159]
	v_lshl_add_u64 v[158:159], v[158:159], 0, v[198:199]
	flat_load_dwordx4 v[166:169], v[158:159] nt
	s_mov_b32 s0, 0x3c800000
	v_and_b32_e32 v155, 1, v154
	v_add_u32_e32 v156, s16, v156
	v_cmp_eq_u32_e64 s[8:9], 0, v155
	v_ashrrev_i32_e32 v157, 31, v156
	v_lshlrev_b64 v[156:157], 11, v[156:157]
	v_sub_u32_e32 v154, s15, v206
	v_lshl_add_u64 v[156:157], s[24:25], 0, v[156:157]
	v_cmp_ne_u32_e32 vcc, 0, v206
	v_lshl_add_u64 v[156:157], v[138:139], 1, v[156:157]
	s_waitcnt vmcnt(0) lgkmcnt(0)
	v_or_b32_e32 v236, 16, v206
	v_add_u32_e32 v236, s16, v236
	v_ashrrev_i32_e32 v237, 31, v236
	v_lshlrev_b64 v[236:237], 12, v[236:237]
	v_lshl_add_u64 v[236:237], s[26:27], 0, v[236:237]
	v_lshl_add_u64 v[236:237], v[236:237], 0, v[198:199]
	global_load_dwordx4 v[232:235], v[236:237], off nt
	v_or_b32_e32 v236, 32, v206
	v_add_u32_e32 v236, s16, v236
	v_ashrrev_i32_e32 v237, 31, v236
	v_lshlrev_b64 v[236:237], 12, v[236:237]
	v_lshl_add_u64 v[236:237], s[26:27], 0, v[236:237]
	v_lshl_add_u64 v[236:237], v[236:237], 0, v[198:199]
	global_load_dwordx4 v[246:249], v[236:237], off nt
	v_pk_mul_f32 v[164:165], v[164:165], s[0:1] op_sel_hi:[1,0]
	v_pk_mul_f32 v[162:163], v[162:163], s[0:1] op_sel_hi:[1,0]
	v_xor_b32_e32 v170, 0x80000000, v164
	v_xor_b32_e32 v171, 0x80000000, v165
	v_xor_b32_e32 v172, 0x80000000, v162
	v_xor_b32_e32 v173, 0x80000000, v163
	v_cndmask_b32_e64 v201, v171, v165, s[8:9]
	v_cndmask_b32_e64 v200, v170, v164, s[8:9]
	v_cndmask_b32_e64 v205, v173, v163, s[8:9]
	v_cndmask_b32_e64 v204, v172, v162, s[8:9]
	v_pk_add_f32 v[162:163], v[168:169], v[200:201]
	v_pk_add_f32 v[164:165], v[166:167], v[204:205]
	v_sub_f32_e32 v155, v162, v126
	v_sub_f32_e32 v167, v163, v127
	v_sub_f32_e32 v166, v164, v124
	v_cvt_pk_bf16_f32 v167, v155, v167
	v_ashrrev_i32_e32 v155, 31, v154
	v_sub_f32_e32 v168, v165, v125
	v_cvt_pk_bf16_f32 v166, v166, v168
	global_store_dwordx2 v[156:157], v[166:167], off
	s_and_saveexec_b64 s[0:1], vcc
	s_cbranch_execz .LBB0_130
	v_pk_add_f32 v[162:163], v[126:127], v[162:163]
	v_pk_add_f32 v[164:165], v[124:125], v[164:165]
	s_nop 0
	v_cvt_pk_bf16_f32 v164, v164, v165
	v_cvt_pk_bf16_f32 v165, v162, v163
	v_lshlrev_b64 v[162:163], 11, v[154:155]
	v_lshl_add_u64 v[162:163], s[24:25], 0, v[162:163]
	v_lshl_add_u64 v[162:163], v[138:139], 1, v[162:163]
	global_store_dwordx2 v[162:163], v[164:165], off

.LBB0_169:
	s_add_u32 s0, s66, 0xfff80080
	s_addc_u32 s1, s67, -1
	s_add_i32 s2, 0, 0x10000
	v_add_u32_e32 v166, s2, v138
	ds_read_b128 v[154:157], v166
	ds_read_b128 v[158:161], v166 offset:1024
	ds_read_b128 v[162:165], v166 offset:2048
	ds_read_b128 v[166:169], v166 offset:3072
	s_cmp_eq_u32 s45, 28
	s_cselect_b32 s69, s9, s1
	s_cselect_b32 s68, s8, s0
	s_cselect_b32 s1, s65, s41
	s_cselect_b32 s0, s64, s17
	s_add_i32 m0, s11, 0xc000
	ds_read_b128 v[170:173], v139
	ds_read_b128 v[174:177], v139 offset:1024
	ds_read_b128 v[178:181], v139 offset:2048
	ds_read_b128 v[182:185], v139 offset:3072
	ds_read_b128 v[186:189], v139 offset:4096
	ds_read_b128 v[190:193], v139 offset:5120
	ds_read_b128 v[194:197], v139 offset:6144
	ds_read_b128 v[198:201], v139 offset:7168
	global_load_lds_dwordx4 v136, s[66:67]
	s_add_i32 m0, s11, 0xe000
	s_nop 0
	global_load_lds_dwordx4 v134, s[66:67]
	s_waitcnt lgkmcnt(8)
	s_barrier
	s_waitcnt lgkmcnt(0)
	s_setprio 1
	s_waitcnt lgkmcnt(0)
	v_mfma_f32_16x16x32_bf16 v[124:127], v[154:157], v[170:173], v[124:127]
	v_mfma_f32_16x16x32_bf16 v[120:123], v[162:165], v[170:173], v[120:123]
	v_mfma_f32_16x16x32_bf16 v[116:119], v[154:157], v[178:181], v[116:119]
	v_mfma_f32_16x16x32_bf16 v[112:115], v[162:165], v[178:181], v[112:115]
	v_mfma_f32_16x16x32_bf16 v[104:107], v[154:157], v[186:189], v[104:107]
	v_mfma_f32_16x16x32_bf16 v[96:99], v[162:165], v[186:189], v[96:99]
	v_mfma_f32_16x16x32_bf16 v[88:91], v[154:157], v[194:197], v[88:91]
	v_mfma_f32_16x16x32_bf16 v[80:83], v[162:165], v[194:197], v[80:83]
	v_mfma_f32_16x16x32_bf16 v[124:127], v[158:161], v[174:177], v[124:127]
	v_mfma_f32_16x16x32_bf16 v[120:123], v[166:169], v[174:177], v[120:123]
	v_mfma_f32_16x16x32_bf16 v[116:119], v[158:161], v[182:185], v[116:119]
	v_mfma_f32_16x16x32_bf16 v[112:115], v[166:169], v[182:185], v[112:115]
	v_mfma_f32_16x16x32_bf16 v[104:107], v[158:161], v[190:193], v[104:107]
	v_mfma_f32_16x16x32_bf16 v[96:99], v[166:169], v[190:193], v[96:99]
	v_mfma_f32_16x16x32_bf16 v[88:91], v[158:161], v[198:201], v[88:91]
	v_mfma_f32_16x16x32_bf16 v[80:83], v[166:169], v[198:201], v[80:83]
	s_setprio 0
	s_barrier
	s_add_i32 s30, 0, 0x14000
	v_add_u32_e32 v210, s30, v138
	s_add_i32 s2, s2, s20
	ds_read_b128 v[202:205], v210
	ds_read_b128 v[206:209], v210 offset:1024
	ds_read_b128 v[228:231], v210 offset:2048
	ds_read_b128 v[232:235], v210 offset:3072
	s_mov_b32 m0, s2
	s_nop 0
	global_load_lds_dwordx4 v140, s[0:1]
	s_add_i32 m0, s2, 0x2000
	s_nop 0
	global_load_lds_dwordx4 v132, s[0:1]
	s_barrier
	s_waitcnt lgkmcnt(0)
	s_setprio 1
	s_waitcnt lgkmcnt(0)
	v_mfma_f32_16x16x32_bf16 v[108:111], v[202:205], v[170:173], v[108:111]
	v_mfma_f32_16x16x32_bf16 v[100:103], v[228:231], v[170:173], v[100:103]
	v_mfma_f32_16x16x32_bf16 v[92:95], v[202:205], v[178:181], v[92:95]
	v_mfma_f32_16x16x32_bf16 v[84:87], v[228:231], v[178:181], v[84:87]
	v_mfma_f32_16x16x32_bf16 v[76:79], v[202:205], v[186:189], v[76:79]
	v_mfma_f32_16x16x32_bf16 v[72:75], v[228:231], v[186:189], v[72:75]
	v_mfma_f32_16x16x32_bf16 v[68:71], v[202:205], v[194:197], v[68:71]
	v_mfma_f32_16x16x32_bf16 v[64:67], v[228:231], v[194:197], v[64:67]
	v_mfma_f32_16x16x32_bf16 v[108:111], v[206:209], v[174:177], v[108:111]
	v_mfma_f32_16x16x32_bf16 v[100:103], v[232:235], v[174:177], v[100:103]
	v_mfma_f32_16x16x32_bf16 v[92:95], v[206:209], v[182:185], v[92:95]
	v_mfma_f32_16x16x32_bf16 v[84:87], v[232:235], v[182:185], v[84:87]
	v_mfma_f32_16x16x32_bf16 v[76:79], v[206:209], v[190:193], v[76:79]
	v_mfma_f32_16x16x32_bf16 v[72:75], v[232:235], v[190:193], v[72:75]
	v_mfma_f32_16x16x32_bf16 v[68:71], v[206:209], v[198:201], v[68:71]
	v_mfma_f32_16x16x32_bf16 v[64:67], v[232:235], v[198:201], v[64:67]
	s_setprio 0
	s_mov_b32 m0, s11
	s_barrier
	ds_read_b128 v[170:173], v139 offset:16384
	ds_read_b128 v[174:177], v139 offset:17408
	ds_read_b128 v[178:181], v139 offset:18432
	ds_read_b128 v[182:185], v139 offset:19456
	ds_read_b128 v[186:189], v139 offset:20480
	ds_read_b128 v[190:193], v139 offset:21504
	ds_read_b128 v[194:197], v139 offset:22528
	ds_read_b128 v[198:201], v139 offset:23552
	global_load_lds_dwordx4 v128, s[68:69]
	s_mov_b32 m0, s13
	s_nop 0
	global_load_lds_dwordx4 v130, s[68:69]
	s_barrier
	s_waitcnt lgkmcnt(0)
	s_setprio 1
	s_waitcnt lgkmcnt(0)
	v_mfma_f32_16x16x32_bf16 v[60:63], v[154:157], v[170:173], v[60:63]
	v_mfma_f32_16x16x32_bf16 v[56:59], v[162:165], v[170:173], v[56:59]
	v_mfma_f32_16x16x32_bf16 v[52:55], v[154:157], v[178:181], v[52:55]
	v_mfma_f32_16x16x32_bf16 v[48:51], v[162:165], v[178:181], v[48:51]
	v_mfma_f32_16x16x32_bf16 v[36:39], v[154:157], v[186:189], v[36:39]
	v_mfma_f32_16x16x32_bf16 v[32:35], v[162:165], v[186:189], v[32:35]
	v_mfma_f32_16x16x32_bf16 v[20:23], v[154:157], v[194:197], v[20:23]
	v_mfma_f32_16x16x32_bf16 v[16:19], v[162:165], v[194:197], v[16:19]
	v_mfma_f32_16x16x32_bf16 v[60:63], v[158:161], v[174:177], v[60:63]
	v_mfma_f32_16x16x32_bf16 v[56:59], v[166:169], v[174:177], v[56:59]
	v_mfma_f32_16x16x32_bf16 v[52:55], v[158:161], v[182:185], v[52:55]
	v_mfma_f32_16x16x32_bf16 v[48:51], v[166:169], v[182:185], v[48:51]
	v_mfma_f32_16x16x32_bf16 v[36:39], v[158:161], v[190:193], v[36:39]
	v_mfma_f32_16x16x32_bf16 v[32:35], v[166:169], v[190:193], v[32:35]
	v_mfma_f32_16x16x32_bf16 v[20:23], v[158:161], v[198:201], v[20:23]
	v_mfma_f32_16x16x32_bf16 v[16:19], v[166:169], v[198:201], v[16:19]
	s_setprio 0
	s_barrier
	s_add_u32 s18, s0, 0x100000
	s_addc_u32 s19, s1, 0
	s_add_i32 s2, s30, s20
	s_mov_b32 m0, s2
	s_nop 0
	global_load_lds_dwordx4 v140, s[18:19]
	s_add_i32 m0, s2, 0x2000
	s_nop 0
	global_load_lds_dwordx4 v132, s[18:19]
	s_waitcnt vmcnt(6)
	s_barrier
	s_setprio 1
	v_mfma_f32_16x16x32_bf16 v[44:47], v[202:205], v[170:173], v[44:47]
	v_mfma_f32_16x16x32_bf16 v[40:43], v[228:231], v[170:173], v[40:43]
	v_mfma_f32_16x16x32_bf16 v[28:31], v[202:205], v[178:181], v[28:31]
	v_mfma_f32_16x16x32_bf16 v[24:27], v[228:231], v[178:181], v[24:27]
	v_mfma_f32_16x16x32_bf16 v[12:15], v[202:205], v[186:189], v[12:15]
	v_mfma_f32_16x16x32_bf16 v[8:11], v[228:231], v[186:189], v[8:11]
	v_mfma_f32_16x16x32_bf16 v[4:7], v[202:205], v[194:197], v[4:7]
	v_mfma_f32_16x16x32_bf16 v[0:3], v[228:231], v[194:197], v[0:3]
	v_mfma_f32_16x16x32_bf16 v[44:47], v[206:209], v[174:177], v[44:47]
	v_mfma_f32_16x16x32_bf16 v[40:43], v[232:235], v[174:177], v[40:43]
	v_mfma_f32_16x16x32_bf16 v[28:31], v[206:209], v[182:185], v[28:31]
	v_mfma_f32_16x16x32_bf16 v[24:27], v[232:235], v[182:185], v[24:27]
	v_mfma_f32_16x16x32_bf16 v[12:15], v[206:209], v[190:193], v[12:15]
	v_mfma_f32_16x16x32_bf16 v[8:11], v[232:235], v[190:193], v[8:11]
	v_mfma_f32_16x16x32_bf16 v[4:7], v[206:209], v[198:201], v[4:7]
	v_mfma_f32_16x16x32_bf16 v[0:3], v[232:235], v[198:201], v[0:3]
	s_setprio 0
	s_add_i32 s2, 0, 0x18000
	v_add_u32_e32 v166, s2, v138
	s_barrier
	ds_read_b128 v[154:157], v166
	ds_read_b128 v[158:161], v166 offset:1024
	ds_read_b128 v[162:165], v166 offset:2048
	ds_read_b128 v[166:169], v166 offset:3072
	s_add_u32 s18, s68, 0x80000
	s_addc_u32 s19, s69, 0
	s_mov_b32 m0, s15
	ds_read_b128 v[170:173], v139 offset:32768
	ds_read_b128 v[174:177], v139 offset:33792
	ds_read_b128 v[178:181], v139 offset:34816
	ds_read_b128 v[182:185], v139 offset:35840
	ds_read_b128 v[186:189], v139 offset:36864
	ds_read_b128 v[190:193], v139 offset:37888
	ds_read_b128 v[194:197], v139 offset:38912
	ds_read_b128 v[198:201], v139 offset:39936
	global_load_lds_dwordx4 v128, s[18:19]
	s_mov_b32 m0, s21
	s_nop 0
	global_load_lds_dwordx4 v130, s[18:19]
	s_waitcnt lgkmcnt(8)
	s_barrier
	s_waitcnt lgkmcnt(0)
	s_setprio 1
	s_waitcnt lgkmcnt(0)
	v_mfma_f32_16x16x32_bf16 v[124:127], v[154:157], v[170:173], v[124:127]
	v_mfma_f32_16x16x32_bf16 v[120:123], v[162:165], v[170:173], v[120:123]
	v_mfma_f32_16x16x32_bf16 v[116:119], v[154:157], v[178:181], v[116:119]
	v_mfma_f32_16x16x32_bf16 v[112:115], v[162:165], v[178:181], v[112:115]
	v_mfma_f32_16x16x32_bf16 v[104:107], v[154:157], v[186:189], v[104:107]
	v_mfma_f32_16x16x32_bf16 v[96:99], v[162:165], v[186:189], v[96:99]
	v_mfma_f32_16x16x32_bf16 v[88:91], v[154:157], v[194:197], v[88:91]
	v_mfma_f32_16x16x32_bf16 v[80:83], v[162:165], v[194:197], v[80:83]
	v_mfma_f32_16x16x32_bf16 v[124:127], v[158:161], v[174:177], v[124:127]
	v_mfma_f32_16x16x32_bf16 v[120:123], v[166:169], v[174:177], v[120:123]
	v_mfma_f32_16x16x32_bf16 v[116:119], v[158:161], v[182:185], v[116:119]
	v_mfma_f32_16x16x32_bf16 v[112:115], v[166:169], v[182:185], v[112:115]
	v_mfma_f32_16x16x32_bf16 v[104:107], v[158:161], v[190:193], v[104:107]
	v_mfma_f32_16x16x32_bf16 v[96:99], v[166:169], v[190:193], v[96:99]
	v_mfma_f32_16x16x32_bf16 v[88:91], v[158:161], v[198:201], v[88:91]
	v_mfma_f32_16x16x32_bf16 v[80:83], v[166:169], v[198:201], v[80:83]
	s_setprio 0
	s_barrier
	s_add_i32 s18, 0, 0x1c000
	s_add_i32 s2, s2, s20
	v_add_u32_e32 v232, s18, v138
	s_mov_b32 m0, s2
	ds_read_b128 v[202:205], v232
	ds_read_b128 v[206:209], v232 offset:1024
	ds_read_b128 v[228:231], v232 offset:2048
	ds_read_b128 v[232:235], v232 offset:3072
	s_add_u32 s100, s0, 0x80
	s_addc_u32 s101, s1, 0
	global_load_lds_dwordx4 v140, s[100:101]
	s_add_i32 m0, s2, 0x2000
	s_nop 0
	global_load_lds_dwordx4 v132, s[100:101]
	s_barrier
	s_waitcnt lgkmcnt(0)
	s_setprio 1
	s_waitcnt lgkmcnt(0)
	v_mfma_f32_16x16x32_bf16 v[108:111], v[202:205], v[170:173], v[108:111]
	v_mfma_f32_16x16x32_bf16 v[100:103], v[228:231], v[170:173], v[100:103]
	v_mfma_f32_16x16x32_bf16 v[92:95], v[202:205], v[178:181], v[92:95]
	v_mfma_f32_16x16x32_bf16 v[84:87], v[228:231], v[178:181], v[84:87]
	v_mfma_f32_16x16x32_bf16 v[76:79], v[202:205], v[186:189], v[76:79]
	v_mfma_f32_16x16x32_bf16 v[72:75], v[228:231], v[186:189], v[72:75]
	v_mfma_f32_16x16x32_bf16 v[68:71], v[202:205], v[194:197], v[68:71]
	v_mfma_f32_16x16x32_bf16 v[64:67], v[228:231], v[194:197], v[64:67]
	v_mfma_f32_16x16x32_bf16 v[108:111], v[206:209], v[174:177], v[108:111]
	v_mfma_f32_16x16x32_bf16 v[100:103], v[232:235], v[174:177], v[100:103]
	v_mfma_f32_16x16x32_bf16 v[92:95], v[206:209], v[182:185], v[92:95]
	v_mfma_f32_16x16x32_bf16 v[84:87], v[232:235], v[182:185], v[84:87]
	v_mfma_f32_16x16x32_bf16 v[76:79], v[206:209], v[190:193], v[76:79]
	v_mfma_f32_16x16x32_bf16 v[72:75], v[232:235], v[190:193], v[72:75]
	v_mfma_f32_16x16x32_bf16 v[68:71], v[206:209], v[198:201], v[68:71]
	v_mfma_f32_16x16x32_bf16 v[64:67], v[232:235], v[198:201], v[64:67]
	s_setprio 0
	s_mov_b32 m0, s59
	s_barrier
	ds_read_b128 v[170:173], v139 offset:49152
	ds_read_b128 v[174:177], v139 offset:50176
	ds_read_b128 v[178:181], v139 offset:51200
	ds_read_b128 v[182:185], v139 offset:52224
	ds_read_b128 v[186:189], v139 offset:53248
	ds_read_b128 v[190:193], v139 offset:54272
	ds_read_b128 v[194:197], v139 offset:55296
	ds_read_b128 v[198:201], v139 offset:56320
	s_add_u32 s100, s68, 0x80
	s_addc_u32 s101, s69, 0
	global_load_lds_dwordx4 v128, s[100:101]
	s_mov_b32 m0, s71
	s_nop 0
	global_load_lds_dwordx4 v130, s[100:101]
	s_barrier
	s_waitcnt lgkmcnt(0)
	s_setprio 1
	s_waitcnt lgkmcnt(0)
	v_mfma_f32_16x16x32_bf16 v[60:63], v[154:157], v[170:173], v[60:63]
	v_mfma_f32_16x16x32_bf16 v[56:59], v[162:165], v[170:173], v[56:59]
	v_mfma_f32_16x16x32_bf16 v[52:55], v[154:157], v[178:181], v[52:55]
	v_mfma_f32_16x16x32_bf16 v[48:51], v[162:165], v[178:181], v[48:51]
	v_mfma_f32_16x16x32_bf16 v[36:39], v[154:157], v[186:189], v[36:39]
	v_mfma_f32_16x16x32_bf16 v[32:35], v[162:165], v[186:189], v[32:35]
	v_mfma_f32_16x16x32_bf16 v[20:23], v[154:157], v[194:197], v[20:23]
	v_mfma_f32_16x16x32_bf16 v[16:19], v[162:165], v[194:197], v[16:19]
	v_mfma_f32_16x16x32_bf16 v[60:63], v[158:161], v[174:177], v[60:63]
	v_mfma_f32_16x16x32_bf16 v[56:59], v[166:169], v[174:177], v[56:59]
	v_mfma_f32_16x16x32_bf16 v[52:55], v[158:161], v[182:185], v[52:55]
	v_mfma_f32_16x16x32_bf16 v[48:51], v[166:169], v[182:185], v[48:51]
	v_mfma_f32_16x16x32_bf16 v[36:39], v[158:161], v[190:193], v[36:39]
	v_mfma_f32_16x16x32_bf16 v[32:35], v[166:169], v[190:193], v[32:35]
	v_mfma_f32_16x16x32_bf16 v[20:23], v[158:161], v[198:201], v[20:23]
	v_mfma_f32_16x16x32_bf16 v[16:19], v[166:169], v[198:201], v[16:19]
	s_setprio 0
	s_barrier
	s_add_u32 s0, s0, 0x100080
	s_addc_u32 s1, s1, 0
	s_add_i32 s2, s18, s20
	s_mov_b32 m0, s2
	s_nop 0
	global_load_lds_dwordx4 v140, s[0:1]
	s_add_i32 m0, s2, 0x2000
	s_nop 0
	global_load_lds_dwordx4 v132, s[0:1]
	s_waitcnt vmcnt(6)
	s_barrier
	s_setprio 1
	v_mfma_f32_16x16x32_bf16 v[44:47], v[202:205], v[170:173], v[44:47]
	v_mfma_f32_16x16x32_bf16 v[40:43], v[228:231], v[170:173], v[40:43]
	v_mfma_f32_16x16x32_bf16 v[28:31], v[202:205], v[178:181], v[28:31]
	v_mfma_f32_16x16x32_bf16 v[24:27], v[228:231], v[178:181], v[24:27]
	v_mfma_f32_16x16x32_bf16 v[12:15], v[202:205], v[186:189], v[12:15]
	v_mfma_f32_16x16x32_bf16 v[8:11], v[228:231], v[186:189], v[8:11]
	v_mfma_f32_16x16x32_bf16 v[4:7], v[202:205], v[194:197], v[4:7]
	v_mfma_f32_16x16x32_bf16 v[0:3], v[228:231], v[194:197], v[0:3]
	v_mfma_f32_16x16x32_bf16 v[44:47], v[206:209], v[174:177], v[44:47]
	v_mfma_f32_16x16x32_bf16 v[40:43], v[232:235], v[174:177], v[40:43]
	v_mfma_f32_16x16x32_bf16 v[28:31], v[206:209], v[182:185], v[28:31]
	v_mfma_f32_16x16x32_bf16 v[24:27], v[232:235], v[182:185], v[24:27]
	v_mfma_f32_16x16x32_bf16 v[12:15], v[206:209], v[190:193], v[12:15]
	v_mfma_f32_16x16x32_bf16 v[8:11], v[232:235], v[190:193], v[8:11]
	v_mfma_f32_16x16x32_bf16 v[4:7], v[206:209], v[198:201], v[4:7]
	v_mfma_f32_16x16x32_bf16 v[0:3], v[232:235], v[198:201], v[0:3]
	s_setprio 0
	s_add_i32 s45, s45, 2
	s_add_u32 s17, s17, 0x100
	s_addc_u32 s41, s41, 0
	s_add_u32 s66, s66, 0x100
	s_addc_u32 s67, s67, 0
	s_cmp_gt_u32 s45, 29
	s_barrier
	s_cbranch_scc0 .LBB0_169
	s_lshl_b32 s0, s10, 11
	s_lshl_b32 s1, s14, 8
	s_add_i32 s0, s0, s57
	v_mbcnt_lo_u32_b32 v155, -1, 0
	v_mbcnt_hi_u32_b32 v155, -1, v155
	s_lshl_b32 s2, s12, 8
	v_ashrrev_i32_e32 v154, 2, v155
	s_add_i32 s0, s0, s1
	v_and_b32_e32 v154, -4, v154
	s_or_b32 s2, s2, s58
	v_and_or_b32 v156, v155, 15, s0
	v_add_u32_e32 v154, s2, v154
	v_ashrrev_i32_e32 v157, 31, v156
	v_ashrrev_i32_e32 v155, 31, v154
	v_lshlrev_b64 v[158:159], 12, v[156:157]
	v_lshl_add_u64 v[158:159], s[26:27], 0, v[158:159]
	v_lshlrev_b64 v[154:155], 2, v[154:155]
	v_lshl_add_u64 v[158:159], v[158:159], 0, v[154:155]
	flat_store_dwordx4 v[158:159], v[124:127]
	flat_store_dwordx4 v[158:159], v[120:123] offset:64
	flat_store_dwordx4 v[158:159], v[108:111] offset:512
	flat_store_dwordx4 v[158:159], v[100:103] offset:576
	s_mov_b64 s[0:1], 0x80000
	s_mov_b32 s10, s16
	v_or_b32_e32 v100, 16, v156
	v_ashrrev_i32_e32 v101, 31, v100
	v_lshlrev_b64 v[100:101], 12, v[100:101]
	v_lshl_add_u64 v[100:101], s[26:27], 0, v[100:101]
	v_lshl_add_u64 v[100:101], v[100:101], 0, v[154:155]
	flat_store_dwordx4 v[100:101], v[116:119]
	flat_store_dwordx4 v[100:101], v[112:115] offset:64
	flat_store_dwordx4 v[100:101], v[92:95] offset:512
	flat_store_dwordx4 v[100:101], v[84:87] offset:576
	s_mov_b32 s12, s40
	s_mov_b32 s14, s44
	v_or_b32_e32 v84, 32, v156
	v_ashrrev_i32_e32 v85, 31, v84
	v_lshlrev_b64 v[84:85], 12, v[84:85]
	v_lshl_add_u64 v[84:85], s[26:27], 0, v[84:85]
	v_lshl_add_u64 v[84:85], v[84:85], 0, v[154:155]
	flat_store_dwordx4 v[84:85], v[104:107]
	flat_store_dwordx4 v[84:85], v[96:99] offset:64
	flat_store_dwordx4 v[84:85], v[76:79] offset:512
	flat_store_dwordx4 v[84:85], v[72:75] offset:576
	s_mov_b64 s[66:67], s[64:65]
	s_nop 0
	v_or_b32_e32 v72, 48, v156
	v_ashrrev_i32_e32 v73, 31, v72
	v_lshlrev_b64 v[72:73], 12, v[72:73]
	v_lshl_add_u64 v[72:73], s[26:27], 0, v[72:73]
	v_lshl_add_u64 v[72:73], v[72:73], 0, v[154:155]
	flat_store_dwordx4 v[72:73], v[88:91]
	flat_store_dwordx4 v[72:73], v[80:83] offset:64
	flat_store_dwordx4 v[72:73], v[68:71] offset:512
	flat_store_dwordx4 v[72:73], v[64:67] offset:576
	s_nop 1
	v_lshl_add_u64 v[64:65], v[158:159], 0, s[0:1]
	s_mov_b32 s0, 0x80000
	v_add_co_u32_e32 v66, vcc, s0, v158
	s_mov_b64 s[0:1], 0x90000
	s_nop 0
	v_addc_co_u32_e32 v67, vcc, 0, v159, vcc
	flat_store_dwordx4 v[66:67], v[60:63]
	flat_store_dwordx4 v[64:65], v[56:59] offset:64
	flat_store_dwordx4 v[64:65], v[44:47] offset:512
	flat_store_dwordx4 v[64:65], v[40:43] offset:576
	s_nop 1
	v_lshl_add_u64 v[40:41], v[158:159], 0, s[0:1]
	s_mov_b32 s0, 0x90000
	v_add_co_u32_e32 v42, vcc, s0, v158
	s_mov_b64 s[0:1], 0xa0000
	s_nop 0
	v_addc_co_u32_e32 v43, vcc, 0, v159, vcc
	flat_store_dwordx4 v[42:43], v[52:55]
	flat_store_dwordx4 v[40:41], v[48:51] offset:64
	flat_store_dwordx4 v[40:41], v[28:31] offset:512
	flat_store_dwordx4 v[40:41], v[24:27] offset:576
	s_nop 1
	v_lshl_add_u64 v[24:25], v[158:159], 0, s[0:1]
	s_mov_b32 s0, 0xa0000
	v_add_co_u32_e32 v26, vcc, s0, v158
	s_mov_b64 s[0:1], 0xb0000
	s_nop 0
	v_addc_co_u32_e32 v27, vcc, 0, v159, vcc
	flat_store_dwordx4 v[26:27], v[36:39]
	flat_store_dwordx4 v[24:25], v[32:35] offset:64
	flat_store_dwordx4 v[24:25], v[12:15] offset:512
	flat_store_dwordx4 v[24:25], v[8:11] offset:576
	s_nop 1
	v_add_co_u32_e32 v10, vcc, 0xb0000, v158
	v_lshl_add_u64 v[8:9], v[158:159], 0, s[0:1]
	s_nop 0
	v_addc_co_u32_e32 v11, vcc, 0, v159, vcc
	s_and_b64 vcc, exec, s[6:7]
	s_mov_b64 s[0:1], s[8:9]
	flat_store_dwordx4 v[10:11], v[20:23]
	flat_store_dwordx4 v[8:9], v[16:19] offset:64
	flat_store_dwordx4 v[8:9], v[4:7] offset:512
	flat_store_dwordx4 v[8:9], v[0:3] offset:576
	s_cbranch_vccz .LBB0_160
	s_waitcnt vmcnt(0)
	s_cmpk_gt_u32 s51, 0xff
	s_cbranch_scc1 .LBB0_173
	s_barrier

.LBB0_203:
	s_add_u32 s2, s44, s13
	s_addc_u32 s15, s45, 0
	s_add_u32 s17, s2, 0x100
	s_addc_u32 s21, s15, 0
	s_and_b64 s[18:19], s[0:1], exec
	s_cselect_b32 s81, s9, s21
	s_cselect_b32 s80, s8, s17
	s_add_u32 s13, s64, s13
	s_addc_u32 s17, s65, 0
	s_add_u32 s13, s13, 0x100
	s_addc_u32 s17, s17, 0
	s_add_i32 s21, 0, 0x10000
	s_and_b64 s[0:1], s[0:1], exec
	s_cselect_b32 s89, s11, s17
	s_cselect_b32 s88, s10, s13
	s_add_u32 s96, s2, 0x10080
	s_addc_u32 s97, s15, 0
	s_add_i32 s43, s21, s52
	s_add_i32 m0, s41, 0xc000
	s_add_i32 s47, s41, 0xe000
	s_add_i32 s42, 0, 0x14000
	s_add_i32 s31, s43, 0x2000
	s_add_u32 s76, s88, 0x40000
	v_add_u32_e32 v138, s21, v136
	s_addc_u32 s77, s89, 0
	s_add_i32 s19, s42, s52
	ds_read_b128 v[154:157], v138
	ds_read_b128 v[158:161], v138 offset:1024
	ds_read_b128 v[162:165], v138 offset:2048
	ds_read_b128 v[166:169], v138 offset:3072
	s_add_i32 s18, s19, 0x2000
	s_add_i32 s17, 0, 0x18000
	s_add_u32 s68, s80, 0x10000
	s_addc_u32 s69, s81, 0
	s_add_i32 s15, s17, s52
	s_add_i32 s13, 0, 0x1c000
	s_add_i32 s2, s15, 0x2000
	s_add_u32 s0, s88, 0x40080
	s_addc_u32 s1, s89, 0
	s_add_i32 s30, s13, s52
	s_add_i32 s21, s30, 0x2000
	ds_read_b128 v[170:173], v137
	ds_read_b128 v[174:177], v137 offset:1024
	ds_read_b128 v[178:181], v137 offset:2048
	ds_read_b128 v[182:185], v137 offset:3072
	ds_read_b128 v[186:189], v137 offset:4096
	ds_read_b128 v[190:193], v137 offset:5120
	ds_read_b128 v[194:197], v137 offset:6144
	ds_read_b128 v[198:201], v137 offset:7168
	global_load_lds_dwordx4 v128, s[96:97]
	s_mov_b32 m0, s47
	s_nop 0
	global_load_lds_dwordx4 v132, s[96:97]
	s_waitcnt lgkmcnt(8)
	s_barrier
	s_waitcnt lgkmcnt(0)
	s_setprio 1
	s_waitcnt lgkmcnt(0)
	v_mfma_f32_16x16x32_bf16 v[124:127], v[154:157], v[170:173], v[124:127]
	v_mfma_f32_16x16x32_bf16 v[120:123], v[162:165], v[170:173], v[120:123]
	v_mfma_f32_16x16x32_bf16 v[112:115], v[154:157], v[178:181], v[112:115]
	v_mfma_f32_16x16x32_bf16 v[104:107], v[162:165], v[178:181], v[104:107]
	v_mfma_f32_16x16x32_bf16 v[96:99], v[154:157], v[186:189], v[96:99]
	v_mfma_f32_16x16x32_bf16 v[88:91], v[162:165], v[186:189], v[88:91]
	v_mfma_f32_16x16x32_bf16 v[80:83], v[154:157], v[194:197], v[80:83]
	v_mfma_f32_16x16x32_bf16 v[72:75], v[162:165], v[194:197], v[72:75]
	v_mfma_f32_16x16x32_bf16 v[124:127], v[158:161], v[174:177], v[124:127]
	v_mfma_f32_16x16x32_bf16 v[120:123], v[166:169], v[174:177], v[120:123]
	v_mfma_f32_16x16x32_bf16 v[112:115], v[158:161], v[182:185], v[112:115]
	v_mfma_f32_16x16x32_bf16 v[104:107], v[166:169], v[182:185], v[104:107]
	v_mfma_f32_16x16x32_bf16 v[96:99], v[158:161], v[190:193], v[96:99]
	v_mfma_f32_16x16x32_bf16 v[88:91], v[166:169], v[190:193], v[88:91]
	v_mfma_f32_16x16x32_bf16 v[80:83], v[158:161], v[198:201], v[80:83]
	v_mfma_f32_16x16x32_bf16 v[72:75], v[166:169], v[198:201], v[72:75]
	s_setprio 0
	s_barrier
	v_add_u32_e32 v138, s42, v136
	s_mov_b32 m0, s43
	ds_read_b128 v[202:205], v138
	ds_read_b128 v[206:209], v138 offset:1024
	ds_read_b128 v[228:231], v138 offset:2048
	ds_read_b128 v[232:235], v138 offset:3072
	global_load_lds_dwordx4 v130, s[88:89]
	s_mov_b32 m0, s31
	s_nop 0
	global_load_lds_dwordx4 v134, s[88:89]
	s_barrier
	s_waitcnt lgkmcnt(0)
	s_setprio 1
	s_waitcnt lgkmcnt(0)
	v_mfma_f32_16x16x32_bf16 v[116:119], v[202:205], v[170:173], v[116:119]
	v_mfma_f32_16x16x32_bf16 v[108:111], v[228:231], v[170:173], v[108:111]
	v_mfma_f32_16x16x32_bf16 v[100:103], v[202:205], v[178:181], v[100:103]
	v_mfma_f32_16x16x32_bf16 v[92:95], v[228:231], v[178:181], v[92:95]
	v_mfma_f32_16x16x32_bf16 v[84:87], v[202:205], v[186:189], v[84:87]
	v_mfma_f32_16x16x32_bf16 v[76:79], v[228:231], v[186:189], v[76:79]
	v_mfma_f32_16x16x32_bf16 v[68:71], v[202:205], v[194:197], v[68:71]
	v_mfma_f32_16x16x32_bf16 v[64:67], v[228:231], v[194:197], v[64:67]
	v_mfma_f32_16x16x32_bf16 v[116:119], v[206:209], v[174:177], v[116:119]
	v_mfma_f32_16x16x32_bf16 v[108:111], v[232:235], v[174:177], v[108:111]
	v_mfma_f32_16x16x32_bf16 v[100:103], v[206:209], v[182:185], v[100:103]
	v_mfma_f32_16x16x32_bf16 v[92:95], v[232:235], v[182:185], v[92:95]
	v_mfma_f32_16x16x32_bf16 v[84:87], v[206:209], v[190:193], v[84:87]
	v_mfma_f32_16x16x32_bf16 v[76:79], v[232:235], v[190:193], v[76:79]
	v_mfma_f32_16x16x32_bf16 v[68:71], v[206:209], v[198:201], v[68:71]
	v_mfma_f32_16x16x32_bf16 v[64:67], v[232:235], v[198:201], v[64:67]
	s_setprio 0
	s_mov_b32 m0, s41
	s_barrier
	ds_read_b128 v[170:173], v137 offset:16384
	ds_read_b128 v[174:177], v137 offset:17408
	ds_read_b128 v[178:181], v137 offset:18432
	ds_read_b128 v[182:185], v137 offset:19456
	ds_read_b128 v[186:189], v137 offset:20480
	ds_read_b128 v[190:193], v137 offset:21504
	ds_read_b128 v[194:197], v137 offset:22528
	ds_read_b128 v[198:201], v137 offset:23552
	global_load_lds_dwordx4 v128, s[80:81]
	s_mov_b32 m0, s57
	s_nop 0
	global_load_lds_dwordx4 v132, s[80:81]
	s_barrier
	s_waitcnt lgkmcnt(0)
	s_setprio 1
	s_waitcnt lgkmcnt(0)
	v_mfma_f32_16x16x32_bf16 v[60:63], v[154:157], v[170:173], v[60:63]
	v_mfma_f32_16x16x32_bf16 v[56:59], v[162:165], v[170:173], v[56:59]
	v_mfma_f32_16x16x32_bf16 v[48:51], v[154:157], v[178:181], v[48:51]
	v_mfma_f32_16x16x32_bf16 v[40:43], v[162:165], v[178:181], v[40:43]
	v_mfma_f32_16x16x32_bf16 v[32:35], v[154:157], v[186:189], v[32:35]
	v_mfma_f32_16x16x32_bf16 v[24:27], v[162:165], v[186:189], v[24:27]
	v_mfma_f32_16x16x32_bf16 v[16:19], v[154:157], v[194:197], v[16:19]
	v_mfma_f32_16x16x32_bf16 v[8:11], v[162:165], v[194:197], v[8:11]
	v_mfma_f32_16x16x32_bf16 v[60:63], v[158:161], v[174:177], v[60:63]
	v_mfma_f32_16x16x32_bf16 v[56:59], v[166:169], v[174:177], v[56:59]
	v_mfma_f32_16x16x32_bf16 v[48:51], v[158:161], v[182:185], v[48:51]
	v_mfma_f32_16x16x32_bf16 v[40:43], v[166:169], v[182:185], v[40:43]
	v_mfma_f32_16x16x32_bf16 v[32:35], v[158:161], v[190:193], v[32:35]
	v_mfma_f32_16x16x32_bf16 v[24:27], v[166:169], v[190:193], v[24:27]
	v_mfma_f32_16x16x32_bf16 v[16:19], v[158:161], v[198:201], v[16:19]
	v_mfma_f32_16x16x32_bf16 v[8:11], v[166:169], v[198:201], v[8:11]
	s_setprio 0
	s_barrier
	s_mov_b32 m0, s19
	s_nop 0
	global_load_lds_dwordx4 v130, s[76:77]
	s_mov_b32 m0, s18
	s_nop 0
	global_load_lds_dwordx4 v134, s[76:77]
	s_waitcnt vmcnt(6)
	s_barrier
	s_setprio 1
	v_mfma_f32_16x16x32_bf16 v[52:55], v[202:205], v[170:173], v[52:55]
	v_mfma_f32_16x16x32_bf16 v[44:47], v[228:231], v[170:173], v[44:47]
	v_mfma_f32_16x16x32_bf16 v[36:39], v[202:205], v[178:181], v[36:39]
	v_mfma_f32_16x16x32_bf16 v[28:31], v[228:231], v[178:181], v[28:31]
	v_mfma_f32_16x16x32_bf16 v[20:23], v[202:205], v[186:189], v[20:23]
	v_mfma_f32_16x16x32_bf16 v[12:15], v[228:231], v[186:189], v[12:15]
	v_mfma_f32_16x16x32_bf16 v[4:7], v[202:205], v[194:197], v[4:7]
	v_mfma_f32_16x16x32_bf16 v[0:3], v[228:231], v[194:197], v[0:3]
	v_mfma_f32_16x16x32_bf16 v[52:55], v[206:209], v[174:177], v[52:55]
	v_mfma_f32_16x16x32_bf16 v[44:47], v[232:235], v[174:177], v[44:47]
	v_mfma_f32_16x16x32_bf16 v[36:39], v[206:209], v[182:185], v[36:39]
	v_mfma_f32_16x16x32_bf16 v[28:31], v[232:235], v[182:185], v[28:31]
	v_mfma_f32_16x16x32_bf16 v[20:23], v[206:209], v[190:193], v[20:23]
	v_mfma_f32_16x16x32_bf16 v[12:15], v[232:235], v[190:193], v[12:15]
	v_mfma_f32_16x16x32_bf16 v[4:7], v[206:209], v[198:201], v[4:7]
	v_mfma_f32_16x16x32_bf16 v[0:3], v[232:235], v[198:201], v[0:3]
	s_setprio 0
	v_add_u32_e32 v140, s17, v136
	s_barrier
	ds_read_b128 v[154:157], v140
	ds_read_b128 v[158:161], v140 offset:1024
	ds_read_b128 v[162:165], v140 offset:2048
	ds_read_b128 v[166:169], v140 offset:3072
	s_mov_b32 m0, s58
	ds_read_b128 v[170:173], v137 offset:32768
	ds_read_b128 v[174:177], v137 offset:33792
	ds_read_b128 v[178:181], v137 offset:34816
	ds_read_b128 v[182:185], v137 offset:35840
	ds_read_b128 v[186:189], v137 offset:36864
	ds_read_b128 v[190:193], v137 offset:37888
	ds_read_b128 v[194:197], v137 offset:38912
	ds_read_b128 v[198:201], v137 offset:39936
	global_load_lds_dwordx4 v128, s[68:69]
	s_mov_b32 m0, s59
	s_nop 0
	global_load_lds_dwordx4 v132, s[68:69]
	s_waitcnt lgkmcnt(8)
	s_barrier
	s_waitcnt lgkmcnt(0)
	s_setprio 1
	s_waitcnt lgkmcnt(0)
	v_mfma_f32_16x16x32_bf16 v[124:127], v[154:157], v[170:173], v[124:127]
	v_mfma_f32_16x16x32_bf16 v[120:123], v[162:165], v[170:173], v[120:123]
	v_mfma_f32_16x16x32_bf16 v[112:115], v[154:157], v[178:181], v[112:115]
	v_mfma_f32_16x16x32_bf16 v[104:107], v[162:165], v[178:181], v[104:107]
	v_mfma_f32_16x16x32_bf16 v[96:99], v[154:157], v[186:189], v[96:99]
	v_mfma_f32_16x16x32_bf16 v[88:91], v[162:165], v[186:189], v[88:91]
	v_mfma_f32_16x16x32_bf16 v[80:83], v[154:157], v[194:197], v[80:83]
	v_mfma_f32_16x16x32_bf16 v[72:75], v[162:165], v[194:197], v[72:75]
	v_mfma_f32_16x16x32_bf16 v[124:127], v[158:161], v[174:177], v[124:127]
	v_mfma_f32_16x16x32_bf16 v[120:123], v[166:169], v[174:177], v[120:123]
	v_mfma_f32_16x16x32_bf16 v[112:115], v[158:161], v[182:185], v[112:115]
	v_mfma_f32_16x16x32_bf16 v[104:107], v[166:169], v[182:185], v[104:107]
	v_mfma_f32_16x16x32_bf16 v[96:99], v[158:161], v[190:193], v[96:99]
	v_mfma_f32_16x16x32_bf16 v[88:91], v[166:169], v[190:193], v[88:91]
	v_mfma_f32_16x16x32_bf16 v[80:83], v[158:161], v[198:201], v[80:83]
	v_mfma_f32_16x16x32_bf16 v[72:75], v[166:169], v[198:201], v[72:75]
	s_setprio 0
	s_barrier
	s_mov_b32 m0, s15
	v_add_u32_e32 v140, s13, v136
	ds_read_b128 v[202:205], v140
	ds_read_b128 v[206:209], v140 offset:1024
	ds_read_b128 v[228:231], v140 offset:2048
	ds_read_b128 v[232:235], v140 offset:3072
	s_add_u32 s100, s88, 0x80
	s_addc_u32 s101, s89, 0
	global_load_lds_dwordx4 v130, s[100:101]
	s_mov_b32 m0, s2
	s_nop 0
	global_load_lds_dwordx4 v134, s[100:101]
	s_barrier
	s_waitcnt lgkmcnt(0)
	s_setprio 1
	s_waitcnt lgkmcnt(0)
	v_mfma_f32_16x16x32_bf16 v[116:119], v[202:205], v[170:173], v[116:119]
	v_mfma_f32_16x16x32_bf16 v[108:111], v[228:231], v[170:173], v[108:111]
	v_mfma_f32_16x16x32_bf16 v[100:103], v[202:205], v[178:181], v[100:103]
	v_mfma_f32_16x16x32_bf16 v[92:95], v[228:231], v[178:181], v[92:95]
	v_mfma_f32_16x16x32_bf16 v[84:87], v[202:205], v[186:189], v[84:87]
	v_mfma_f32_16x16x32_bf16 v[76:79], v[228:231], v[186:189], v[76:79]
	v_mfma_f32_16x16x32_bf16 v[68:71], v[202:205], v[194:197], v[68:71]
	v_mfma_f32_16x16x32_bf16 v[64:67], v[228:231], v[194:197], v[64:67]
	v_mfma_f32_16x16x32_bf16 v[116:119], v[206:209], v[174:177], v[116:119]
	v_mfma_f32_16x16x32_bf16 v[108:111], v[232:235], v[174:177], v[108:111]
	v_mfma_f32_16x16x32_bf16 v[100:103], v[206:209], v[182:185], v[100:103]
	v_mfma_f32_16x16x32_bf16 v[92:95], v[232:235], v[182:185], v[92:95]
	v_mfma_f32_16x16x32_bf16 v[84:87], v[206:209], v[190:193], v[84:87]
	v_mfma_f32_16x16x32_bf16 v[76:79], v[232:235], v[190:193], v[76:79]
	v_mfma_f32_16x16x32_bf16 v[68:71], v[206:209], v[198:201], v[68:71]
	v_mfma_f32_16x16x32_bf16 v[64:67], v[232:235], v[198:201], v[64:67]
	s_setprio 0
	s_mov_b32 m0, s73
	s_barrier
	ds_read_b128 v[170:173], v137 offset:49152
	ds_read_b128 v[174:177], v137 offset:50176
	ds_read_b128 v[178:181], v137 offset:51200
	ds_read_b128 v[182:185], v137 offset:52224
	ds_read_b128 v[186:189], v137 offset:53248
	ds_read_b128 v[190:193], v137 offset:54272
	ds_read_b128 v[194:197], v137 offset:55296
	ds_read_b128 v[198:201], v137 offset:56320
	s_add_u32 s100, s80, 0x80
	s_addc_u32 s101, s81, 0
	global_load_lds_dwordx4 v128, s[100:101]
	s_mov_b32 m0, s74
	s_nop 0
	global_load_lds_dwordx4 v132, s[100:101]
	s_barrier
	s_waitcnt lgkmcnt(0)
	s_setprio 1
	s_waitcnt lgkmcnt(0)
	v_mfma_f32_16x16x32_bf16 v[60:63], v[154:157], v[170:173], v[60:63]
	v_mfma_f32_16x16x32_bf16 v[56:59], v[162:165], v[170:173], v[56:59]
	v_mfma_f32_16x16x32_bf16 v[48:51], v[154:157], v[178:181], v[48:51]
	v_mfma_f32_16x16x32_bf16 v[40:43], v[162:165], v[178:181], v[40:43]
	v_mfma_f32_16x16x32_bf16 v[32:35], v[154:157], v[186:189], v[32:35]
	v_mfma_f32_16x16x32_bf16 v[24:27], v[162:165], v[186:189], v[24:27]
	v_mfma_f32_16x16x32_bf16 v[16:19], v[154:157], v[194:197], v[16:19]
	v_mfma_f32_16x16x32_bf16 v[8:11], v[162:165], v[194:197], v[8:11]
	v_mfma_f32_16x16x32_bf16 v[60:63], v[158:161], v[174:177], v[60:63]
	v_mfma_f32_16x16x32_bf16 v[56:59], v[166:169], v[174:177], v[56:59]
	v_mfma_f32_16x16x32_bf16 v[48:51], v[158:161], v[182:185], v[48:51]
	v_mfma_f32_16x16x32_bf16 v[40:43], v[166:169], v[182:185], v[40:43]
	v_mfma_f32_16x16x32_bf16 v[32:35], v[158:161], v[190:193], v[32:35]
	v_mfma_f32_16x16x32_bf16 v[24:27], v[166:169], v[190:193], v[24:27]
	v_mfma_f32_16x16x32_bf16 v[16:19], v[158:161], v[198:201], v[16:19]
	v_mfma_f32_16x16x32_bf16 v[8:11], v[166:169], v[198:201], v[8:11]
	s_setprio 0
	s_barrier
	s_mov_b32 m0, s30
	s_nop 0
	global_load_lds_dwordx4 v130, s[0:1]
	s_mov_b32 m0, s21
	s_nop 0
	global_load_lds_dwordx4 v134, s[0:1]
	s_waitcnt vmcnt(6)
	s_barrier
	s_setprio 1
	v_mfma_f32_16x16x32_bf16 v[52:55], v[202:205], v[170:173], v[52:55]
	v_mfma_f32_16x16x32_bf16 v[44:47], v[228:231], v[170:173], v[44:47]
	v_mfma_f32_16x16x32_bf16 v[36:39], v[202:205], v[178:181], v[36:39]
	v_mfma_f32_16x16x32_bf16 v[28:31], v[228:231], v[178:181], v[28:31]
	v_mfma_f32_16x16x32_bf16 v[20:23], v[202:205], v[186:189], v[20:23]
	v_mfma_f32_16x16x32_bf16 v[12:15], v[228:231], v[186:189], v[12:15]
	v_mfma_f32_16x16x32_bf16 v[4:7], v[202:205], v[194:197], v[4:7]
	v_mfma_f32_16x16x32_bf16 v[0:3], v[228:231], v[194:197], v[0:3]
	v_mfma_f32_16x16x32_bf16 v[52:55], v[206:209], v[174:177], v[52:55]
	v_mfma_f32_16x16x32_bf16 v[44:47], v[232:235], v[174:177], v[44:47]
	v_mfma_f32_16x16x32_bf16 v[36:39], v[206:209], v[182:185], v[36:39]
	v_mfma_f32_16x16x32_bf16 v[28:31], v[232:235], v[182:185], v[28:31]
	v_mfma_f32_16x16x32_bf16 v[20:23], v[206:209], v[190:193], v[20:23]
	v_mfma_f32_16x16x32_bf16 v[12:15], v[232:235], v[190:193], v[12:15]
	v_mfma_f32_16x16x32_bf16 v[4:7], v[206:209], v[198:201], v[4:7]
	v_mfma_f32_16x16x32_bf16 v[0:3], v[232:235], v[198:201], v[0:3]
	s_setprio 0
	s_movk_i32 s13, 0x100
	s_andn2_b64 vcc, exec, s[66:67]
	s_mov_b64 s[0:1], -1
	s_mov_b64 s[66:67], 0
	s_barrier
	s_cbranch_vccz .LBB0_203
	v_mbcnt_lo_u32_b32 v138, -1, 0
	v_mbcnt_hi_u32_b32 v138, -1, v138
	s_lshl_b32 s0, s40, 8
	v_ashrrev_i32_e32 v139, 1, v138
	s_or_b32 s0, s0, s72
	v_and_b32_e32 v139, -8, v139
	v_add_u32_e32 v139, s0, v139
	s_lshl_b32 s1, s20, 8
	v_and_or_b32 v138, v138, 15, s71
	s_and_b32 s1, s1, 0x300
	v_cvt_pk_bf16_f32 v124, v124, v125
	v_cvt_pk_bf16_f32 v125, v126, v127
	v_cvt_pk_bf16_f32 v126, v120, v121
	v_ashrrev_i32_e32 v120, 1, v139
	v_add_u32_e32 v138, s1, v138
	v_cvt_pk_bf16_f32 v127, v122, v123
	v_and_b32_e32 v122, 0xfffffc00, v120
	v_add_u32_e32 v120, v122, v138
	s_ashr_i32 s0, s20, 2
	v_ashrrev_i32_e32 v121, 31, v120
	s_ashr_i32 s1, s0, 31
	v_lshlrev_b64 v[120:121], 13, v[120:121]
	s_lshl_b64 s[0:1], s[0:1], 12
	v_and_b32_e32 v140, 0x7f8, v139
	v_lshl_add_u64 v[120:121], s[38:39], 0, v[120:121]
	v_lshl_add_u64 v[120:121], v[120:121], 0, s[0:1]
	v_lshlrev_b32_e32 v140, 1, v140
	v_lshl_add_u64 v[120:121], v[120:121], 0, v[140:141]
	flat_store_dwordx4 v[120:121], v[124:127]
	v_add_u32_e32 v120, 0x80, v139
	v_cvt_pk_bf16_f32 v116, v116, v117
	v_cvt_pk_bf16_f32 v117, v118, v119
	v_cvt_pk_bf16_f32 v118, v108, v109
	v_ashrrev_i32_e32 v108, 1, v120
	v_and_b32_e32 v121, 0x7f8, v120
	v_and_b32_e32 v120, 0xfffffc00, v108
	v_add_u32_e32 v108, v120, v138
	v_ashrrev_i32_e32 v109, 31, v108
	v_lshlrev_b64 v[108:109], 13, v[108:109]
	v_lshl_add_u64 v[108:109], s[38:39], 0, v[108:109]
	v_cvt_pk_bf16_f32 v119, v110, v111
	v_lshl_add_u64 v[110:111], v[108:109], 0, s[0:1]
	v_lshlrev_b32_e32 v108, 1, v121
	v_mov_b32_e32 v109, v141
	v_lshl_add_u64 v[110:111], v[110:111], 0, v[108:109]
	flat_store_dwordx4 v[110:111], v[116:119]
	v_cvt_pk_bf16_f32 v110, v112, v113
	v_cvt_pk_bf16_f32 v112, v104, v105
	v_cvt_pk_bf16_f32 v100, v100, v101
	v_cvt_pk_bf16_f32 v101, v102, v103
	v_cvt_pk_bf16_f32 v102, v92, v93
	s_nop 1
	v_or_b32_e32 v116, 16, v138
	v_add_u32_e32 v104, v122, v116
	v_add_u32_e32 v92, v120, v116
	v_ashrrev_i32_e32 v105, 31, v104
	v_ashrrev_i32_e32 v93, 31, v92
	v_lshlrev_b64 v[104:105], 13, v[104:105]
	v_lshlrev_b64 v[92:93], 13, v[92:93]
	v_lshl_add_u64 v[104:105], s[38:39], 0, v[104:105]
	v_lshl_add_u64 v[92:93], s[38:39], 0, v[92:93]
	v_lshl_add_u64 v[104:105], v[104:105], 0, s[0:1]
	v_lshl_add_u64 v[92:93], v[92:93], 0, s[0:1]
	v_lshl_add_u64 v[104:105], v[104:105], 0, v[140:141]
	v_lshl_add_u64 v[92:93], v[92:93], 0, v[108:109]
	v_cvt_pk_bf16_f32 v111, v114, v115
	v_cvt_pk_bf16_f32 v113, v106, v107
	flat_store_dwordx4 v[104:105], v[110:113]
	v_cvt_pk_bf16_f32 v103, v94, v95
	flat_store_dwordx4 v[92:93], v[100:103]
	v_cvt_pk_bf16_f32 v94, v88, v89
	v_cvt_pk_bf16_f32 v84, v84, v85
	v_cvt_pk_bf16_f32 v85, v86, v87
	v_cvt_pk_bf16_f32 v86, v76, v77
	v_cvt_pk_bf16_f32 v92, v96, v97
	s_nop 1
	v_or_b32_e32 v100, 32, v138
	v_add_u32_e32 v88, v122, v100
	v_add_u32_e32 v76, v120, v100
	v_ashrrev_i32_e32 v89, 31, v88
	v_ashrrev_i32_e32 v77, 31, v76
	v_lshlrev_b64 v[88:89], 13, v[88:89]
	v_lshlrev_b64 v[76:77], 13, v[76:77]
	v_lshl_add_u64 v[88:89], s[38:39], 0, v[88:89]
	v_lshl_add_u64 v[76:77], s[38:39], 0, v[76:77]
	v_lshl_add_u64 v[88:89], v[88:89], 0, s[0:1]
	v_lshl_add_u64 v[76:77], v[76:77], 0, s[0:1]
	v_lshl_add_u64 v[88:89], v[88:89], 0, v[140:141]
	v_lshl_add_u64 v[76:77], v[76:77], 0, v[108:109]
	v_cvt_pk_bf16_f32 v93, v98, v99
	v_cvt_pk_bf16_f32 v95, v90, v91
	flat_store_dwordx4 v[88:89], v[92:95]
	v_cvt_pk_bf16_f32 v87, v78, v79
	flat_store_dwordx4 v[76:77], v[84:87]
	v_cvt_pk_bf16_f32 v78, v72, v73
	v_cvt_pk_bf16_f32 v68, v68, v69
	v_cvt_pk_bf16_f32 v69, v70, v71
	v_cvt_pk_bf16_f32 v70, v64, v65
	v_cvt_pk_bf16_f32 v76, v80, v81
	s_nop 1
	v_or_b32_e32 v84, 48, v138
	v_add_u32_e32 v72, v122, v84
	v_add_u32_e32 v64, v120, v84
	v_ashrrev_i32_e32 v73, 31, v72
	v_ashrrev_i32_e32 v65, 31, v64
	v_lshlrev_b64 v[72:73], 13, v[72:73]
	v_lshlrev_b64 v[64:65], 13, v[64:65]
	v_lshl_add_u64 v[72:73], s[38:39], 0, v[72:73]
	v_lshl_add_u64 v[64:65], s[38:39], 0, v[64:65]
	v_lshl_add_u64 v[72:73], v[72:73], 0, s[0:1]
	v_lshl_add_u64 v[64:65], v[64:65], 0, s[0:1]
	v_lshl_add_u64 v[72:73], v[72:73], 0, v[140:141]
	v_lshl_add_u64 v[64:65], v[64:65], 0, v[108:109]
	v_cvt_pk_bf16_f32 v77, v82, v83
	v_cvt_pk_bf16_f32 v79, v74, v75
	flat_store_dwordx4 v[72:73], v[76:79]
	v_cvt_pk_bf16_f32 v71, v66, v67
	flat_store_dwordx4 v[64:65], v[68:71]
	v_add_u32_e32 v64, 0x80, v138
	v_cvt_pk_bf16_f32 v60, v60, v61
	v_cvt_pk_bf16_f32 v61, v62, v63
	v_cvt_pk_bf16_f32 v62, v56, v57
	v_add_u32_e32 v56, v122, v64
	v_cvt_pk_bf16_f32 v52, v52, v53
	v_cvt_pk_bf16_f32 v53, v54, v55
	v_cvt_pk_bf16_f32 v54, v44, v45
	v_add_u32_e32 v44, v120, v64
	v_ashrrev_i32_e32 v57, 31, v56
	v_ashrrev_i32_e32 v45, 31, v44
	v_lshlrev_b64 v[56:57], 13, v[56:57]
	v_lshlrev_b64 v[44:45], 13, v[44:45]
	v_lshl_add_u64 v[56:57], s[38:39], 0, v[56:57]
	v_lshl_add_u64 v[44:45], s[38:39], 0, v[44:45]
	v_lshl_add_u64 v[56:57], v[56:57], 0, s[0:1]
	v_lshl_add_u64 v[44:45], v[44:45], 0, s[0:1]
	v_lshl_add_u64 v[56:57], v[56:57], 0, v[140:141]
	v_lshl_add_u64 v[44:45], v[44:45], 0, v[108:109]
	v_cvt_pk_bf16_f32 v63, v58, v59
	flat_store_dwordx4 v[56:57], v[60:63]
	v_cvt_pk_bf16_f32 v55, v46, v47
	flat_store_dwordx4 v[44:45], v[52:55]
	v_cvt_pk_bf16_f32 v46, v40, v41
	v_cvt_pk_bf16_f32 v36, v36, v37
	v_cvt_pk_bf16_f32 v37, v38, v39
	v_cvt_pk_bf16_f32 v38, v28, v29
	v_cvt_pk_bf16_f32 v44, v48, v49
	s_nop 1
	v_add_u32_e32 v52, 0x90, v138
	v_add_u32_e32 v40, v122, v52
	v_add_u32_e32 v28, v120, v52
	v_ashrrev_i32_e32 v41, 31, v40
	v_ashrrev_i32_e32 v29, 31, v28
	v_lshlrev_b64 v[40:41], 13, v[40:41]
	v_lshlrev_b64 v[28:29], 13, v[28:29]
	v_lshl_add_u64 v[40:41], s[38:39], 0, v[40:41]
	v_lshl_add_u64 v[28:29], s[38:39], 0, v[28:29]
	v_lshl_add_u64 v[40:41], v[40:41], 0, s[0:1]
	v_lshl_add_u64 v[28:29], v[28:29], 0, s[0:1]
	v_lshl_add_u64 v[40:41], v[40:41], 0, v[140:141]
	v_lshl_add_u64 v[28:29], v[28:29], 0, v[108:109]
	v_cvt_pk_bf16_f32 v45, v50, v51
	v_cvt_pk_bf16_f32 v47, v42, v43
	flat_store_dwordx4 v[40:41], v[44:47]
	v_cvt_pk_bf16_f32 v39, v30, v31
	flat_store_dwordx4 v[28:29], v[36:39]
	v_cvt_pk_bf16_f32 v30, v24, v25
	v_cvt_pk_bf16_f32 v20, v20, v21
	v_cvt_pk_bf16_f32 v21, v22, v23
	v_cvt_pk_bf16_f32 v22, v12, v13
	v_cvt_pk_bf16_f32 v28, v32, v33
	s_nop 1
	v_add_u32_e32 v36, 0xa0, v138
	v_add_u32_e32 v24, v122, v36
	v_add_u32_e32 v12, v120, v36
	v_ashrrev_i32_e32 v25, 31, v24
	v_ashrrev_i32_e32 v13, 31, v12
	v_lshlrev_b64 v[24:25], 13, v[24:25]
	v_lshlrev_b64 v[12:13], 13, v[12:13]
	v_lshl_add_u64 v[24:25], s[38:39], 0, v[24:25]
	v_lshl_add_u64 v[12:13], s[38:39], 0, v[12:13]
	v_lshl_add_u64 v[24:25], v[24:25], 0, s[0:1]
	v_lshl_add_u64 v[12:13], v[12:13], 0, s[0:1]
	v_lshl_add_u64 v[24:25], v[24:25], 0, v[140:141]
	v_lshl_add_u64 v[12:13], v[12:13], 0, v[108:109]
	v_cvt_pk_bf16_f32 v29, v34, v35
	v_cvt_pk_bf16_f32 v31, v26, v27
	flat_store_dwordx4 v[24:25], v[28:31]
	v_cvt_pk_bf16_f32 v23, v14, v15
	flat_store_dwordx4 v[12:13], v[20:23]
	v_cvt_pk_bf16_f32 v14, v8, v9
	v_cvt_pk_bf16_f32 v4, v4, v5
	v_cvt_pk_bf16_f32 v5, v6, v7
	v_cvt_pk_bf16_f32 v6, v0, v1
	s_and_b64 vcc, exec, s[6:7]
	s_nop 0
	v_add_u32_e32 v20, 0xb0, v138
	v_add_u32_e32 v8, v122, v20
	v_add_u32_e32 v0, v120, v20
	v_ashrrev_i32_e32 v9, 31, v8
	v_ashrrev_i32_e32 v1, 31, v0
	v_lshlrev_b64 v[8:9], 13, v[8:9]
	v_lshlrev_b64 v[0:1], 13, v[0:1]
	v_lshl_add_u64 v[8:9], s[38:39], 0, v[8:9]
	v_lshl_add_u64 v[0:1], s[38:39], 0, v[0:1]
	v_lshl_add_u64 v[8:9], v[8:9], 0, s[0:1]
	v_lshl_add_u64 v[0:1], v[0:1], 0, s[0:1]
	v_lshl_add_u64 v[8:9], v[8:9], 0, v[140:141]
	v_lshl_add_u64 v[0:1], v[0:1], 0, v[108:109]
	s_mov_b32 s20, s12
	s_mov_b32 s40, s14
	s_mov_b64 s[64:65], s[10:11]
	s_mov_b64 s[44:45], s[8:9]
	v_readlane_b32 s89, v252, 11
	s_mov_b32 s81, 0x10000
	s_mov_b32 s88, 0x8000
	v_readlane_b32 s77, v252, 31
	v_cvt_pk_bf16_f32 v12, v16, v17
	v_cvt_pk_bf16_f32 v13, v18, v19
	v_cvt_pk_bf16_f32 v15, v10, v11
	flat_store_dwordx4 v[8:9], v[12:15]
	v_cvt_pk_bf16_f32 v7, v2, v3
	flat_store_dwordx4 v[0:1], v[4:7]
	s_cbranch_vccz .LBB0_192
	s_waitcnt vmcnt(0)
	s_cmpk_gt_u32 s49, 0xff
	s_cbranch_scc1 .LBB0_207
	s_barrier

.LBB0_275:
	s_add_u32 s0, s12, 0x100
	s_addc_u32 s1, s13, 0
	s_add_i32 s2, 0, 0x10000
	v_add_u32_e32 v138, s2, v154
	ds_read_b128 v[156:159], v138
	ds_read_b128 v[160:163], v138 offset:1024
	ds_read_b128 v[164:167], v138 offset:2048
	ds_read_b128 v[168:171], v138 offset:3072
	s_cmp_eq_u32 s65, 40
	s_cselect_b32 s15, s5, s1
	s_cselect_b32 s14, s4, s0
	s_cselect_b32 s11, s9, s64
	s_cselect_b32 s10, s8, s59
	s_add_i32 m0, s40, 0xc000
	ds_read_b128 v[172:175], v155
	ds_read_b128 v[176:179], v155 offset:1024
	ds_read_b128 v[180:183], v155 offset:2048
	ds_read_b128 v[184:187], v155 offset:3072
	ds_read_b128 v[188:191], v155 offset:4096
	ds_read_b128 v[192:195], v155 offset:5120
	ds_read_b128 v[196:199], v155 offset:6144
	ds_read_b128 v[200:203], v155 offset:7168
	global_load_lds_dwordx4 v136, s[12:13]
	s_add_i32 m0, s40, 0xe000
	s_nop 0
	global_load_lds_dwordx4 v134, s[12:13]
	s_waitcnt lgkmcnt(8)
	s_barrier
	s_waitcnt lgkmcnt(0)
	s_setprio 1
	s_waitcnt lgkmcnt(0)
	v_mfma_f32_16x16x32_bf16 v[124:127], v[156:159], v[172:175], v[124:127]
	v_mfma_f32_16x16x32_bf16 v[120:123], v[164:167], v[172:175], v[120:123]
	v_mfma_f32_16x16x32_bf16 v[116:119], v[156:159], v[180:183], v[116:119]
	v_mfma_f32_16x16x32_bf16 v[108:111], v[164:167], v[180:183], v[108:111]
	v_mfma_f32_16x16x32_bf16 v[100:103], v[156:159], v[188:191], v[100:103]
	v_mfma_f32_16x16x32_bf16 v[92:95], v[164:167], v[188:191], v[92:95]
	v_mfma_f32_16x16x32_bf16 v[84:87], v[156:159], v[196:199], v[84:87]
	v_mfma_f32_16x16x32_bf16 v[76:79], v[164:167], v[196:199], v[76:79]
	v_mfma_f32_16x16x32_bf16 v[124:127], v[160:163], v[176:179], v[124:127]
	v_mfma_f32_16x16x32_bf16 v[120:123], v[168:171], v[176:179], v[120:123]
	v_mfma_f32_16x16x32_bf16 v[116:119], v[160:163], v[184:187], v[116:119]
	v_mfma_f32_16x16x32_bf16 v[108:111], v[168:171], v[184:187], v[108:111]
	v_mfma_f32_16x16x32_bf16 v[100:103], v[160:163], v[192:195], v[100:103]
	v_mfma_f32_16x16x32_bf16 v[92:95], v[168:171], v[192:195], v[92:95]
	v_mfma_f32_16x16x32_bf16 v[84:87], v[160:163], v[200:203], v[84:87]
	v_mfma_f32_16x16x32_bf16 v[76:79], v[168:171], v[200:203], v[76:79]
	s_setprio 0
	s_barrier
	s_add_i32 s18, 0, 0x14000
	v_add_u32_e32 v138, s18, v154
	s_add_i32 s2, s2, s39
	ds_read_b128 v[204:207], v138
	ds_read_b128 v[208:211], v138 offset:1024
	ds_read_b128 v[228:231], v138 offset:2048
	ds_read_b128 v[232:235], v138 offset:3072
	s_mov_b32 m0, s2
	s_nop 0
	global_load_lds_dwordx4 v140, s[10:11]
	s_add_i32 m0, s2, 0x2000
	s_nop 0
	global_load_lds_dwordx4 v132, s[10:11]
	s_barrier
	s_waitcnt lgkmcnt(0)
	s_setprio 1
	s_waitcnt lgkmcnt(0)
	v_mfma_f32_16x16x32_bf16 v[112:115], v[204:207], v[172:175], v[112:115]
	v_mfma_f32_16x16x32_bf16 v[104:107], v[228:231], v[172:175], v[104:107]
	v_mfma_f32_16x16x32_bf16 v[96:99], v[204:207], v[180:183], v[96:99]
	v_mfma_f32_16x16x32_bf16 v[88:91], v[228:231], v[180:183], v[88:91]
	v_mfma_f32_16x16x32_bf16 v[80:83], v[204:207], v[188:191], v[80:83]
	v_mfma_f32_16x16x32_bf16 v[72:75], v[228:231], v[188:191], v[72:75]
	v_mfma_f32_16x16x32_bf16 v[68:71], v[204:207], v[196:199], v[68:71]
	v_mfma_f32_16x16x32_bf16 v[64:67], v[228:231], v[196:199], v[64:67]
	v_mfma_f32_16x16x32_bf16 v[112:115], v[208:211], v[176:179], v[112:115]
	v_mfma_f32_16x16x32_bf16 v[104:107], v[232:235], v[176:179], v[104:107]
	v_mfma_f32_16x16x32_bf16 v[96:99], v[208:211], v[184:187], v[96:99]
	v_mfma_f32_16x16x32_bf16 v[88:91], v[232:235], v[184:187], v[88:91]
	v_mfma_f32_16x16x32_bf16 v[80:83], v[208:211], v[192:195], v[80:83]
	v_mfma_f32_16x16x32_bf16 v[72:75], v[232:235], v[192:195], v[72:75]
	v_mfma_f32_16x16x32_bf16 v[68:71], v[208:211], v[200:203], v[68:71]
	v_mfma_f32_16x16x32_bf16 v[64:67], v[232:235], v[200:203], v[64:67]
	s_setprio 0
	s_mov_b32 m0, s40
	s_barrier
	ds_read_b128 v[172:175], v155 offset:16384
	ds_read_b128 v[176:179], v155 offset:17408
	ds_read_b128 v[180:183], v155 offset:18432
	ds_read_b128 v[184:187], v155 offset:19456
	ds_read_b128 v[188:191], v155 offset:20480
	ds_read_b128 v[192:195], v155 offset:21504
	ds_read_b128 v[196:199], v155 offset:22528
	ds_read_b128 v[200:203], v155 offset:23552
	global_load_lds_dwordx4 v128, s[14:15]
	s_mov_b32 m0, s41
	s_nop 0
	global_load_lds_dwordx4 v130, s[14:15]
	s_barrier
	s_waitcnt lgkmcnt(0)
	s_setprio 1
	s_waitcnt lgkmcnt(0)
	v_mfma_f32_16x16x32_bf16 v[60:63], v[156:159], v[172:175], v[60:63]
	v_mfma_f32_16x16x32_bf16 v[56:59], v[164:167], v[172:175], v[56:59]
	v_mfma_f32_16x16x32_bf16 v[52:55], v[156:159], v[180:183], v[52:55]
	v_mfma_f32_16x16x32_bf16 v[44:47], v[164:167], v[180:183], v[44:47]
	v_mfma_f32_16x16x32_bf16 v[36:39], v[156:159], v[188:191], v[36:39]
	v_mfma_f32_16x16x32_bf16 v[28:31], v[164:167], v[188:191], v[28:31]
	v_mfma_f32_16x16x32_bf16 v[20:23], v[156:159], v[196:199], v[20:23]
	v_mfma_f32_16x16x32_bf16 v[12:15], v[164:167], v[196:199], v[12:15]
	v_mfma_f32_16x16x32_bf16 v[60:63], v[160:163], v[176:179], v[60:63]
	v_mfma_f32_16x16x32_bf16 v[56:59], v[168:171], v[176:179], v[56:59]
	v_mfma_f32_16x16x32_bf16 v[52:55], v[160:163], v[184:187], v[52:55]
	v_mfma_f32_16x16x32_bf16 v[44:47], v[168:171], v[184:187], v[44:47]
	v_mfma_f32_16x16x32_bf16 v[36:39], v[160:163], v[192:195], v[36:39]
	v_mfma_f32_16x16x32_bf16 v[28:31], v[168:171], v[192:195], v[28:31]
	v_mfma_f32_16x16x32_bf16 v[20:23], v[160:163], v[200:203], v[20:23]
	v_mfma_f32_16x16x32_bf16 v[12:15], v[168:171], v[200:203], v[12:15]
	s_setprio 0
	s_barrier
	s_add_u32 s12, s10, 0xb0000
	s_addc_u32 s13, s11, 0
	s_add_i32 s2, s18, s39
	s_mov_b32 m0, s2
	s_nop 0
	global_load_lds_dwordx4 v140, s[12:13]
	s_add_i32 m0, s2, 0x2000
	s_nop 0
	global_load_lds_dwordx4 v132, s[12:13]
	s_waitcnt vmcnt(6)
	s_barrier
	s_setprio 1
	v_mfma_f32_16x16x32_bf16 v[48:51], v[204:207], v[172:175], v[48:51]
	v_mfma_f32_16x16x32_bf16 v[40:43], v[228:231], v[172:175], v[40:43]
	v_mfma_f32_16x16x32_bf16 v[32:35], v[204:207], v[180:183], v[32:35]
	v_mfma_f32_16x16x32_bf16 v[24:27], v[228:231], v[180:183], v[24:27]
	v_mfma_f32_16x16x32_bf16 v[16:19], v[204:207], v[188:191], v[16:19]
	v_mfma_f32_16x16x32_bf16 v[8:11], v[228:231], v[188:191], v[8:11]
	v_mfma_f32_16x16x32_bf16 v[4:7], v[204:207], v[196:199], v[4:7]
	v_mfma_f32_16x16x32_bf16 v[0:3], v[228:231], v[196:199], v[0:3]
	v_mfma_f32_16x16x32_bf16 v[48:51], v[208:211], v[176:179], v[48:51]
	v_mfma_f32_16x16x32_bf16 v[40:43], v[232:235], v[176:179], v[40:43]
	v_mfma_f32_16x16x32_bf16 v[32:35], v[208:211], v[184:187], v[32:35]
	v_mfma_f32_16x16x32_bf16 v[24:27], v[232:235], v[184:187], v[24:27]
	v_mfma_f32_16x16x32_bf16 v[16:19], v[208:211], v[192:195], v[16:19]
	v_mfma_f32_16x16x32_bf16 v[8:11], v[232:235], v[192:195], v[8:11]
	v_mfma_f32_16x16x32_bf16 v[4:7], v[208:211], v[200:203], v[4:7]
	v_mfma_f32_16x16x32_bf16 v[0:3], v[232:235], v[200:203], v[0:3]
	s_setprio 0
	s_add_i32 s2, 0, 0x18000
	v_add_u32_e32 v168, s2, v154
	s_barrier
	ds_read_b128 v[156:159], v168
	ds_read_b128 v[160:163], v168 offset:1024
	ds_read_b128 v[164:167], v168 offset:2048
	ds_read_b128 v[168:171], v168 offset:3072
	s_add_u32 s12, s14, 0xb0000
	s_addc_u32 s13, s15, 0
	s_mov_b32 m0, s44
	ds_read_b128 v[172:175], v155 offset:32768
	ds_read_b128 v[176:179], v155 offset:33792
	ds_read_b128 v[180:183], v155 offset:34816
	ds_read_b128 v[184:187], v155 offset:35840
	ds_read_b128 v[188:191], v155 offset:36864
	ds_read_b128 v[192:195], v155 offset:37888
	ds_read_b128 v[196:199], v155 offset:38912
	ds_read_b128 v[200:203], v155 offset:39936
	global_load_lds_dwordx4 v128, s[12:13]
	s_mov_b32 m0, s45
	s_nop 0
	global_load_lds_dwordx4 v130, s[12:13]
	s_waitcnt lgkmcnt(8)
	s_barrier
	s_waitcnt lgkmcnt(0)
	s_setprio 1
	s_waitcnt lgkmcnt(0)
	v_mfma_f32_16x16x32_bf16 v[124:127], v[156:159], v[172:175], v[124:127]
	v_mfma_f32_16x16x32_bf16 v[120:123], v[164:167], v[172:175], v[120:123]
	v_mfma_f32_16x16x32_bf16 v[116:119], v[156:159], v[180:183], v[116:119]
	v_mfma_f32_16x16x32_bf16 v[108:111], v[164:167], v[180:183], v[108:111]
	v_mfma_f32_16x16x32_bf16 v[100:103], v[156:159], v[188:191], v[100:103]
	v_mfma_f32_16x16x32_bf16 v[92:95], v[164:167], v[188:191], v[92:95]
	v_mfma_f32_16x16x32_bf16 v[84:87], v[156:159], v[196:199], v[84:87]
	v_mfma_f32_16x16x32_bf16 v[76:79], v[164:167], v[196:199], v[76:79]
	v_mfma_f32_16x16x32_bf16 v[124:127], v[160:163], v[176:179], v[124:127]
	v_mfma_f32_16x16x32_bf16 v[120:123], v[168:171], v[176:179], v[120:123]
	v_mfma_f32_16x16x32_bf16 v[116:119], v[160:163], v[184:187], v[116:119]
	v_mfma_f32_16x16x32_bf16 v[108:111], v[168:171], v[184:187], v[108:111]
	v_mfma_f32_16x16x32_bf16 v[100:103], v[160:163], v[192:195], v[100:103]
	v_mfma_f32_16x16x32_bf16 v[92:95], v[168:171], v[192:195], v[92:95]
	v_mfma_f32_16x16x32_bf16 v[84:87], v[160:163], v[200:203], v[84:87]
	v_mfma_f32_16x16x32_bf16 v[76:79], v[168:171], v[200:203], v[76:79]
	s_setprio 0
	s_barrier
	s_add_i32 s12, 0, 0x1c000
	s_add_i32 s2, s2, s39
	v_add_u32_e32 v232, s12, v154
	s_mov_b32 m0, s2
	ds_read_b128 v[204:207], v232
	ds_read_b128 v[208:211], v232 offset:1024
	ds_read_b128 v[228:231], v232 offset:2048
	ds_read_b128 v[232:235], v232 offset:3072
	s_add_u32 s100, s10, 0x80
	s_addc_u32 s101, s11, 0
	global_load_lds_dwordx4 v140, s[100:101]
	s_add_i32 m0, s2, 0x2000
	s_nop 0
	global_load_lds_dwordx4 v132, s[100:101]
	s_barrier
	s_waitcnt lgkmcnt(0)
	s_setprio 1
	s_waitcnt lgkmcnt(0)
	v_mfma_f32_16x16x32_bf16 v[112:115], v[204:207], v[172:175], v[112:115]
	v_mfma_f32_16x16x32_bf16 v[104:107], v[228:231], v[172:175], v[104:107]
	v_mfma_f32_16x16x32_bf16 v[96:99], v[204:207], v[180:183], v[96:99]
	v_mfma_f32_16x16x32_bf16 v[88:91], v[228:231], v[180:183], v[88:91]
	v_mfma_f32_16x16x32_bf16 v[80:83], v[204:207], v[188:191], v[80:83]
	v_mfma_f32_16x16x32_bf16 v[72:75], v[228:231], v[188:191], v[72:75]
	v_mfma_f32_16x16x32_bf16 v[68:71], v[204:207], v[196:199], v[68:71]
	v_mfma_f32_16x16x32_bf16 v[64:67], v[228:231], v[196:199], v[64:67]
	v_mfma_f32_16x16x32_bf16 v[112:115], v[208:211], v[176:179], v[112:115]
	v_mfma_f32_16x16x32_bf16 v[104:107], v[232:235], v[176:179], v[104:107]
	v_mfma_f32_16x16x32_bf16 v[96:99], v[208:211], v[184:187], v[96:99]
	v_mfma_f32_16x16x32_bf16 v[88:91], v[232:235], v[184:187], v[88:91]
	v_mfma_f32_16x16x32_bf16 v[80:83], v[208:211], v[192:195], v[80:83]
	v_mfma_f32_16x16x32_bf16 v[72:75], v[232:235], v[192:195], v[72:75]
	v_mfma_f32_16x16x32_bf16 v[68:71], v[208:211], v[200:203], v[68:71]
	v_mfma_f32_16x16x32_bf16 v[64:67], v[232:235], v[200:203], v[64:67]
	s_setprio 0
	s_mov_b32 m0, s49
	s_barrier
	ds_read_b128 v[172:175], v155 offset:49152
	ds_read_b128 v[176:179], v155 offset:50176
	ds_read_b128 v[180:183], v155 offset:51200
	ds_read_b128 v[184:187], v155 offset:52224
	ds_read_b128 v[188:191], v155 offset:53248
	ds_read_b128 v[192:195], v155 offset:54272
	ds_read_b128 v[196:199], v155 offset:55296
	ds_read_b128 v[200:203], v155 offset:56320
	s_add_u32 s100, s14, 0x80
	s_addc_u32 s101, s15, 0
	global_load_lds_dwordx4 v128, s[100:101]
	s_mov_b32 m0, s20
	s_nop 0
	global_load_lds_dwordx4 v130, s[100:101]
	s_barrier
	s_waitcnt lgkmcnt(0)
	s_setprio 1
	s_waitcnt lgkmcnt(0)
	v_mfma_f32_16x16x32_bf16 v[60:63], v[156:159], v[172:175], v[60:63]
	v_mfma_f32_16x16x32_bf16 v[56:59], v[164:167], v[172:175], v[56:59]
	v_mfma_f32_16x16x32_bf16 v[52:55], v[156:159], v[180:183], v[52:55]
	v_mfma_f32_16x16x32_bf16 v[44:47], v[164:167], v[180:183], v[44:47]
	v_mfma_f32_16x16x32_bf16 v[36:39], v[156:159], v[188:191], v[36:39]
	v_mfma_f32_16x16x32_bf16 v[28:31], v[164:167], v[188:191], v[28:31]
	v_mfma_f32_16x16x32_bf16 v[20:23], v[156:159], v[196:199], v[20:23]
	v_mfma_f32_16x16x32_bf16 v[12:15], v[164:167], v[196:199], v[12:15]
	v_mfma_f32_16x16x32_bf16 v[60:63], v[160:163], v[176:179], v[60:63]
	v_mfma_f32_16x16x32_bf16 v[56:59], v[168:171], v[176:179], v[56:59]
	v_mfma_f32_16x16x32_bf16 v[52:55], v[160:163], v[184:187], v[52:55]
	v_mfma_f32_16x16x32_bf16 v[44:47], v[168:171], v[184:187], v[44:47]
	v_mfma_f32_16x16x32_bf16 v[36:39], v[160:163], v[192:195], v[36:39]
	v_mfma_f32_16x16x32_bf16 v[28:31], v[168:171], v[192:195], v[28:31]
	v_mfma_f32_16x16x32_bf16 v[20:23], v[160:163], v[200:203], v[20:23]
	v_mfma_f32_16x16x32_bf16 v[12:15], v[168:171], v[200:203], v[12:15]
	s_setprio 0
	s_barrier
	s_add_u32 s10, s10, 0xb0080
	s_addc_u32 s11, s11, 0
	s_add_i32 s2, s12, s39
	s_mov_b32 m0, s2
	s_nop 0
	global_load_lds_dwordx4 v140, s[10:11]
	s_add_i32 m0, s2, 0x2000
	s_nop 0
	global_load_lds_dwordx4 v132, s[10:11]
	s_waitcnt vmcnt(6)
	s_barrier
	s_setprio 1
	v_mfma_f32_16x16x32_bf16 v[48:51], v[204:207], v[172:175], v[48:51]
	v_mfma_f32_16x16x32_bf16 v[40:43], v[228:231], v[172:175], v[40:43]
	v_mfma_f32_16x16x32_bf16 v[32:35], v[204:207], v[180:183], v[32:35]
	v_mfma_f32_16x16x32_bf16 v[24:27], v[228:231], v[180:183], v[24:27]
	v_mfma_f32_16x16x32_bf16 v[16:19], v[204:207], v[188:191], v[16:19]
	v_mfma_f32_16x16x32_bf16 v[8:11], v[228:231], v[188:191], v[8:11]
	v_mfma_f32_16x16x32_bf16 v[4:7], v[204:207], v[196:199], v[4:7]
	v_mfma_f32_16x16x32_bf16 v[0:3], v[228:231], v[196:199], v[0:3]
	v_mfma_f32_16x16x32_bf16 v[48:51], v[208:211], v[176:179], v[48:51]
	v_mfma_f32_16x16x32_bf16 v[40:43], v[232:235], v[176:179], v[40:43]
	v_mfma_f32_16x16x32_bf16 v[32:35], v[208:211], v[184:187], v[32:35]
	v_mfma_f32_16x16x32_bf16 v[24:27], v[232:235], v[184:187], v[24:27]
	v_mfma_f32_16x16x32_bf16 v[16:19], v[208:211], v[192:195], v[16:19]
	v_mfma_f32_16x16x32_bf16 v[8:11], v[232:235], v[192:195], v[8:11]
	v_mfma_f32_16x16x32_bf16 v[4:7], v[208:211], v[200:203], v[4:7]
	v_mfma_f32_16x16x32_bf16 v[0:3], v[232:235], v[200:203], v[0:3]
	s_setprio 0
	s_add_i32 s65, s65, 2
	s_add_u32 s59, s59, 0x100
	s_addc_u32 s64, s64, 0
	s_cmp_gt_u32 s65, 41
	s_mov_b64 s[12:13], s[0:1]
	s_barrier
	s_cbranch_scc0 .LBB0_275
	s_lshl_b32 s0, s57, 8
	v_mbcnt_lo_u32_b32 v139, -1, 0
	v_mbcnt_hi_u32_b32 v139, -1, v139
	s_lshl_b32 s1, s58, 8
	v_ashrrev_i32_e32 v138, 1, v139
	s_add_i32 s0, s0, s46
	v_and_b32_e32 v138, -8, v138
	s_or_b32 s1, s1, s48
	v_and_or_b32 v156, v139, 15, s0
	v_add_u32_e32 v138, s1, v138
	v_ashrrev_i32_e32 v157, 31, v156
	v_ashrrev_i32_e32 v139, 31, v138
	v_lshlrev_b64 v[158:159], 11, v[156:157]
	v_lshl_add_u64 v[158:159], s[24:25], 0, v[158:159]
	v_lshlrev_b64 v[160:161], 1, v[138:139]
	v_lshl_add_u64 v[138:139], v[158:159], 0, v[160:161]
	v_cvt_pk_bf16_f32 v60, v60, v61
	v_cvt_pk_bf16_f32 v61, v62, v63
	v_cvt_pk_bf16_f32 v62, v56, v57
	v_add_co_u32_e32 v56, vcc, s19, v138
	v_cvt_pk_bf16_f32 v112, v112, v113
	v_cvt_pk_bf16_f32 v113, v114, v115
	v_cvt_pk_bf16_f32 v114, v104, v105
	v_or_b32_e32 v104, 16, v156
	s_nop 0
	v_addc_co_u32_e32 v57, vcc, 0, v139, vcc
	v_cvt_pk_bf16_f32 v48, v48, v49
	v_cvt_pk_bf16_f32 v49, v50, v51
	v_cvt_pk_bf16_f32 v51, v42, v43
	v_cvt_pk_bf16_f32 v42, v44, v45
	v_add_co_u32_e32 v44, vcc, s30, v138
	v_ashrrev_i32_e32 v105, 31, v104
	v_cvt_pk_bf16_f32 v96, v96, v97
	v_cvt_pk_bf16_f32 v97, v98, v99
	v_cvt_pk_bf16_f32 v98, v88, v89
	v_or_b32_e32 v88, 32, v156
	v_addc_co_u32_e32 v45, vcc, 0, v139, vcc
	v_lshlrev_b64 v[104:105], 11, v[104:105]
	v_ashrrev_i32_e32 v89, 31, v88
	v_cvt_pk_bf16_f32 v80, v80, v81
	v_cvt_pk_bf16_f32 v81, v82, v83
	v_cvt_pk_bf16_f32 v82, v72, v73
	v_or_b32_e32 v72, 48, v156
	s_mov_b64 s[0:1], 0x40000
	v_cvt_pk_bf16_f32 v32, v32, v33
	v_cvt_pk_bf16_f32 v33, v34, v35
	v_cvt_pk_bf16_f32 v35, v26, v27
	v_cvt_pk_bf16_f32 v26, v28, v29
	v_add_co_u32_e32 v28, vcc, s31, v138
	v_lshl_add_u64 v[104:105], s[24:25], 0, v[104:105]
	v_lshlrev_b64 v[88:89], 11, v[88:89]
	v_ashrrev_i32_e32 v73, 31, v72
	v_cvt_pk_bf16_f32 v68, v68, v69
	v_cvt_pk_bf16_f32 v69, v70, v71
	v_cvt_pk_bf16_f32 v70, v64, v65
	v_lshl_add_u64 v[64:65], v[138:139], 0, s[0:1]
	s_mov_b64 s[0:1], 0x48000
	v_addc_co_u32_e32 v29, vcc, 0, v139, vcc
	v_cvt_pk_bf16_f32 v115, v106, v107
	flat_store_dwordx4 v[138:139], v[112:115] offset:256
	v_lshl_add_u64 v[88:89], s[24:25], 0, v[88:89]
	v_lshlrev_b64 v[72:73], 11, v[72:73]
	v_lshl_add_u64 v[112:113], v[104:105], 0, v[160:161]
	v_cvt_pk_bf16_f32 v50, v40, v41
	flat_store_dwordx4 v[64:65], v[48:51] offset:256
	v_cvt_pk_bf16_f32 v16, v16, v17
	v_cvt_pk_bf16_f32 v17, v18, v19
	v_cvt_pk_bf16_f32 v19, v10, v11
	v_cvt_pk_bf16_f32 v10, v12, v13
	v_add_co_u32_e32 v12, vcc, s42, v138
	s_nop 0
	v_lshl_add_u64 v[48:49], v[138:139], 0, s[0:1]
	s_mov_b64 s[0:1], 0x50000
	v_cvt_pk_bf16_f32 v99, v90, v91
	flat_store_dwordx4 v[112:113], v[96:99] offset:256
	v_lshl_add_u64 v[72:73], s[24:25], 0, v[72:73]
	v_cvt_pk_bf16_f32 v34, v24, v25
	flat_store_dwordx4 v[48:49], v[32:35] offset:256
	v_lshl_add_u64 v[96:97], v[88:89], 0, v[160:161]
	v_addc_co_u32_e32 v13, vcc, 0, v139, vcc
	v_lshl_add_u64 v[32:33], v[138:139], 0, s[0:1]
	s_mov_b64 s[0:1], 0x58000
	v_cvt_pk_bf16_f32 v83, v74, v75
	flat_store_dwordx4 v[96:97], v[80:83] offset:256
	v_cvt_pk_bf16_f32 v18, v8, v9
	flat_store_dwordx4 v[32:33], v[16:19] offset:256
	s_and_b64 vcc, exec, s[6:7]
	v_lshl_add_u64 v[80:81], v[72:73], 0, v[160:161]
	v_lshl_add_u64 v[16:17], v[138:139], 0, s[0:1]
	s_mov_b32 s58, s52
	s_mov_b32 s57, s51
	s_mov_b64 s[0:1], s[8:9]
	s_mov_b64 s[12:13], s[4:5]
	v_cvt_pk_bf16_f32 v124, v124, v125
	v_cvt_pk_bf16_f32 v125, v126, v127
	v_cvt_pk_bf16_f32 v126, v120, v121
	v_cvt_pk_bf16_f32 v127, v122, v123
	flat_store_dwordx4 v[138:139], v[124:127]
	v_cvt_pk_bf16_f32 v104, v116, v117
	v_cvt_pk_bf16_f32 v105, v118, v119
	v_cvt_pk_bf16_f32 v106, v108, v109
	v_cvt_pk_bf16_f32 v107, v110, v111
	flat_store_dwordx4 v[112:113], v[104:107]
	v_cvt_pk_bf16_f32 v88, v100, v101
	v_cvt_pk_bf16_f32 v89, v102, v103
	v_cvt_pk_bf16_f32 v90, v92, v93
	v_cvt_pk_bf16_f32 v91, v94, v95
	flat_store_dwordx4 v[96:97], v[88:91]
	v_cvt_pk_bf16_f32 v72, v84, v85
	v_cvt_pk_bf16_f32 v73, v86, v87
	v_cvt_pk_bf16_f32 v74, v76, v77
	v_cvt_pk_bf16_f32 v75, v78, v79
	flat_store_dwordx4 v[80:81], v[72:75]
	v_cvt_pk_bf16_f32 v71, v66, v67
	flat_store_dwordx4 v[80:81], v[68:71] offset:256
	v_cvt_pk_bf16_f32 v63, v58, v59
	flat_store_dwordx4 v[56:57], v[60:63]
	v_cvt_pk_bf16_f32 v40, v52, v53
	v_cvt_pk_bf16_f32 v41, v54, v55
	v_cvt_pk_bf16_f32 v43, v46, v47
	flat_store_dwordx4 v[44:45], v[40:43]
	v_cvt_pk_bf16_f32 v24, v36, v37
	v_cvt_pk_bf16_f32 v25, v38, v39
	v_cvt_pk_bf16_f32 v27, v30, v31
	flat_store_dwordx4 v[28:29], v[24:27]
	v_cvt_pk_bf16_f32 v8, v20, v21
	v_cvt_pk_bf16_f32 v9, v22, v23
	v_cvt_pk_bf16_f32 v11, v14, v15
	flat_store_dwordx4 v[12:13], v[8:11]
	v_cvt_pk_bf16_f32 v4, v4, v5
	v_cvt_pk_bf16_f32 v5, v6, v7
	v_cvt_pk_bf16_f32 v6, v0, v1
	v_cvt_pk_bf16_f32 v7, v2, v3
	flat_store_dwordx4 v[16:17], v[4:7] offset:256
	s_cbranch_vccz .LBB0_264
	s_waitcnt vmcnt(0)
	s_cmpk_gt_u32 s17, 0xff
	s_cbranch_scc1 .LBB0_279
	s_barrier

.LBB0_289:
	s_add_u32 s0, s16, 0xfffc0080
	s_addc_u32 s1, s17, -1
	s_add_i32 s2, 0, 0x10000
	v_add_u32_e32 v138, s2, v154
	ds_read_b128 v[156:159], v138
	ds_read_b128 v[160:163], v138 offset:1024
	ds_read_b128 v[164:167], v138 offset:2048
	ds_read_b128 v[168:171], v138 offset:3072
	s_cmp_eq_u32 s21, 12
	s_cselect_b32 s37, s11, s1
	s_cselect_b32 s36, s10, s0
	s_cselect_b32 s1, s13, s9
	s_cselect_b32 s0, s12, s5
	s_add_i32 m0, s15, 0xc000
	ds_read_b128 v[172:175], v155
	ds_read_b128 v[176:179], v155 offset:1024
	ds_read_b128 v[180:183], v155 offset:2048
	ds_read_b128 v[184:187], v155 offset:3072
	ds_read_b128 v[188:191], v155 offset:4096
	ds_read_b128 v[192:195], v155 offset:5120
	ds_read_b128 v[196:199], v155 offset:6144
	ds_read_b128 v[200:203], v155 offset:7168
	global_load_lds_dwordx4 v136, s[16:17]
	s_add_i32 m0, s15, 0xe000
	s_nop 0
	global_load_lds_dwordx4 v134, s[16:17]
	s_waitcnt lgkmcnt(8)
	s_barrier
	s_waitcnt lgkmcnt(0)
	s_setprio 1
	s_waitcnt lgkmcnt(0)
	v_mfma_f32_16x16x32_bf16 v[124:127], v[156:159], v[172:175], v[124:127]
	v_mfma_f32_16x16x32_bf16 v[120:123], v[164:167], v[172:175], v[120:123]
	v_mfma_f32_16x16x32_bf16 v[108:111], v[156:159], v[180:183], v[108:111]
	v_mfma_f32_16x16x32_bf16 v[104:107], v[164:167], v[180:183], v[104:107]
	v_mfma_f32_16x16x32_bf16 v[92:95], v[156:159], v[188:191], v[92:95]
	v_mfma_f32_16x16x32_bf16 v[88:91], v[164:167], v[188:191], v[88:91]
	v_mfma_f32_16x16x32_bf16 v[76:79], v[156:159], v[196:199], v[76:79]
	v_mfma_f32_16x16x32_bf16 v[72:75], v[164:167], v[196:199], v[72:75]
	v_mfma_f32_16x16x32_bf16 v[124:127], v[160:163], v[176:179], v[124:127]
	v_mfma_f32_16x16x32_bf16 v[120:123], v[168:171], v[176:179], v[120:123]
	v_mfma_f32_16x16x32_bf16 v[108:111], v[160:163], v[184:187], v[108:111]
	v_mfma_f32_16x16x32_bf16 v[104:107], v[168:171], v[184:187], v[104:107]
	v_mfma_f32_16x16x32_bf16 v[92:95], v[160:163], v[192:195], v[92:95]
	v_mfma_f32_16x16x32_bf16 v[88:91], v[168:171], v[192:195], v[88:91]
	v_mfma_f32_16x16x32_bf16 v[76:79], v[160:163], v[200:203], v[76:79]
	v_mfma_f32_16x16x32_bf16 v[72:75], v[168:171], v[200:203], v[72:75]
	s_setprio 0
	s_barrier
	s_add_i32 s30, 0, 0x14000
	v_add_u32_e32 v138, s30, v154
	s_add_i32 s2, s2, s44
	ds_read_b128 v[204:207], v138
	ds_read_b128 v[208:211], v138 offset:1024
	ds_read_b128 v[228:231], v138 offset:2048
	ds_read_b128 v[232:235], v138 offset:3072
	s_mov_b32 m0, s2
	s_nop 0
	global_load_lds_dwordx4 v140, s[0:1]
	s_add_i32 m0, s2, 0x2000
	s_nop 0
	global_load_lds_dwordx4 v128, s[0:1]
	s_barrier
	s_waitcnt lgkmcnt(0)
	s_setprio 1
	s_waitcnt lgkmcnt(0)
	v_mfma_f32_16x16x32_bf16 v[116:119], v[204:207], v[172:175], v[116:119]
	v_mfma_f32_16x16x32_bf16 v[112:115], v[228:231], v[172:175], v[112:115]
	v_mfma_f32_16x16x32_bf16 v[100:103], v[204:207], v[180:183], v[100:103]
	v_mfma_f32_16x16x32_bf16 v[96:99], v[228:231], v[180:183], v[96:99]
	v_mfma_f32_16x16x32_bf16 v[84:87], v[204:207], v[188:191], v[84:87]
	v_mfma_f32_16x16x32_bf16 v[80:83], v[228:231], v[188:191], v[80:83]
	v_mfma_f32_16x16x32_bf16 v[68:71], v[204:207], v[196:199], v[68:71]
	v_mfma_f32_16x16x32_bf16 v[64:67], v[228:231], v[196:199], v[64:67]
	v_mfma_f32_16x16x32_bf16 v[116:119], v[208:211], v[176:179], v[116:119]
	v_mfma_f32_16x16x32_bf16 v[112:115], v[232:235], v[176:179], v[112:115]
	v_mfma_f32_16x16x32_bf16 v[100:103], v[208:211], v[184:187], v[100:103]
	v_mfma_f32_16x16x32_bf16 v[96:99], v[232:235], v[184:187], v[96:99]
	v_mfma_f32_16x16x32_bf16 v[84:87], v[208:211], v[192:195], v[84:87]
	v_mfma_f32_16x16x32_bf16 v[80:83], v[232:235], v[192:195], v[80:83]
	v_mfma_f32_16x16x32_bf16 v[68:71], v[208:211], v[200:203], v[68:71]
	v_mfma_f32_16x16x32_bf16 v[64:67], v[232:235], v[200:203], v[64:67]
	s_setprio 0
	s_mov_b32 m0, s15
	s_barrier
	ds_read_b128 v[172:175], v155 offset:16384
	ds_read_b128 v[176:179], v155 offset:17408
	ds_read_b128 v[180:183], v155 offset:18432
	ds_read_b128 v[184:187], v155 offset:19456
	ds_read_b128 v[188:191], v155 offset:20480
	ds_read_b128 v[192:195], v155 offset:21504
	ds_read_b128 v[196:199], v155 offset:22528
	ds_read_b128 v[200:203], v155 offset:23552
	global_load_lds_dwordx4 v132, s[36:37]
	s_mov_b32 m0, s45
	s_nop 0
	global_load_lds_dwordx4 v130, s[36:37]
	s_barrier
	s_waitcnt lgkmcnt(0)
	s_setprio 1
	s_waitcnt lgkmcnt(0)
	v_mfma_f32_16x16x32_bf16 v[60:63], v[156:159], v[172:175], v[60:63]
	v_mfma_f32_16x16x32_bf16 v[56:59], v[164:167], v[172:175], v[56:59]
	v_mfma_f32_16x16x32_bf16 v[44:47], v[156:159], v[180:183], v[44:47]
	v_mfma_f32_16x16x32_bf16 v[40:43], v[164:167], v[180:183], v[40:43]
	v_mfma_f32_16x16x32_bf16 v[28:31], v[156:159], v[188:191], v[28:31]
	v_mfma_f32_16x16x32_bf16 v[24:27], v[164:167], v[188:191], v[24:27]
	v_mfma_f32_16x16x32_bf16 v[12:15], v[156:159], v[196:199], v[12:15]
	v_mfma_f32_16x16x32_bf16 v[8:11], v[164:167], v[196:199], v[8:11]
	v_mfma_f32_16x16x32_bf16 v[60:63], v[160:163], v[176:179], v[60:63]
	v_mfma_f32_16x16x32_bf16 v[56:59], v[168:171], v[176:179], v[56:59]
	v_mfma_f32_16x16x32_bf16 v[44:47], v[160:163], v[184:187], v[44:47]
	v_mfma_f32_16x16x32_bf16 v[40:43], v[168:171], v[184:187], v[40:43]
	v_mfma_f32_16x16x32_bf16 v[28:31], v[160:163], v[192:195], v[28:31]
	v_mfma_f32_16x16x32_bf16 v[24:27], v[168:171], v[192:195], v[24:27]
	v_mfma_f32_16x16x32_bf16 v[12:15], v[160:163], v[200:203], v[12:15]
	v_mfma_f32_16x16x32_bf16 v[8:11], v[168:171], v[200:203], v[8:11]
	s_setprio 0
	s_barrier
	s_add_u32 s18, s0, 0x40000
	s_addc_u32 s19, s1, 0
	s_add_i32 s2, s30, s44
	s_mov_b32 m0, s2
	s_nop 0
	global_load_lds_dwordx4 v140, s[18:19]
	s_add_i32 m0, s2, 0x2000
	s_nop 0
	global_load_lds_dwordx4 v128, s[18:19]
	s_waitcnt vmcnt(6)
	s_barrier
	s_setprio 1
	v_mfma_f32_16x16x32_bf16 v[52:55], v[204:207], v[172:175], v[52:55]
	v_mfma_f32_16x16x32_bf16 v[48:51], v[228:231], v[172:175], v[48:51]
	v_mfma_f32_16x16x32_bf16 v[36:39], v[204:207], v[180:183], v[36:39]
	v_mfma_f32_16x16x32_bf16 v[32:35], v[228:231], v[180:183], v[32:35]
	v_mfma_f32_16x16x32_bf16 v[20:23], v[204:207], v[188:191], v[20:23]
	v_mfma_f32_16x16x32_bf16 v[16:19], v[228:231], v[188:191], v[16:19]
	v_mfma_f32_16x16x32_bf16 v[4:7], v[204:207], v[196:199], v[4:7]
	v_mfma_f32_16x16x32_bf16 v[0:3], v[228:231], v[196:199], v[0:3]
	v_mfma_f32_16x16x32_bf16 v[52:55], v[208:211], v[176:179], v[52:55]
	v_mfma_f32_16x16x32_bf16 v[48:51], v[232:235], v[176:179], v[48:51]
	v_mfma_f32_16x16x32_bf16 v[36:39], v[208:211], v[184:187], v[36:39]
	v_mfma_f32_16x16x32_bf16 v[32:35], v[232:235], v[184:187], v[32:35]
	v_mfma_f32_16x16x32_bf16 v[20:23], v[208:211], v[192:195], v[20:23]
	v_mfma_f32_16x16x32_bf16 v[16:19], v[232:235], v[192:195], v[16:19]
	v_mfma_f32_16x16x32_bf16 v[4:7], v[208:211], v[200:203], v[4:7]
	v_mfma_f32_16x16x32_bf16 v[0:3], v[232:235], v[200:203], v[0:3]
	s_setprio 0
	s_add_i32 s2, 0, 0x18000
	v_add_u32_e32 v168, s2, v154
	s_barrier
	ds_read_b128 v[156:159], v168
	ds_read_b128 v[160:163], v168 offset:1024
	ds_read_b128 v[164:167], v168 offset:2048
	ds_read_b128 v[168:171], v168 offset:3072
	s_add_u32 s18, s36, 0x40000
	s_addc_u32 s19, s37, 0
	s_mov_b32 m0, s46
	ds_read_b128 v[172:175], v155 offset:32768
	ds_read_b128 v[176:179], v155 offset:33792
	ds_read_b128 v[180:183], v155 offset:34816
	ds_read_b128 v[184:187], v155 offset:35840
	ds_read_b128 v[188:191], v155 offset:36864
	ds_read_b128 v[192:195], v155 offset:37888
	ds_read_b128 v[196:199], v155 offset:38912
	ds_read_b128 v[200:203], v155 offset:39936
	global_load_lds_dwordx4 v132, s[18:19]
	s_mov_b32 m0, s48
	s_nop 0
	global_load_lds_dwordx4 v130, s[18:19]
	s_waitcnt lgkmcnt(8)
	s_barrier
	s_waitcnt lgkmcnt(0)
	s_setprio 1
	s_waitcnt lgkmcnt(0)
	v_mfma_f32_16x16x32_bf16 v[124:127], v[156:159], v[172:175], v[124:127]
	v_mfma_f32_16x16x32_bf16 v[120:123], v[164:167], v[172:175], v[120:123]
	v_mfma_f32_16x16x32_bf16 v[108:111], v[156:159], v[180:183], v[108:111]
	v_mfma_f32_16x16x32_bf16 v[104:107], v[164:167], v[180:183], v[104:107]
	v_mfma_f32_16x16x32_bf16 v[92:95], v[156:159], v[188:191], v[92:95]
	v_mfma_f32_16x16x32_bf16 v[88:91], v[164:167], v[188:191], v[88:91]
	v_mfma_f32_16x16x32_bf16 v[76:79], v[156:159], v[196:199], v[76:79]
	v_mfma_f32_16x16x32_bf16 v[72:75], v[164:167], v[196:199], v[72:75]
	v_mfma_f32_16x16x32_bf16 v[124:127], v[160:163], v[176:179], v[124:127]
	v_mfma_f32_16x16x32_bf16 v[120:123], v[168:171], v[176:179], v[120:123]
	v_mfma_f32_16x16x32_bf16 v[108:111], v[160:163], v[184:187], v[108:111]
	v_mfma_f32_16x16x32_bf16 v[104:107], v[168:171], v[184:187], v[104:107]
	v_mfma_f32_16x16x32_bf16 v[92:95], v[160:163], v[192:195], v[92:95]
	v_mfma_f32_16x16x32_bf16 v[88:91], v[168:171], v[192:195], v[88:91]
	v_mfma_f32_16x16x32_bf16 v[76:79], v[160:163], v[200:203], v[76:79]
	v_mfma_f32_16x16x32_bf16 v[72:75], v[168:171], v[200:203], v[72:75]
	s_setprio 0
	s_barrier
	s_add_i32 s18, 0, 0x1c000
	s_add_i32 s2, s2, s44
	v_add_u32_e32 v232, s18, v154
	s_mov_b32 m0, s2
	ds_read_b128 v[204:207], v232
	ds_read_b128 v[208:211], v232 offset:1024
	ds_read_b128 v[228:231], v232 offset:2048
	ds_read_b128 v[232:235], v232 offset:3072
	s_add_u32 s100, s0, 0x80
	s_addc_u32 s101, s1, 0
	global_load_lds_dwordx4 v140, s[100:101]
	s_add_i32 m0, s2, 0x2000
	s_nop 0
	global_load_lds_dwordx4 v128, s[100:101]
	s_barrier
	s_waitcnt lgkmcnt(0)
	s_setprio 1
	s_waitcnt lgkmcnt(0)
	v_mfma_f32_16x16x32_bf16 v[116:119], v[204:207], v[172:175], v[116:119]
	v_mfma_f32_16x16x32_bf16 v[112:115], v[228:231], v[172:175], v[112:115]
	v_mfma_f32_16x16x32_bf16 v[100:103], v[204:207], v[180:183], v[100:103]
	v_mfma_f32_16x16x32_bf16 v[96:99], v[228:231], v[180:183], v[96:99]
	v_mfma_f32_16x16x32_bf16 v[84:87], v[204:207], v[188:191], v[84:87]
	v_mfma_f32_16x16x32_bf16 v[80:83], v[228:231], v[188:191], v[80:83]
	v_mfma_f32_16x16x32_bf16 v[68:71], v[204:207], v[196:199], v[68:71]
	v_mfma_f32_16x16x32_bf16 v[64:67], v[228:231], v[196:199], v[64:67]
	v_mfma_f32_16x16x32_bf16 v[116:119], v[208:211], v[176:179], v[116:119]
	v_mfma_f32_16x16x32_bf16 v[112:115], v[232:235], v[176:179], v[112:115]
	v_mfma_f32_16x16x32_bf16 v[100:103], v[208:211], v[184:187], v[100:103]
	v_mfma_f32_16x16x32_bf16 v[96:99], v[232:235], v[184:187], v[96:99]
	v_mfma_f32_16x16x32_bf16 v[84:87], v[208:211], v[192:195], v[84:87]
	v_mfma_f32_16x16x32_bf16 v[80:83], v[232:235], v[192:195], v[80:83]
	v_mfma_f32_16x16x32_bf16 v[68:71], v[208:211], v[200:203], v[68:71]
	v_mfma_f32_16x16x32_bf16 v[64:67], v[232:235], v[200:203], v[64:67]
	s_setprio 0
	s_mov_b32 m0, s57
	s_barrier
	ds_read_b128 v[172:175], v155 offset:49152
	ds_read_b128 v[176:179], v155 offset:50176
	ds_read_b128 v[180:183], v155 offset:51200
	ds_read_b128 v[184:187], v155 offset:52224
	ds_read_b128 v[188:191], v155 offset:53248
	ds_read_b128 v[192:195], v155 offset:54272
	ds_read_b128 v[196:199], v155 offset:55296
	ds_read_b128 v[200:203], v155 offset:56320
	s_add_u32 s100, s36, 0x80
	s_addc_u32 s101, s37, 0
	global_load_lds_dwordx4 v132, s[100:101]
	s_mov_b32 m0, s58
	s_nop 0
	global_load_lds_dwordx4 v130, s[100:101]
	s_barrier
	s_waitcnt lgkmcnt(0)
	s_setprio 1
	s_waitcnt lgkmcnt(0)
	v_mfma_f32_16x16x32_bf16 v[60:63], v[156:159], v[172:175], v[60:63]
	v_mfma_f32_16x16x32_bf16 v[56:59], v[164:167], v[172:175], v[56:59]
	v_mfma_f32_16x16x32_bf16 v[44:47], v[156:159], v[180:183], v[44:47]
	v_mfma_f32_16x16x32_bf16 v[40:43], v[164:167], v[180:183], v[40:43]
	v_mfma_f32_16x16x32_bf16 v[28:31], v[156:159], v[188:191], v[28:31]
	v_mfma_f32_16x16x32_bf16 v[24:27], v[164:167], v[188:191], v[24:27]
	v_mfma_f32_16x16x32_bf16 v[12:15], v[156:159], v[196:199], v[12:15]
	v_mfma_f32_16x16x32_bf16 v[8:11], v[164:167], v[196:199], v[8:11]
	v_mfma_f32_16x16x32_bf16 v[60:63], v[160:163], v[176:179], v[60:63]
	v_mfma_f32_16x16x32_bf16 v[56:59], v[168:171], v[176:179], v[56:59]
	v_mfma_f32_16x16x32_bf16 v[44:47], v[160:163], v[184:187], v[44:47]
	v_mfma_f32_16x16x32_bf16 v[40:43], v[168:171], v[184:187], v[40:43]
	v_mfma_f32_16x16x32_bf16 v[28:31], v[160:163], v[192:195], v[28:31]
	v_mfma_f32_16x16x32_bf16 v[24:27], v[168:171], v[192:195], v[24:27]
	v_mfma_f32_16x16x32_bf16 v[12:15], v[160:163], v[200:203], v[12:15]
	v_mfma_f32_16x16x32_bf16 v[8:11], v[168:171], v[200:203], v[8:11]
	s_setprio 0
	s_barrier
	s_add_u32 s0, s0, 0x40080
	s_addc_u32 s1, s1, 0
	s_add_i32 s2, s18, s44
	s_mov_b32 m0, s2
	s_nop 0
	global_load_lds_dwordx4 v140, s[0:1]
	s_add_i32 m0, s2, 0x2000
	s_nop 0
	global_load_lds_dwordx4 v128, s[0:1]
	s_waitcnt vmcnt(6)
	s_barrier
	s_setprio 1
	v_mfma_f32_16x16x32_bf16 v[52:55], v[204:207], v[172:175], v[52:55]
	v_mfma_f32_16x16x32_bf16 v[48:51], v[228:231], v[172:175], v[48:51]
	v_mfma_f32_16x16x32_bf16 v[36:39], v[204:207], v[180:183], v[36:39]
	v_mfma_f32_16x16x32_bf16 v[32:35], v[228:231], v[180:183], v[32:35]
	v_mfma_f32_16x16x32_bf16 v[20:23], v[204:207], v[188:191], v[20:23]
	v_mfma_f32_16x16x32_bf16 v[16:19], v[228:231], v[188:191], v[16:19]
	v_mfma_f32_16x16x32_bf16 v[4:7], v[204:207], v[196:199], v[4:7]
	v_mfma_f32_16x16x32_bf16 v[0:3], v[228:231], v[196:199], v[0:3]
	v_mfma_f32_16x16x32_bf16 v[52:55], v[208:211], v[176:179], v[52:55]
	v_mfma_f32_16x16x32_bf16 v[48:51], v[232:235], v[176:179], v[48:51]
	v_mfma_f32_16x16x32_bf16 v[36:39], v[208:211], v[184:187], v[36:39]
	v_mfma_f32_16x16x32_bf16 v[32:35], v[232:235], v[184:187], v[32:35]
	v_mfma_f32_16x16x32_bf16 v[20:23], v[208:211], v[192:195], v[20:23]
	v_mfma_f32_16x16x32_bf16 v[16:19], v[232:235], v[192:195], v[16:19]
	v_mfma_f32_16x16x32_bf16 v[4:7], v[208:211], v[200:203], v[4:7]
	v_mfma_f32_16x16x32_bf16 v[0:3], v[232:235], v[200:203], v[0:3]
	s_setprio 0
	s_add_i32 s21, s21, 2
	s_add_u32 s5, s5, 0x100
	s_addc_u32 s9, s9, 0
	s_add_u32 s16, s16, 0x100
	s_addc_u32 s17, s17, 0
	s_cmp_gt_u32 s21, 13
	s_barrier
	s_cbranch_scc0 .LBB0_289
	v_mul_f32_e32 v161, 0xbfb8aa3b, v124
	v_exp_f32_e32 v161, v161
	v_mul_f32_e32 v162, 0xbfb8aa3b, v125
	v_exp_f32_e32 v162, v162
	v_mul_f32_e32 v163, 0xbfb8aa3b, v126
	v_exp_f32_e32 v163, v163
	v_mul_f32_e32 v164, 0xbfb8aa3b, v127
	v_exp_f32_e32 v164, v164
	v_mul_f32_e32 v165, 0xbfb8aa3b, v120
	v_exp_f32_e32 v165, v165
	v_mul_f32_e32 v166, 0xbfb8aa3b, v121
	v_add_f32_e32 v161, 1.0, v161
	v_exp_f32_e32 v166, v166
	v_mul_f32_e32 v167, 0xbfb8aa3b, v122
	v_rcp_f32_e32 v161, v161
	v_add_f32_e32 v162, 1.0, v162
	v_exp_f32_e32 v167, v167
	v_mul_f32_e32 v168, 0xbfb8aa3b, v123
	v_rcp_f32_e32 v162, v162
	v_add_f32_e32 v163, 1.0, v163
	v_exp_f32_e32 v168, v168
	v_rcp_f32_e32 v163, v163
	v_add_f32_e32 v164, 1.0, v164
	v_rcp_f32_e32 v164, v164
	v_add_f32_e32 v165, 1.0, v165
	v_rcp_f32_e32 v165, v165
	v_add_f32_e32 v166, 1.0, v166
	v_mul_f32_e32 v124, v124, v161
	v_rcp_f32_e32 v166, v166
	v_add_f32_e32 v167, 1.0, v167
	v_mul_f32_e32 v116, v124, v116
	v_mul_f32_e32 v124, v125, v162
	s_lshl_b32 s0, s14, 8
	v_rcp_f32_e32 v167, v167
	v_add_f32_e32 v168, 1.0, v168
	v_mul_f32_e32 v117, v124, v117
	v_mul_f32_e32 v124, v126, v163
	v_mbcnt_lo_u32_b32 v138, -1, 0
	v_mbcnt_hi_u32_b32 v138, -1, v138
	s_add_i32 s0, s0, s51
	v_rcp_f32_e32 v168, v168
	v_mul_f32_e32 v124, v124, v118
	v_mul_f32_e32 v118, v127, v164
	v_and_or_b32 v160, v138, 15, s0
	s_lshl_b32 s0, s20, 7
	v_ashrrev_i32_e32 v138, 1, v138
	v_mul_f32_e32 v125, v118, v119
	v_mul_f32_e32 v118, v120, v165
	s_or_b32 s0, s0, s52
	v_and_b32_e32 v138, -8, v138
	v_mul_f32_e32 v120, v118, v112
	v_mul_f32_e32 v112, v121, v166
	v_add_u32_e32 v156, s0, v138
	v_mul_f32_e32 v121, v112, v113
	v_mul_f32_e32 v112, v122, v167
	v_ashrrev_i32_e32 v157, 31, v156
	v_mov_b64_e32 v[138:139], s[34:35]
	v_mul_f32_e32 v122, v112, v114
	v_mul_f32_e32 v112, v123, v168
	v_mad_i64_i32 v[158:159], s[0:1], v160, s33, v[138:139]
	v_mul_f32_e32 v123, v112, v115
	v_lshlrev_b64 v[112:113], 1, v[156:157]
	v_lshl_add_u64 v[118:119], v[158:159], 0, v[112:113]
	v_cvt_pk_bf16_f32 v114, v116, v117
	v_cvt_pk_bf16_f32 v116, v120, v121
	v_cvt_pk_bf16_f32 v115, v124, v125
	v_cvt_pk_bf16_f32 v117, v122, v123
	flat_store_dwordx4 v[118:119], v[114:117]
	v_mul_f32_e32 v118, 0xbfb8aa3b, v110
	v_exp_f32_e32 v118, v118
	v_mul_f32_e32 v116, 0xbfb8aa3b, v108
	v_exp_f32_e32 v116, v116
	v_mul_f32_e32 v117, 0xbfb8aa3b, v109
	v_exp_f32_e32 v117, v117
	v_mul_f32_e32 v119, 0xbfb8aa3b, v111
	v_exp_f32_e32 v119, v119
	v_mul_f32_e32 v120, 0xbfb8aa3b, v104
	v_exp_f32_e32 v120, v120
	v_mul_f32_e32 v121, 0xbfb8aa3b, v105
	v_add_f32_e32 v116, 1.0, v116
	v_exp_f32_e32 v121, v121
	v_mul_f32_e32 v122, 0xbfb8aa3b, v106
	v_rcp_f32_e32 v116, v116
	v_add_f32_e32 v117, 1.0, v117
	v_exp_f32_e32 v122, v122
	v_mul_f32_e32 v123, 0xbfb8aa3b, v107
	v_rcp_f32_e32 v117, v117
	v_add_f32_e32 v118, 1.0, v118
	v_exp_f32_e32 v123, v123
	v_rcp_f32_e32 v118, v118
	v_add_f32_e32 v119, 1.0, v119
	v_rcp_f32_e32 v119, v119
	v_add_f32_e32 v120, 1.0, v120
	v_rcp_f32_e32 v120, v120
	v_add_f32_e32 v121, 1.0, v121
	v_mul_f32_e32 v108, v108, v116
	v_rcp_f32_e32 v121, v121
	v_add_f32_e32 v122, 1.0, v122
	v_mul_f32_e32 v108, v108, v100
	v_mul_f32_e32 v100, v109, v117
	v_rcp_f32_e32 v122, v122
	v_add_f32_e32 v123, 1.0, v123
	v_mul_f32_e32 v109, v100, v101
	v_mul_f32_e32 v100, v110, v118
	v_rcp_f32_e32 v123, v123
	v_mul_f32_e32 v102, v100, v102
	v_mul_f32_e32 v100, v111, v119
	v_mul_f32_e32 v103, v100, v103
	v_mul_f32_e32 v100, v104, v120
	v_mul_f32_e32 v104, v100, v96
	v_mul_f32_e32 v96, v105, v121
	v_or_b32_e32 v114, 16, v160
	v_mul_f32_e32 v105, v96, v97
	v_mul_f32_e32 v96, v106, v122
	v_mad_i64_i32 v[114:115], s[0:1], v114, s33, v[138:139]
	v_mul_f32_e32 v106, v96, v98
	v_mul_f32_e32 v96, v107, v123
	v_mul_f32_e32 v99, v96, v99
	v_lshl_add_u64 v[100:101], v[114:115], 0, v[112:113]
	v_cvt_pk_bf16_f32 v98, v104, v105
	v_cvt_pk_bf16_f32 v96, v108, v109
	v_cvt_pk_bf16_f32 v97, v102, v103
	v_cvt_pk_bf16_f32 v99, v106, v99
	flat_store_dwordx4 v[100:101], v[96:99]
	v_mul_f32_e32 v100, 0xbfb8aa3b, v94
	v_exp_f32_e32 v100, v100
	v_mul_f32_e32 v98, 0xbfb8aa3b, v92
	v_exp_f32_e32 v98, v98
	v_mul_f32_e32 v99, 0xbfb8aa3b, v93
	v_exp_f32_e32 v99, v99
	v_mul_f32_e32 v101, 0xbfb8aa3b, v95
	v_exp_f32_e32 v101, v101
	v_mul_f32_e32 v102, 0xbfb8aa3b, v88
	v_exp_f32_e32 v102, v102
	v_mul_f32_e32 v103, 0xbfb8aa3b, v89
	v_add_f32_e32 v98, 1.0, v98
	v_exp_f32_e32 v103, v103
	v_mul_f32_e32 v104, 0xbfb8aa3b, v90
	v_rcp_f32_e32 v98, v98
	v_add_f32_e32 v99, 1.0, v99
	v_exp_f32_e32 v104, v104
	v_mul_f32_e32 v105, 0xbfb8aa3b, v91
	v_rcp_f32_e32 v99, v99
	v_add_f32_e32 v100, 1.0, v100
	v_exp_f32_e32 v105, v105
	v_rcp_f32_e32 v100, v100
	v_add_f32_e32 v101, 1.0, v101
	v_rcp_f32_e32 v101, v101
	v_add_f32_e32 v102, 1.0, v102
	v_rcp_f32_e32 v102, v102
	v_add_f32_e32 v103, 1.0, v103
	v_mul_f32_e32 v92, v92, v98
	v_rcp_f32_e32 v103, v103
	v_add_f32_e32 v104, 1.0, v104
	v_mul_f32_e32 v92, v92, v84
	v_mul_f32_e32 v84, v93, v99
	v_rcp_f32_e32 v104, v104
	v_add_f32_e32 v105, 1.0, v105
	v_mul_f32_e32 v93, v84, v85
	v_mul_f32_e32 v84, v94, v100
	v_rcp_f32_e32 v105, v105
	v_mul_f32_e32 v86, v84, v86
	v_mul_f32_e32 v84, v95, v101
	v_mul_f32_e32 v87, v84, v87
	v_mul_f32_e32 v84, v88, v102
	v_mul_f32_e32 v88, v84, v80
	v_mul_f32_e32 v80, v89, v103
	v_or_b32_e32 v96, 32, v160
	v_mul_f32_e32 v89, v80, v81
	v_mul_f32_e32 v80, v90, v104
	v_mad_i64_i32 v[96:97], s[0:1], v96, s33, v[138:139]
	v_mul_f32_e32 v90, v80, v82
	v_mul_f32_e32 v80, v91, v105
	v_mul_f32_e32 v83, v80, v83
	v_lshl_add_u64 v[84:85], v[96:97], 0, v[112:113]
	v_cvt_pk_bf16_f32 v82, v88, v89
	v_cvt_pk_bf16_f32 v80, v92, v93
	v_cvt_pk_bf16_f32 v81, v86, v87
	v_cvt_pk_bf16_f32 v83, v90, v83
	flat_store_dwordx4 v[84:85], v[80:83]
	v_mul_f32_e32 v84, 0xbfb8aa3b, v78
	v_exp_f32_e32 v84, v84
	v_mul_f32_e32 v82, 0xbfb8aa3b, v76
	v_exp_f32_e32 v82, v82
	v_mul_f32_e32 v83, 0xbfb8aa3b, v77
	v_exp_f32_e32 v83, v83
	v_mul_f32_e32 v85, 0xbfb8aa3b, v79
	v_exp_f32_e32 v85, v85
	v_mul_f32_e32 v86, 0xbfb8aa3b, v72
	v_exp_f32_e32 v86, v86
	v_mul_f32_e32 v87, 0xbfb8aa3b, v73
	v_add_f32_e32 v82, 1.0, v82
	v_exp_f32_e32 v87, v87
	v_mul_f32_e32 v88, 0xbfb8aa3b, v74
	v_rcp_f32_e32 v82, v82
	v_add_f32_e32 v83, 1.0, v83
	v_exp_f32_e32 v88, v88
	v_mul_f32_e32 v89, 0xbfb8aa3b, v75
	v_rcp_f32_e32 v83, v83
	v_add_f32_e32 v84, 1.0, v84
	v_exp_f32_e32 v89, v89
	v_rcp_f32_e32 v84, v84
	v_add_f32_e32 v85, 1.0, v85
	v_rcp_f32_e32 v85, v85
	v_add_f32_e32 v86, 1.0, v86
	v_rcp_f32_e32 v86, v86
	v_add_f32_e32 v87, 1.0, v87
	v_mul_f32_e32 v76, v76, v82
	v_rcp_f32_e32 v87, v87
	v_add_f32_e32 v88, 1.0, v88
	v_mul_f32_e32 v76, v76, v68
	v_mul_f32_e32 v68, v77, v83
	v_rcp_f32_e32 v88, v88
	v_add_f32_e32 v89, 1.0, v89
	v_mul_f32_e32 v77, v68, v69
	v_mul_f32_e32 v68, v78, v84
	v_rcp_f32_e32 v89, v89
	v_mul_f32_e32 v70, v68, v70
	v_mul_f32_e32 v68, v79, v85
	v_mul_f32_e32 v71, v68, v71
	v_mul_f32_e32 v68, v72, v86
	v_mul_f32_e32 v72, v68, v64
	v_mul_f32_e32 v64, v73, v87
	v_or_b32_e32 v80, 48, v160
	v_mul_f32_e32 v73, v64, v65
	v_mul_f32_e32 v64, v74, v88
	v_mad_i64_i32 v[80:81], s[0:1], v80, s33, v[138:139]
	v_mul_f32_e32 v74, v64, v66
	v_mul_f32_e32 v64, v75, v89
	v_mul_f32_e32 v67, v64, v67
	v_lshl_add_u64 v[68:69], v[80:81], 0, v[112:113]
	v_cvt_pk_bf16_f32 v66, v72, v73
	v_cvt_pk_bf16_f32 v64, v76, v77
	v_cvt_pk_bf16_f32 v65, v70, v71
	v_cvt_pk_bf16_f32 v67, v74, v67
	flat_store_dwordx4 v[68:69], v[64:67]
	v_mul_f32_e32 v68, 0xbfb8aa3b, v62
	v_exp_f32_e32 v68, v68
	v_mul_f32_e32 v66, 0xbfb8aa3b, v60
	v_exp_f32_e32 v66, v66
	v_mul_f32_e32 v67, 0xbfb8aa3b, v61
	v_exp_f32_e32 v67, v67
	v_mul_f32_e32 v69, 0xbfb8aa3b, v63
	v_exp_f32_e32 v69, v69
	v_mul_f32_e32 v70, 0xbfb8aa3b, v56
	v_exp_f32_e32 v70, v70
	v_mul_f32_e32 v71, 0xbfb8aa3b, v57
	v_add_f32_e32 v66, 1.0, v66
	v_exp_f32_e32 v71, v71
	v_mul_f32_e32 v72, 0xbfb8aa3b, v58
	v_rcp_f32_e32 v66, v66
	v_add_f32_e32 v67, 1.0, v67
	v_exp_f32_e32 v72, v72
	v_mul_f32_e32 v73, 0xbfb8aa3b, v59
	v_rcp_f32_e32 v67, v67
	v_add_f32_e32 v68, 1.0, v68
	v_exp_f32_e32 v73, v73
	v_rcp_f32_e32 v68, v68
	v_add_f32_e32 v69, 1.0, v69
	v_rcp_f32_e32 v69, v69
	v_add_f32_e32 v70, 1.0, v70
	v_rcp_f32_e32 v70, v70
	v_add_f32_e32 v71, 1.0, v71
	v_mul_f32_e32 v60, v60, v66
	v_rcp_f32_e32 v71, v71
	v_add_f32_e32 v72, 1.0, v72
	v_mul_f32_e32 v60, v60, v52
	v_mul_f32_e32 v52, v61, v67
	v_rcp_f32_e32 v72, v72
	v_add_f32_e32 v73, 1.0, v73
	v_mul_f32_e32 v61, v52, v53
	v_mul_f32_e32 v52, v62, v68
	v_rcp_f32_e32 v73, v73
	v_mul_f32_e32 v54, v52, v54
	v_mul_f32_e32 v52, v63, v69
	v_mul_f32_e32 v55, v52, v55
	v_mul_f32_e32 v52, v56, v70
	v_mul_f32_e32 v56, v52, v48
	v_mul_f32_e32 v48, v57, v71
	v_add_u32_e32 v64, 0x80, v160
	v_mul_f32_e32 v57, v48, v49
	v_mul_f32_e32 v48, v58, v72
	v_mad_i64_i32 v[64:65], s[0:1], v64, s33, v[138:139]
	v_mul_f32_e32 v58, v48, v50
	v_mul_f32_e32 v48, v59, v73
	v_mul_f32_e32 v51, v48, v51
	v_lshl_add_u64 v[52:53], v[64:65], 0, v[112:113]
	v_cvt_pk_bf16_f32 v50, v56, v57
	v_cvt_pk_bf16_f32 v48, v60, v61
	v_cvt_pk_bf16_f32 v49, v54, v55
	v_cvt_pk_bf16_f32 v51, v58, v51
	flat_store_dwordx4 v[52:53], v[48:51]
	v_mul_f32_e32 v52, 0xbfb8aa3b, v46
	v_exp_f32_e32 v52, v52
	v_mul_f32_e32 v50, 0xbfb8aa3b, v44
	v_exp_f32_e32 v50, v50
	v_mul_f32_e32 v51, 0xbfb8aa3b, v45
	v_exp_f32_e32 v51, v51
	v_mul_f32_e32 v53, 0xbfb8aa3b, v47
	v_exp_f32_e32 v53, v53
	v_mul_f32_e32 v54, 0xbfb8aa3b, v40
	v_exp_f32_e32 v54, v54
	v_mul_f32_e32 v55, 0xbfb8aa3b, v41
	v_add_f32_e32 v50, 1.0, v50
	v_exp_f32_e32 v55, v55
	v_mul_f32_e32 v56, 0xbfb8aa3b, v42
	v_rcp_f32_e32 v50, v50
	v_add_f32_e32 v51, 1.0, v51
	v_exp_f32_e32 v56, v56
	v_mul_f32_e32 v57, 0xbfb8aa3b, v43
	v_rcp_f32_e32 v51, v51
	v_add_f32_e32 v52, 1.0, v52
	v_exp_f32_e32 v57, v57
	v_rcp_f32_e32 v52, v52
	v_add_f32_e32 v53, 1.0, v53
	v_rcp_f32_e32 v53, v53
	v_add_f32_e32 v54, 1.0, v54
	v_rcp_f32_e32 v54, v54
	v_add_f32_e32 v55, 1.0, v55
	v_mul_f32_e32 v44, v44, v50
	v_rcp_f32_e32 v55, v55
	v_add_f32_e32 v56, 1.0, v56
	v_mul_f32_e32 v44, v44, v36
	v_mul_f32_e32 v36, v45, v51
	v_rcp_f32_e32 v56, v56
	v_add_f32_e32 v57, 1.0, v57
	v_mul_f32_e32 v45, v36, v37
	v_mul_f32_e32 v36, v46, v52
	v_rcp_f32_e32 v57, v57
	v_mul_f32_e32 v38, v36, v38
	v_mul_f32_e32 v36, v47, v53
	v_mul_f32_e32 v39, v36, v39
	v_mul_f32_e32 v36, v40, v54
	v_mul_f32_e32 v40, v36, v32
	v_mul_f32_e32 v32, v41, v55
	v_add_u32_e32 v48, 0x90, v160
	v_mul_f32_e32 v41, v32, v33
	v_mul_f32_e32 v32, v42, v56
	v_mad_i64_i32 v[48:49], s[0:1], v48, s33, v[138:139]
	v_mul_f32_e32 v42, v32, v34
	v_mul_f32_e32 v32, v43, v57
	v_mul_f32_e32 v35, v32, v35
	v_lshl_add_u64 v[36:37], v[48:49], 0, v[112:113]
	v_cvt_pk_bf16_f32 v34, v40, v41
	v_cvt_pk_bf16_f32 v32, v44, v45
	v_cvt_pk_bf16_f32 v33, v38, v39
	v_cvt_pk_bf16_f32 v35, v42, v35
	flat_store_dwordx4 v[36:37], v[32:35]
	v_mul_f32_e32 v36, 0xbfb8aa3b, v30
	v_exp_f32_e32 v36, v36
	v_mul_f32_e32 v34, 0xbfb8aa3b, v28
	v_exp_f32_e32 v34, v34
	v_mul_f32_e32 v35, 0xbfb8aa3b, v29
	v_exp_f32_e32 v35, v35
	v_mul_f32_e32 v37, 0xbfb8aa3b, v31
	v_exp_f32_e32 v37, v37
	v_mul_f32_e32 v38, 0xbfb8aa3b, v24
	v_exp_f32_e32 v38, v38
	v_mul_f32_e32 v39, 0xbfb8aa3b, v25
	v_add_f32_e32 v34, 1.0, v34
	v_exp_f32_e32 v39, v39
	v_mul_f32_e32 v40, 0xbfb8aa3b, v26
	v_rcp_f32_e32 v34, v34
	v_add_f32_e32 v35, 1.0, v35
	v_exp_f32_e32 v40, v40
	v_mul_f32_e32 v41, 0xbfb8aa3b, v27
	v_rcp_f32_e32 v35, v35
	v_add_f32_e32 v36, 1.0, v36
	v_exp_f32_e32 v41, v41
	v_rcp_f32_e32 v36, v36
	v_add_f32_e32 v37, 1.0, v37
	v_rcp_f32_e32 v37, v37
	v_add_f32_e32 v38, 1.0, v38
	v_rcp_f32_e32 v38, v38
	v_add_f32_e32 v39, 1.0, v39
	v_mul_f32_e32 v28, v28, v34
	v_rcp_f32_e32 v39, v39
	v_add_f32_e32 v40, 1.0, v40
	v_mul_f32_e32 v28, v28, v20
	v_mul_f32_e32 v20, v29, v35
	v_rcp_f32_e32 v40, v40
	v_add_f32_e32 v41, 1.0, v41
	v_mul_f32_e32 v29, v20, v21
	v_mul_f32_e32 v20, v30, v36
	v_rcp_f32_e32 v41, v41
	v_mul_f32_e32 v22, v20, v22
	v_mul_f32_e32 v20, v31, v37
	v_mul_f32_e32 v23, v20, v23
	v_mul_f32_e32 v20, v24, v38
	v_mul_f32_e32 v24, v20, v16
	v_mul_f32_e32 v16, v25, v39
	v_add_u32_e32 v32, 0xa0, v160
	v_mul_f32_e32 v25, v16, v17
	v_mul_f32_e32 v16, v26, v40
	v_mad_i64_i32 v[32:33], s[0:1], v32, s33, v[138:139]
	v_mul_f32_e32 v26, v16, v18
	v_mul_f32_e32 v16, v27, v41
	v_mul_f32_e32 v19, v16, v19
	v_lshl_add_u64 v[20:21], v[32:33], 0, v[112:113]
	v_cvt_pk_bf16_f32 v18, v24, v25
	v_cvt_pk_bf16_f32 v16, v28, v29
	v_cvt_pk_bf16_f32 v17, v22, v23
	v_cvt_pk_bf16_f32 v19, v26, v19
	flat_store_dwordx4 v[20:21], v[16:19]
	v_mul_f32_e32 v20, 0xbfb8aa3b, v14
	v_exp_f32_e32 v20, v20
	v_mul_f32_e32 v18, 0xbfb8aa3b, v12
	v_exp_f32_e32 v18, v18
	v_mul_f32_e32 v19, 0xbfb8aa3b, v13
	v_exp_f32_e32 v19, v19
	v_mul_f32_e32 v21, 0xbfb8aa3b, v15
	v_exp_f32_e32 v21, v21
	v_mul_f32_e32 v22, 0xbfb8aa3b, v8
	v_exp_f32_e32 v22, v22
	v_mul_f32_e32 v23, 0xbfb8aa3b, v9
	v_add_f32_e32 v18, 1.0, v18
	v_exp_f32_e32 v23, v23
	v_mul_f32_e32 v24, 0xbfb8aa3b, v10
	v_rcp_f32_e32 v18, v18
	v_add_f32_e32 v19, 1.0, v19
	v_exp_f32_e32 v24, v24
	v_mul_f32_e32 v25, 0xbfb8aa3b, v11
	v_rcp_f32_e32 v19, v19
	v_add_f32_e32 v20, 1.0, v20
	v_exp_f32_e32 v25, v25
	v_rcp_f32_e32 v20, v20
	v_add_f32_e32 v21, 1.0, v21
	v_rcp_f32_e32 v21, v21
	v_add_f32_e32 v22, 1.0, v22
	v_rcp_f32_e32 v22, v22
	v_add_f32_e32 v23, 1.0, v23
	v_mul_f32_e32 v12, v12, v18
	v_rcp_f32_e32 v23, v23
	v_add_f32_e32 v24, 1.0, v24
	v_mul_f32_e32 v12, v12, v4
	v_mul_f32_e32 v4, v13, v19
	v_rcp_f32_e32 v24, v24
	v_add_f32_e32 v25, 1.0, v25
	v_mul_f32_e32 v13, v4, v5
	v_mul_f32_e32 v4, v14, v20
	v_rcp_f32_e32 v25, v25
	v_mul_f32_e32 v6, v4, v6
	v_mul_f32_e32 v4, v15, v21
	v_mul_f32_e32 v7, v4, v7
	v_mul_f32_e32 v4, v8, v22
	v_mul_f32_e32 v8, v4, v0
	v_mul_f32_e32 v0, v9, v23
	v_add_u32_e32 v16, 0xb0, v160
	v_mul_f32_e32 v9, v0, v1
	v_mul_f32_e32 v0, v10, v24
	v_mad_i64_i32 v[16:17], s[0:1], v16, s33, v[138:139]
	v_mul_f32_e32 v10, v0, v2
	v_mul_f32_e32 v0, v11, v25
	v_mul_f32_e32 v3, v0, v3
	v_lshl_add_u64 v[4:5], v[16:17], 0, v[112:113]
	s_and_b64 vcc, exec, s[6:7]
	s_mov_b32 s20, s8
	s_mov_b32 s14, s4
	s_mov_b64 s[16:17], s[12:13]
	s_mov_b64 s[0:1], s[10:11]
	v_cvt_pk_bf16_f32 v0, v12, v13
	v_cvt_pk_bf16_f32 v1, v6, v7
	v_cvt_pk_bf16_f32 v2, v8, v9
	v_cvt_pk_bf16_f32 v3, v10, v3
	flat_store_dwordx4 v[4:5], v[0:3]
	s_cbranch_vccz .LBB0_286
	s_waitcnt vmcnt(0)
	s_cmpk_gt_u32 s39, 0xff
	v_readlane_b32 s51, v252, 10
	s_cbranch_scc1 .LBB0_293
	s_barrier

.LBB0_321:
	s_add_u32 s0, s16, 0xfffc0080
	s_addc_u32 s1, s17, -1
	s_add_i32 s2, 0, 0x10000
	v_add_u32_e32 v138, s2, v154
	ds_read_b128 v[156:159], v138
	ds_read_b128 v[160:163], v138 offset:1024
	ds_read_b128 v[164:167], v138 offset:2048
	ds_read_b128 v[168:171], v138 offset:3072
	s_cmp_eq_u32 s59, 12
	s_cselect_b32 s41, s11, s1
	s_cselect_b32 s40, s10, s0
	s_cselect_b32 s1, s13, s9
	s_cselect_b32 s0, s12, s5
	s_add_i32 m0, s15, 0xc000
	ds_read_b128 v[172:175], v155
	ds_read_b128 v[176:179], v155 offset:1024
	ds_read_b128 v[180:183], v155 offset:2048
	ds_read_b128 v[184:187], v155 offset:3072
	ds_read_b128 v[188:191], v155 offset:4096
	ds_read_b128 v[192:195], v155 offset:5120
	ds_read_b128 v[196:199], v155 offset:6144
	ds_read_b128 v[200:203], v155 offset:7168
	global_load_lds_dwordx4 v136, s[16:17]
	s_add_i32 m0, s15, 0xe000
	s_nop 0
	global_load_lds_dwordx4 v134, s[16:17]
	s_waitcnt lgkmcnt(8)
	s_barrier
	s_waitcnt lgkmcnt(0)
	s_setprio 1
	s_waitcnt lgkmcnt(0)
	v_mfma_f32_16x16x32_bf16 v[124:127], v[156:159], v[172:175], v[124:127]
	v_mfma_f32_16x16x32_bf16 v[120:123], v[164:167], v[172:175], v[120:123]
	v_mfma_f32_16x16x32_bf16 v[116:119], v[156:159], v[180:183], v[116:119]
	v_mfma_f32_16x16x32_bf16 v[108:111], v[164:167], v[180:183], v[108:111]
	v_mfma_f32_16x16x32_bf16 v[100:103], v[156:159], v[188:191], v[100:103]
	v_mfma_f32_16x16x32_bf16 v[92:95], v[164:167], v[188:191], v[92:95]
	v_mfma_f32_16x16x32_bf16 v[84:87], v[156:159], v[196:199], v[84:87]
	v_mfma_f32_16x16x32_bf16 v[76:79], v[164:167], v[196:199], v[76:79]
	v_mfma_f32_16x16x32_bf16 v[124:127], v[160:163], v[176:179], v[124:127]
	v_mfma_f32_16x16x32_bf16 v[120:123], v[168:171], v[176:179], v[120:123]
	v_mfma_f32_16x16x32_bf16 v[116:119], v[160:163], v[184:187], v[116:119]
	v_mfma_f32_16x16x32_bf16 v[108:111], v[168:171], v[184:187], v[108:111]
	v_mfma_f32_16x16x32_bf16 v[100:103], v[160:163], v[192:195], v[100:103]
	v_mfma_f32_16x16x32_bf16 v[92:95], v[168:171], v[192:195], v[92:95]
	v_mfma_f32_16x16x32_bf16 v[84:87], v[160:163], v[200:203], v[84:87]
	v_mfma_f32_16x16x32_bf16 v[76:79], v[168:171], v[200:203], v[76:79]
	s_setprio 0
	s_barrier
	s_add_i32 s30, 0, 0x14000
	v_add_u32_e32 v138, s30, v154
	s_add_i32 s2, s2, s45
	ds_read_b128 v[204:207], v138
	ds_read_b128 v[208:211], v138 offset:1024
	ds_read_b128 v[228:231], v138 offset:2048
	ds_read_b128 v[232:235], v138 offset:3072
	s_mov_b32 m0, s2
	s_nop 0
	global_load_lds_dwordx4 v140, s[0:1]
	s_add_i32 m0, s2, 0x2000
	s_nop 0
	global_load_lds_dwordx4 v132, s[0:1]
	s_barrier
	s_waitcnt lgkmcnt(0)
	s_setprio 1
	s_waitcnt lgkmcnt(0)
	v_mfma_f32_16x16x32_bf16 v[112:115], v[204:207], v[172:175], v[112:115]
	v_mfma_f32_16x16x32_bf16 v[104:107], v[228:231], v[172:175], v[104:107]
	v_mfma_f32_16x16x32_bf16 v[96:99], v[204:207], v[180:183], v[96:99]
	v_mfma_f32_16x16x32_bf16 v[88:91], v[228:231], v[180:183], v[88:91]
	v_mfma_f32_16x16x32_bf16 v[80:83], v[204:207], v[188:191], v[80:83]
	v_mfma_f32_16x16x32_bf16 v[72:75], v[228:231], v[188:191], v[72:75]
	v_mfma_f32_16x16x32_bf16 v[68:71], v[204:207], v[196:199], v[68:71]
	v_mfma_f32_16x16x32_bf16 v[64:67], v[228:231], v[196:199], v[64:67]
	v_mfma_f32_16x16x32_bf16 v[112:115], v[208:211], v[176:179], v[112:115]
	v_mfma_f32_16x16x32_bf16 v[104:107], v[232:235], v[176:179], v[104:107]
	v_mfma_f32_16x16x32_bf16 v[96:99], v[208:211], v[184:187], v[96:99]
	v_mfma_f32_16x16x32_bf16 v[88:91], v[232:235], v[184:187], v[88:91]
	v_mfma_f32_16x16x32_bf16 v[80:83], v[208:211], v[192:195], v[80:83]
	v_mfma_f32_16x16x32_bf16 v[72:75], v[232:235], v[192:195], v[72:75]
	v_mfma_f32_16x16x32_bf16 v[68:71], v[208:211], v[200:203], v[68:71]
	v_mfma_f32_16x16x32_bf16 v[64:67], v[232:235], v[200:203], v[64:67]
	s_setprio 0
	s_mov_b32 m0, s15
	s_barrier
	ds_read_b128 v[172:175], v155 offset:16384
	ds_read_b128 v[176:179], v155 offset:17408
	ds_read_b128 v[180:183], v155 offset:18432
	ds_read_b128 v[184:187], v155 offset:19456
	ds_read_b128 v[188:191], v155 offset:20480
	ds_read_b128 v[192:195], v155 offset:21504
	ds_read_b128 v[196:199], v155 offset:22528
	ds_read_b128 v[200:203], v155 offset:23552
	global_load_lds_dwordx4 v128, s[40:41]
	s_mov_b32 m0, s46
	s_nop 0
	global_load_lds_dwordx4 v130, s[40:41]
	s_barrier
	s_waitcnt lgkmcnt(0)
	s_setprio 1
	s_waitcnt lgkmcnt(0)
	v_mfma_f32_16x16x32_bf16 v[60:63], v[156:159], v[172:175], v[60:63]
	v_mfma_f32_16x16x32_bf16 v[56:59], v[164:167], v[172:175], v[56:59]
	v_mfma_f32_16x16x32_bf16 v[52:55], v[156:159], v[180:183], v[52:55]
	v_mfma_f32_16x16x32_bf16 v[44:47], v[164:167], v[180:183], v[44:47]
	v_mfma_f32_16x16x32_bf16 v[36:39], v[156:159], v[188:191], v[36:39]
	v_mfma_f32_16x16x32_bf16 v[28:31], v[164:167], v[188:191], v[28:31]
	v_mfma_f32_16x16x32_bf16 v[20:23], v[156:159], v[196:199], v[20:23]
	v_mfma_f32_16x16x32_bf16 v[12:15], v[164:167], v[196:199], v[12:15]
	v_mfma_f32_16x16x32_bf16 v[60:63], v[160:163], v[176:179], v[60:63]
	v_mfma_f32_16x16x32_bf16 v[56:59], v[168:171], v[176:179], v[56:59]
	v_mfma_f32_16x16x32_bf16 v[52:55], v[160:163], v[184:187], v[52:55]
	v_mfma_f32_16x16x32_bf16 v[44:47], v[168:171], v[184:187], v[44:47]
	v_mfma_f32_16x16x32_bf16 v[36:39], v[160:163], v[192:195], v[36:39]
	v_mfma_f32_16x16x32_bf16 v[28:31], v[168:171], v[192:195], v[28:31]
	v_mfma_f32_16x16x32_bf16 v[20:23], v[160:163], v[200:203], v[20:23]
	v_mfma_f32_16x16x32_bf16 v[12:15], v[168:171], v[200:203], v[12:15]
	s_setprio 0
	s_barrier
	s_add_u32 s18, s0, 0x40000
	s_addc_u32 s19, s1, 0
	s_add_i32 s2, s30, s45
	s_mov_b32 m0, s2
	s_nop 0
	global_load_lds_dwordx4 v140, s[18:19]
	s_add_i32 m0, s2, 0x2000
	s_nop 0
	global_load_lds_dwordx4 v132, s[18:19]
	s_waitcnt vmcnt(6)
	s_barrier
	s_setprio 1
	v_mfma_f32_16x16x32_bf16 v[48:51], v[204:207], v[172:175], v[48:51]
	v_mfma_f32_16x16x32_bf16 v[40:43], v[228:231], v[172:175], v[40:43]
	v_mfma_f32_16x16x32_bf16 v[32:35], v[204:207], v[180:183], v[32:35]
	v_mfma_f32_16x16x32_bf16 v[24:27], v[228:231], v[180:183], v[24:27]
	v_mfma_f32_16x16x32_bf16 v[16:19], v[204:207], v[188:191], v[16:19]
	v_mfma_f32_16x16x32_bf16 v[8:11], v[228:231], v[188:191], v[8:11]
	v_mfma_f32_16x16x32_bf16 v[4:7], v[204:207], v[196:199], v[4:7]
	v_mfma_f32_16x16x32_bf16 v[0:3], v[228:231], v[196:199], v[0:3]
	v_mfma_f32_16x16x32_bf16 v[48:51], v[208:211], v[176:179], v[48:51]
	v_mfma_f32_16x16x32_bf16 v[40:43], v[232:235], v[176:179], v[40:43]
	v_mfma_f32_16x16x32_bf16 v[32:35], v[208:211], v[184:187], v[32:35]
	v_mfma_f32_16x16x32_bf16 v[24:27], v[232:235], v[184:187], v[24:27]
	v_mfma_f32_16x16x32_bf16 v[16:19], v[208:211], v[192:195], v[16:19]
	v_mfma_f32_16x16x32_bf16 v[8:11], v[232:235], v[192:195], v[8:11]
	v_mfma_f32_16x16x32_bf16 v[4:7], v[208:211], v[200:203], v[4:7]
	v_mfma_f32_16x16x32_bf16 v[0:3], v[232:235], v[200:203], v[0:3]
	s_setprio 0
	s_add_i32 s2, 0, 0x18000
	v_add_u32_e32 v168, s2, v154
	s_barrier
	ds_read_b128 v[156:159], v168
	ds_read_b128 v[160:163], v168 offset:1024
	ds_read_b128 v[164:167], v168 offset:2048
	ds_read_b128 v[168:171], v168 offset:3072
	s_add_u32 s18, s40, 0x40000
	s_addc_u32 s19, s41, 0
	s_mov_b32 m0, s48
	ds_read_b128 v[172:175], v155 offset:32768
	ds_read_b128 v[176:179], v155 offset:33792
	ds_read_b128 v[180:183], v155 offset:34816
	ds_read_b128 v[184:187], v155 offset:35840
	ds_read_b128 v[188:191], v155 offset:36864
	ds_read_b128 v[192:195], v155 offset:37888
	ds_read_b128 v[196:199], v155 offset:38912
	ds_read_b128 v[200:203], v155 offset:39936
	global_load_lds_dwordx4 v128, s[18:19]
	s_mov_b32 m0, s49
	s_nop 0
	global_load_lds_dwordx4 v130, s[18:19]
	s_waitcnt lgkmcnt(8)
	s_barrier
	s_waitcnt lgkmcnt(0)
	s_setprio 1
	s_waitcnt lgkmcnt(0)
	v_mfma_f32_16x16x32_bf16 v[124:127], v[156:159], v[172:175], v[124:127]
	v_mfma_f32_16x16x32_bf16 v[120:123], v[164:167], v[172:175], v[120:123]
	v_mfma_f32_16x16x32_bf16 v[116:119], v[156:159], v[180:183], v[116:119]
	v_mfma_f32_16x16x32_bf16 v[108:111], v[164:167], v[180:183], v[108:111]
	v_mfma_f32_16x16x32_bf16 v[100:103], v[156:159], v[188:191], v[100:103]
	v_mfma_f32_16x16x32_bf16 v[92:95], v[164:167], v[188:191], v[92:95]
	v_mfma_f32_16x16x32_bf16 v[84:87], v[156:159], v[196:199], v[84:87]
	v_mfma_f32_16x16x32_bf16 v[76:79], v[164:167], v[196:199], v[76:79]
	v_mfma_f32_16x16x32_bf16 v[124:127], v[160:163], v[176:179], v[124:127]
	v_mfma_f32_16x16x32_bf16 v[120:123], v[168:171], v[176:179], v[120:123]
	v_mfma_f32_16x16x32_bf16 v[116:119], v[160:163], v[184:187], v[116:119]
	v_mfma_f32_16x16x32_bf16 v[108:111], v[168:171], v[184:187], v[108:111]
	v_mfma_f32_16x16x32_bf16 v[100:103], v[160:163], v[192:195], v[100:103]
	v_mfma_f32_16x16x32_bf16 v[92:95], v[168:171], v[192:195], v[92:95]
	v_mfma_f32_16x16x32_bf16 v[84:87], v[160:163], v[200:203], v[84:87]
	v_mfma_f32_16x16x32_bf16 v[76:79], v[168:171], v[200:203], v[76:79]
	s_setprio 0
	s_barrier
	s_add_i32 s18, 0, 0x1c000
	s_add_i32 s2, s2, s45
	v_add_u32_e32 v232, s18, v154
	s_mov_b32 m0, s2
	ds_read_b128 v[204:207], v232
	ds_read_b128 v[208:211], v232 offset:1024
	ds_read_b128 v[228:231], v232 offset:2048
	ds_read_b128 v[232:235], v232 offset:3072
	s_add_u32 s100, s0, 0x80
	s_addc_u32 s101, s1, 0
	global_load_lds_dwordx4 v140, s[100:101]
	s_add_i32 m0, s2, 0x2000
	s_nop 0
	global_load_lds_dwordx4 v132, s[100:101]
	s_barrier
	s_waitcnt lgkmcnt(0)
	s_setprio 1
	s_waitcnt lgkmcnt(0)
	v_mfma_f32_16x16x32_bf16 v[112:115], v[204:207], v[172:175], v[112:115]
	v_mfma_f32_16x16x32_bf16 v[104:107], v[228:231], v[172:175], v[104:107]
	v_mfma_f32_16x16x32_bf16 v[96:99], v[204:207], v[180:183], v[96:99]
	v_mfma_f32_16x16x32_bf16 v[88:91], v[228:231], v[180:183], v[88:91]
	v_mfma_f32_16x16x32_bf16 v[80:83], v[204:207], v[188:191], v[80:83]
	v_mfma_f32_16x16x32_bf16 v[72:75], v[228:231], v[188:191], v[72:75]
	v_mfma_f32_16x16x32_bf16 v[68:71], v[204:207], v[196:199], v[68:71]
	v_mfma_f32_16x16x32_bf16 v[64:67], v[228:231], v[196:199], v[64:67]
	v_mfma_f32_16x16x32_bf16 v[112:115], v[208:211], v[176:179], v[112:115]
	v_mfma_f32_16x16x32_bf16 v[104:107], v[232:235], v[176:179], v[104:107]
	v_mfma_f32_16x16x32_bf16 v[96:99], v[208:211], v[184:187], v[96:99]
	v_mfma_f32_16x16x32_bf16 v[88:91], v[232:235], v[184:187], v[88:91]
	v_mfma_f32_16x16x32_bf16 v[80:83], v[208:211], v[192:195], v[80:83]
	v_mfma_f32_16x16x32_bf16 v[72:75], v[232:235], v[192:195], v[72:75]
	v_mfma_f32_16x16x32_bf16 v[68:71], v[208:211], v[200:203], v[68:71]
	v_mfma_f32_16x16x32_bf16 v[64:67], v[232:235], v[200:203], v[64:67]
	s_setprio 0
	s_mov_b32 m0, s57
	s_barrier
	ds_read_b128 v[172:175], v155 offset:49152
	ds_read_b128 v[176:179], v155 offset:50176
	ds_read_b128 v[180:183], v155 offset:51200
	ds_read_b128 v[184:187], v155 offset:52224
	ds_read_b128 v[188:191], v155 offset:53248
	ds_read_b128 v[192:195], v155 offset:54272
	ds_read_b128 v[196:199], v155 offset:55296
	ds_read_b128 v[200:203], v155 offset:56320
	s_add_u32 s100, s40, 0x80
	s_addc_u32 s101, s41, 0
	global_load_lds_dwordx4 v128, s[100:101]
	s_mov_b32 m0, s58
	s_nop 0
	global_load_lds_dwordx4 v130, s[100:101]
	s_barrier
	s_waitcnt lgkmcnt(0)
	s_setprio 1
	s_waitcnt lgkmcnt(0)
	v_mfma_f32_16x16x32_bf16 v[60:63], v[156:159], v[172:175], v[60:63]
	v_mfma_f32_16x16x32_bf16 v[56:59], v[164:167], v[172:175], v[56:59]
	v_mfma_f32_16x16x32_bf16 v[52:55], v[156:159], v[180:183], v[52:55]
	v_mfma_f32_16x16x32_bf16 v[44:47], v[164:167], v[180:183], v[44:47]
	v_mfma_f32_16x16x32_bf16 v[36:39], v[156:159], v[188:191], v[36:39]
	v_mfma_f32_16x16x32_bf16 v[28:31], v[164:167], v[188:191], v[28:31]
	v_mfma_f32_16x16x32_bf16 v[20:23], v[156:159], v[196:199], v[20:23]
	v_mfma_f32_16x16x32_bf16 v[12:15], v[164:167], v[196:199], v[12:15]
	v_mfma_f32_16x16x32_bf16 v[60:63], v[160:163], v[176:179], v[60:63]
	v_mfma_f32_16x16x32_bf16 v[56:59], v[168:171], v[176:179], v[56:59]
	v_mfma_f32_16x16x32_bf16 v[52:55], v[160:163], v[184:187], v[52:55]
	v_mfma_f32_16x16x32_bf16 v[44:47], v[168:171], v[184:187], v[44:47]
	v_mfma_f32_16x16x32_bf16 v[36:39], v[160:163], v[192:195], v[36:39]
	v_mfma_f32_16x16x32_bf16 v[28:31], v[168:171], v[192:195], v[28:31]
	v_mfma_f32_16x16x32_bf16 v[20:23], v[160:163], v[200:203], v[20:23]
	v_mfma_f32_16x16x32_bf16 v[12:15], v[168:171], v[200:203], v[12:15]
	s_setprio 0
	s_barrier
	s_add_u32 s0, s0, 0x40080
	s_addc_u32 s1, s1, 0
	s_add_i32 s2, s18, s45
	s_mov_b32 m0, s2
	s_nop 0
	global_load_lds_dwordx4 v140, s[0:1]
	s_add_i32 m0, s2, 0x2000
	s_nop 0
	global_load_lds_dwordx4 v132, s[0:1]
	s_waitcnt vmcnt(6)
	s_barrier
	s_setprio 1
	v_mfma_f32_16x16x32_bf16 v[48:51], v[204:207], v[172:175], v[48:51]
	v_mfma_f32_16x16x32_bf16 v[40:43], v[228:231], v[172:175], v[40:43]
	v_mfma_f32_16x16x32_bf16 v[32:35], v[204:207], v[180:183], v[32:35]
	v_mfma_f32_16x16x32_bf16 v[24:27], v[228:231], v[180:183], v[24:27]
	v_mfma_f32_16x16x32_bf16 v[16:19], v[204:207], v[188:191], v[16:19]
	v_mfma_f32_16x16x32_bf16 v[8:11], v[228:231], v[188:191], v[8:11]
	v_mfma_f32_16x16x32_bf16 v[4:7], v[204:207], v[196:199], v[4:7]
	v_mfma_f32_16x16x32_bf16 v[0:3], v[228:231], v[196:199], v[0:3]
	v_mfma_f32_16x16x32_bf16 v[48:51], v[208:211], v[176:179], v[48:51]
	v_mfma_f32_16x16x32_bf16 v[40:43], v[232:235], v[176:179], v[40:43]
	v_mfma_f32_16x16x32_bf16 v[32:35], v[208:211], v[184:187], v[32:35]
	v_mfma_f32_16x16x32_bf16 v[24:27], v[232:235], v[184:187], v[24:27]
	v_mfma_f32_16x16x32_bf16 v[16:19], v[208:211], v[192:195], v[16:19]
	v_mfma_f32_16x16x32_bf16 v[8:11], v[232:235], v[192:195], v[8:11]
	v_mfma_f32_16x16x32_bf16 v[4:7], v[208:211], v[200:203], v[4:7]
	v_mfma_f32_16x16x32_bf16 v[0:3], v[232:235], v[200:203], v[0:3]
	s_setprio 0
	s_add_i32 s59, s59, 2
	s_add_u32 s5, s5, 0x100
	s_addc_u32 s9, s9, 0
	s_add_u32 s16, s16, 0x100
	s_addc_u32 s17, s17, 0
	s_cmp_gt_u32 s59, 13
	s_barrier
	s_cbranch_scc0 .LBB0_321
	s_lshl_b32 s0, s14, 8
	v_mbcnt_lo_u32_b32 v139, -1, 0
	v_mbcnt_hi_u32_b32 v139, -1, v139
	s_lshl_b32 s1, s21, 8
	v_ashrrev_i32_e32 v138, 1, v139
	s_add_i32 s0, s0, s51
	v_and_b32_e32 v138, -8, v138
	s_or_b32 s1, s1, s52
	v_and_or_b32 v156, v139, 15, s0
	v_add_u32_e32 v138, s1, v138
	v_ashrrev_i32_e32 v157, 31, v156
	v_ashrrev_i32_e32 v139, 31, v138
	v_lshlrev_b64 v[158:159], 11, v[156:157]
	v_lshl_add_u64 v[158:159], s[26:27], 0, v[158:159]
	v_lshlrev_b64 v[160:161], 1, v[138:139]
	v_lshl_add_u64 v[138:139], v[158:159], 0, v[160:161]
	v_cvt_pk_bf16_f32 v60, v60, v61
	v_cvt_pk_bf16_f32 v61, v62, v63
	v_cvt_pk_bf16_f32 v62, v56, v57
	v_add_co_u32_e32 v56, vcc, s31, v138
	v_cvt_pk_bf16_f32 v112, v112, v113
	v_cvt_pk_bf16_f32 v113, v114, v115
	v_cvt_pk_bf16_f32 v114, v104, v105
	v_or_b32_e32 v104, 16, v156
	s_nop 0
	v_addc_co_u32_e32 v57, vcc, 0, v139, vcc
	v_cvt_pk_bf16_f32 v48, v48, v49
	v_cvt_pk_bf16_f32 v49, v50, v51
	v_cvt_pk_bf16_f32 v51, v42, v43
	v_cvt_pk_bf16_f32 v42, v44, v45
	v_add_co_u32_e32 v44, vcc, s42, v138
	v_ashrrev_i32_e32 v105, 31, v104
	v_cvt_pk_bf16_f32 v96, v96, v97
	v_cvt_pk_bf16_f32 v97, v98, v99
	v_cvt_pk_bf16_f32 v98, v88, v89
	v_or_b32_e32 v88, 32, v156
	v_addc_co_u32_e32 v45, vcc, 0, v139, vcc
	v_lshlrev_b64 v[104:105], 11, v[104:105]
	v_ashrrev_i32_e32 v89, 31, v88
	v_cvt_pk_bf16_f32 v80, v80, v81
	v_cvt_pk_bf16_f32 v81, v82, v83
	v_cvt_pk_bf16_f32 v82, v72, v73
	v_or_b32_e32 v72, 48, v156
	s_mov_b64 s[0:1], 0x40000
	v_cvt_pk_bf16_f32 v32, v32, v33
	v_cvt_pk_bf16_f32 v33, v34, v35
	v_cvt_pk_bf16_f32 v35, v26, v27
	v_cvt_pk_bf16_f32 v26, v28, v29
	v_add_co_u32_e32 v28, vcc, s43, v138
	v_lshl_add_u64 v[104:105], s[26:27], 0, v[104:105]
	v_lshlrev_b64 v[88:89], 11, v[88:89]
	v_ashrrev_i32_e32 v73, 31, v72
	v_cvt_pk_bf16_f32 v68, v68, v69
	v_cvt_pk_bf16_f32 v69, v70, v71
	v_cvt_pk_bf16_f32 v70, v64, v65
	v_lshl_add_u64 v[64:65], v[138:139], 0, s[0:1]
	s_mov_b64 s[0:1], 0x48000
	v_addc_co_u32_e32 v29, vcc, 0, v139, vcc
	v_cvt_pk_bf16_f32 v115, v106, v107
	flat_store_dwordx4 v[138:139], v[112:115] offset:256
	v_lshl_add_u64 v[88:89], s[26:27], 0, v[88:89]
	v_lshlrev_b64 v[72:73], 11, v[72:73]
	v_lshl_add_u64 v[112:113], v[104:105], 0, v[160:161]
	v_cvt_pk_bf16_f32 v50, v40, v41
	flat_store_dwordx4 v[64:65], v[48:51] offset:256
	v_cvt_pk_bf16_f32 v16, v16, v17
	v_cvt_pk_bf16_f32 v17, v18, v19
	v_cvt_pk_bf16_f32 v19, v10, v11
	v_cvt_pk_bf16_f32 v10, v12, v13
	v_add_co_u32_e32 v12, vcc, s47, v138
	s_nop 0
	v_lshl_add_u64 v[48:49], v[138:139], 0, s[0:1]
	s_mov_b64 s[0:1], 0x50000
	v_cvt_pk_bf16_f32 v99, v90, v91
	flat_store_dwordx4 v[112:113], v[96:99] offset:256
	v_lshl_add_u64 v[72:73], s[26:27], 0, v[72:73]
	v_cvt_pk_bf16_f32 v34, v24, v25
	flat_store_dwordx4 v[48:49], v[32:35] offset:256
	v_lshl_add_u64 v[96:97], v[88:89], 0, v[160:161]
	v_addc_co_u32_e32 v13, vcc, 0, v139, vcc
	v_lshl_add_u64 v[32:33], v[138:139], 0, s[0:1]
	s_mov_b64 s[0:1], 0x58000
	v_cvt_pk_bf16_f32 v83, v74, v75
	flat_store_dwordx4 v[96:97], v[80:83] offset:256
	v_cvt_pk_bf16_f32 v18, v8, v9
	flat_store_dwordx4 v[32:33], v[16:19] offset:256
	s_and_b64 vcc, exec, s[6:7]
	v_lshl_add_u64 v[80:81], v[72:73], 0, v[160:161]
	v_lshl_add_u64 v[16:17], v[138:139], 0, s[0:1]
	s_mov_b32 s21, s8
	s_mov_b32 s14, s4
	s_mov_b64 s[16:17], s[12:13]
	s_mov_b64 s[0:1], s[10:11]
	v_cvt_pk_bf16_f32 v124, v124, v125
	v_cvt_pk_bf16_f32 v125, v126, v127
	v_cvt_pk_bf16_f32 v126, v120, v121
	v_cvt_pk_bf16_f32 v127, v122, v123
	flat_store_dwordx4 v[138:139], v[124:127]
	v_cvt_pk_bf16_f32 v104, v116, v117
	v_cvt_pk_bf16_f32 v105, v118, v119
	v_cvt_pk_bf16_f32 v106, v108, v109
	v_cvt_pk_bf16_f32 v107, v110, v111
	flat_store_dwordx4 v[112:113], v[104:107]
	v_cvt_pk_bf16_f32 v88, v100, v101
	v_cvt_pk_bf16_f32 v89, v102, v103
	v_cvt_pk_bf16_f32 v90, v92, v93
	v_cvt_pk_bf16_f32 v91, v94, v95
	flat_store_dwordx4 v[96:97], v[88:91]
	v_cvt_pk_bf16_f32 v72, v84, v85
	v_cvt_pk_bf16_f32 v73, v86, v87
	v_cvt_pk_bf16_f32 v74, v76, v77
	v_cvt_pk_bf16_f32 v75, v78, v79
	flat_store_dwordx4 v[80:81], v[72:75]
	v_cvt_pk_bf16_f32 v71, v66, v67
	flat_store_dwordx4 v[80:81], v[68:71] offset:256
	v_cvt_pk_bf16_f32 v63, v58, v59
	flat_store_dwordx4 v[56:57], v[60:63]
	v_cvt_pk_bf16_f32 v40, v52, v53
	v_cvt_pk_bf16_f32 v41, v54, v55
	v_cvt_pk_bf16_f32 v43, v46, v47
	flat_store_dwordx4 v[44:45], v[40:43]
	v_cvt_pk_bf16_f32 v24, v36, v37
	v_cvt_pk_bf16_f32 v25, v38, v39
	v_cvt_pk_bf16_f32 v27, v30, v31
	flat_store_dwordx4 v[28:29], v[24:27]
	v_cvt_pk_bf16_f32 v8, v20, v21
	v_cvt_pk_bf16_f32 v9, v22, v23
	v_cvt_pk_bf16_f32 v11, v14, v15
	flat_store_dwordx4 v[12:13], v[8:11]
	v_cvt_pk_bf16_f32 v4, v4, v5
	v_cvt_pk_bf16_f32 v5, v6, v7
	v_cvt_pk_bf16_f32 v6, v0, v1
	v_cvt_pk_bf16_f32 v7, v2, v3
	flat_store_dwordx4 v[16:17], v[4:7] offset:256
	s_cbranch_vccz .LBB0_314
	s_waitcnt vmcnt(0)
	s_cmpk_gt_u32 s37, 0xff
	s_cbranch_scc1 .LBB0_325
	s_barrier

.LBB0_405:
	s_add_i32 s21, s0, 2
	s_add_u32 s1, vcc_lo, 0xfffe0080
	s_addc_u32 s2, vcc_hi, -1
	s_add_i32 s18, 0, 0x10000
	v_add_u32_e32 v164, s18, v178
	ds_read_b128 v[128:131], v164
	ds_read_b128 v[132:135], v164 offset:1024
	ds_read_b128 v[136:139], v164 offset:2048
	ds_read_b128 v[164:167], v164 offset:3072
	s_cmp_eq_u32 s5, s0
	s_cselect_b32 s0, s10, s17
	s_cselect_b32 s89, s9, s2
	s_cselect_b32 s88, s8, s1
	s_cselect_b32 s1, s11, s20
	v_lshl_add_u64 v[176:177], vcc, 0, v[162:163]
	s_add_i32 m0, s97, 0xc000
	ds_read_b128 v[168:171], v179
	ds_read_b128 v[172:175], v179 offset:1024
	ds_read_b128 v[180:183], v179 offset:2048
	ds_read_b128 v[184:187], v179 offset:3072
	ds_read_b128 v[188:191], v179 offset:4096
	ds_read_b128 v[192:195], v179 offset:5120
	ds_read_b128 v[196:199], v179 offset:6144
	ds_read_b128 v[200:203], v179 offset:7168
	global_load_lds_dwordx4 v[176:177], off
	v_lshl_add_u64 v[176:177], vcc, 0, v[160:161]
	s_add_i32 m0, s97, 0xe000
	s_nop 0
	global_load_lds_dwordx4 v[176:177], off
	s_waitcnt lgkmcnt(8)
	s_barrier
	s_waitcnt lgkmcnt(0)
	s_setprio 1
	s_waitcnt lgkmcnt(0)
	v_mfma_f32_16x16x32_bf16 v[120:123], v[128:131], v[168:171], v[120:123]
	v_mfma_f32_16x16x32_bf16 v[68:71], v[136:139], v[168:171], v[68:71]
	v_mfma_f32_16x16x32_bf16 v[116:119], v[128:131], v[180:183], v[116:119]
	v_mfma_f32_16x16x32_bf16 v[60:63], v[136:139], v[180:183], v[60:63]
	v_mfma_f32_16x16x32_bf16 v[108:111], v[128:131], v[188:191], v[108:111]
	v_mfma_f32_16x16x32_bf16 v[44:47], v[136:139], v[188:191], v[44:47]
	v_mfma_f32_16x16x32_bf16 v[100:103], v[128:131], v[196:199], v[100:103]
	v_mfma_f32_16x16x32_bf16 v[36:39], v[136:139], v[196:199], v[36:39]
	v_mfma_f32_16x16x32_bf16 v[120:123], v[132:135], v[172:175], v[120:123]
	v_mfma_f32_16x16x32_bf16 v[68:71], v[164:167], v[172:175], v[68:71]
	v_mfma_f32_16x16x32_bf16 v[116:119], v[132:135], v[184:187], v[116:119]
	v_mfma_f32_16x16x32_bf16 v[60:63], v[164:167], v[184:187], v[60:63]
	v_mfma_f32_16x16x32_bf16 v[108:111], v[132:135], v[192:195], v[108:111]
	v_mfma_f32_16x16x32_bf16 v[44:47], v[164:167], v[192:195], v[44:47]
	v_mfma_f32_16x16x32_bf16 v[100:103], v[132:135], v[200:203], v[100:103]
	v_mfma_f32_16x16x32_bf16 v[36:39], v[164:167], v[200:203], v[36:39]
	s_setprio 0
	s_barrier
	s_add_i32 s2, 0, 0x14000
	v_add_u32_e32 v176, s2, v178
	s_add_i32 s18, s18, s59
	ds_read_b128 v[204:207], v176
	ds_read_b128 v[208:211], v176 offset:1024
	ds_read_b128 v[228:231], v176 offset:2048
	ds_read_b128 v[232:235], v176 offset:3072
	s_mov_b32 m0, s18
	s_nop 0
	global_load_lds_dwordx4 v140, s[0:1]
	s_add_i32 m0, s18, 0x2000
	s_nop 0
	global_load_lds_dwordx4 v158, s[0:1]
	s_barrier
	s_waitcnt lgkmcnt(0)
	s_setprio 1
	s_waitcnt lgkmcnt(0)
	v_mfma_f32_16x16x32_bf16 v[124:127], v[204:207], v[168:171], v[124:127]
	v_mfma_f32_16x16x32_bf16 v[64:67], v[228:231], v[168:171], v[64:67]
	v_mfma_f32_16x16x32_bf16 v[112:115], v[204:207], v[180:183], v[112:115]
	v_mfma_f32_16x16x32_bf16 v[56:59], v[228:231], v[180:183], v[56:59]
	v_mfma_f32_16x16x32_bf16 v[104:107], v[204:207], v[188:191], v[104:107]
	v_mfma_f32_16x16x32_bf16 v[40:43], v[228:231], v[188:191], v[40:43]
	v_mfma_f32_16x16x32_bf16 v[96:99], v[204:207], v[196:199], v[96:99]
	v_mfma_f32_16x16x32_bf16 v[32:35], v[228:231], v[196:199], v[32:35]
	v_mfma_f32_16x16x32_bf16 v[124:127], v[208:211], v[172:175], v[124:127]
	v_mfma_f32_16x16x32_bf16 v[64:67], v[232:235], v[172:175], v[64:67]
	v_mfma_f32_16x16x32_bf16 v[112:115], v[208:211], v[184:187], v[112:115]
	v_mfma_f32_16x16x32_bf16 v[56:59], v[232:235], v[184:187], v[56:59]
	v_mfma_f32_16x16x32_bf16 v[104:107], v[208:211], v[192:195], v[104:107]
	v_mfma_f32_16x16x32_bf16 v[40:43], v[232:235], v[192:195], v[40:43]
	v_mfma_f32_16x16x32_bf16 v[96:99], v[208:211], v[200:203], v[96:99]
	v_mfma_f32_16x16x32_bf16 v[32:35], v[232:235], v[200:203], v[32:35]
	s_setprio 0
	s_mov_b32 m0, s97
	s_barrier
	ds_read_b128 v[168:171], v179 offset:16384
	ds_read_b128 v[172:175], v179 offset:17408
	ds_read_b128 v[180:183], v179 offset:18432
	ds_read_b128 v[184:187], v179 offset:19456
	ds_read_b128 v[188:191], v179 offset:20480
	ds_read_b128 v[192:195], v179 offset:21504
	ds_read_b128 v[196:199], v179 offset:22528
	ds_read_b128 v[200:203], v179 offset:23552
	global_load_lds_dwordx4 v154, s[88:89]
	s_mov_b32 m0, s74
	s_nop 0
	global_load_lds_dwordx4 v156, s[88:89]
	s_barrier
	s_waitcnt lgkmcnt(0)
	s_setprio 1
	s_waitcnt lgkmcnt(0)
	v_mfma_f32_16x16x32_bf16 v[92:95], v[128:131], v[168:171], v[92:95]
	v_mfma_f32_16x16x32_bf16 v[28:31], v[136:139], v[168:171], v[28:31]
	v_mfma_f32_16x16x32_bf16 v[84:87], v[128:131], v[180:183], v[84:87]
	v_mfma_f32_16x16x32_bf16 v[20:23], v[136:139], v[180:183], v[20:23]
	v_mfma_f32_16x16x32_bf16 v[76:79], v[128:131], v[188:191], v[76:79]
	v_mfma_f32_16x16x32_bf16 v[12:15], v[136:139], v[188:191], v[12:15]
	v_mfma_f32_16x16x32_bf16 v[52:55], v[128:131], v[196:199], v[52:55]
	v_mfma_f32_16x16x32_bf16 v[4:7], v[136:139], v[196:199], v[4:7]
	v_mfma_f32_16x16x32_bf16 v[92:95], v[132:135], v[172:175], v[92:95]
	v_mfma_f32_16x16x32_bf16 v[28:31], v[164:167], v[172:175], v[28:31]
	v_mfma_f32_16x16x32_bf16 v[84:87], v[132:135], v[184:187], v[84:87]
	v_mfma_f32_16x16x32_bf16 v[20:23], v[164:167], v[184:187], v[20:23]
	v_mfma_f32_16x16x32_bf16 v[76:79], v[132:135], v[192:195], v[76:79]
	v_mfma_f32_16x16x32_bf16 v[12:15], v[164:167], v[192:195], v[12:15]
	v_mfma_f32_16x16x32_bf16 v[52:55], v[132:135], v[200:203], v[52:55]
	v_mfma_f32_16x16x32_bf16 v[4:7], v[164:167], v[200:203], v[4:7]
	s_setprio 0
	s_barrier
	s_add_u32 s18, s0, 0x10000
	s_addc_u32 s19, s1, 0
	s_add_i32 s2, s2, s59
	s_mov_b32 m0, s2
	s_nop 0
	global_load_lds_dwordx4 v140, s[18:19]
	s_add_i32 m0, s2, 0x2000
	s_nop 0
	global_load_lds_dwordx4 v158, s[18:19]
	s_waitcnt vmcnt(6)
	s_barrier
	s_setprio 1
	v_mfma_f32_16x16x32_bf16 v[88:91], v[204:207], v[168:171], v[88:91]
	v_mfma_f32_16x16x32_bf16 v[24:27], v[228:231], v[168:171], v[24:27]
	v_mfma_f32_16x16x32_bf16 v[80:83], v[204:207], v[180:183], v[80:83]
	v_mfma_f32_16x16x32_bf16 v[16:19], v[228:231], v[180:183], v[16:19]
	v_mfma_f32_16x16x32_bf16 v[72:75], v[204:207], v[188:191], v[72:75]
	v_mfma_f32_16x16x32_bf16 v[8:11], v[228:231], v[188:191], v[8:11]
	v_mfma_f32_16x16x32_bf16 v[48:51], v[204:207], v[196:199], v[48:51]
	v_mfma_f32_16x16x32_bf16 v[0:3], v[228:231], v[196:199], v[0:3]
	v_mfma_f32_16x16x32_bf16 v[88:91], v[208:211], v[172:175], v[88:91]
	v_mfma_f32_16x16x32_bf16 v[24:27], v[232:235], v[172:175], v[24:27]
	v_mfma_f32_16x16x32_bf16 v[80:83], v[208:211], v[184:187], v[80:83]
	v_mfma_f32_16x16x32_bf16 v[16:19], v[232:235], v[184:187], v[16:19]
	v_mfma_f32_16x16x32_bf16 v[72:75], v[208:211], v[192:195], v[72:75]
	v_mfma_f32_16x16x32_bf16 v[8:11], v[232:235], v[192:195], v[8:11]
	v_mfma_f32_16x16x32_bf16 v[48:51], v[208:211], v[200:203], v[48:51]
	v_mfma_f32_16x16x32_bf16 v[0:3], v[232:235], v[200:203], v[0:3]
	s_setprio 0
	s_add_i32 s2, 0, 0x18000
	v_add_u32_e32 v164, s2, v178
	s_barrier
	ds_read_b128 v[128:131], v164
	ds_read_b128 v[132:135], v164 offset:1024
	ds_read_b128 v[136:139], v164 offset:2048
	ds_read_b128 v[164:167], v164 offset:3072
	s_add_u32 s18, s88, 0x20000
	s_addc_u32 s19, s89, 0
	s_mov_b32 m0, s75
	ds_read_b128 v[168:171], v179 offset:32768
	ds_read_b128 v[172:175], v179 offset:33792
	ds_read_b128 v[180:183], v179 offset:34816
	ds_read_b128 v[184:187], v179 offset:35840
	ds_read_b128 v[188:191], v179 offset:36864
	ds_read_b128 v[192:195], v179 offset:37888
	ds_read_b128 v[196:199], v179 offset:38912
	ds_read_b128 v[200:203], v179 offset:39936
	global_load_lds_dwordx4 v154, s[18:19]
	s_mov_b32 m0, s72
	s_nop 0
	global_load_lds_dwordx4 v156, s[18:19]
	s_waitcnt lgkmcnt(8)
	s_barrier
	s_waitcnt lgkmcnt(0)
	s_setprio 1
	s_waitcnt lgkmcnt(0)
	v_mfma_f32_16x16x32_bf16 v[120:123], v[128:131], v[168:171], v[120:123]
	v_mfma_f32_16x16x32_bf16 v[68:71], v[136:139], v[168:171], v[68:71]
	v_mfma_f32_16x16x32_bf16 v[116:119], v[128:131], v[180:183], v[116:119]
	v_mfma_f32_16x16x32_bf16 v[60:63], v[136:139], v[180:183], v[60:63]
	v_mfma_f32_16x16x32_bf16 v[108:111], v[128:131], v[188:191], v[108:111]
	v_mfma_f32_16x16x32_bf16 v[44:47], v[136:139], v[188:191], v[44:47]
	v_mfma_f32_16x16x32_bf16 v[100:103], v[128:131], v[196:199], v[100:103]
	v_mfma_f32_16x16x32_bf16 v[36:39], v[136:139], v[196:199], v[36:39]
	v_mfma_f32_16x16x32_bf16 v[120:123], v[132:135], v[172:175], v[120:123]
	v_mfma_f32_16x16x32_bf16 v[68:71], v[164:167], v[172:175], v[68:71]
	v_mfma_f32_16x16x32_bf16 v[116:119], v[132:135], v[184:187], v[116:119]
	v_mfma_f32_16x16x32_bf16 v[60:63], v[164:167], v[184:187], v[60:63]
	v_mfma_f32_16x16x32_bf16 v[108:111], v[132:135], v[192:195], v[108:111]
	v_mfma_f32_16x16x32_bf16 v[44:47], v[164:167], v[192:195], v[44:47]
	v_mfma_f32_16x16x32_bf16 v[100:103], v[132:135], v[200:203], v[100:103]
	v_mfma_f32_16x16x32_bf16 v[36:39], v[164:167], v[200:203], v[36:39]
	s_setprio 0
	s_barrier
	s_add_i32 s18, 0, 0x1c000
	s_add_i32 s2, s2, s59
	v_add_u32_e32 v232, s18, v178
	s_mov_b32 m0, s2
	ds_read_b128 v[204:207], v232
	ds_read_b128 v[208:211], v232 offset:1024
	ds_read_b128 v[228:231], v232 offset:2048
	ds_read_b128 v[232:235], v232 offset:3072
	s_add_u32 s100, s0, 0x80
	s_addc_u32 s101, s1, 0
	global_load_lds_dwordx4 v140, s[100:101]
	s_add_i32 m0, s2, 0x2000
	s_nop 0
	global_load_lds_dwordx4 v158, s[100:101]
	s_barrier
	s_waitcnt lgkmcnt(0)
	s_setprio 1
	s_waitcnt lgkmcnt(0)
	v_mfma_f32_16x16x32_bf16 v[124:127], v[204:207], v[168:171], v[124:127]
	v_mfma_f32_16x16x32_bf16 v[64:67], v[228:231], v[168:171], v[64:67]
	v_mfma_f32_16x16x32_bf16 v[112:115], v[204:207], v[180:183], v[112:115]
	v_mfma_f32_16x16x32_bf16 v[56:59], v[228:231], v[180:183], v[56:59]
	v_mfma_f32_16x16x32_bf16 v[104:107], v[204:207], v[188:191], v[104:107]
	v_mfma_f32_16x16x32_bf16 v[40:43], v[228:231], v[188:191], v[40:43]
	v_mfma_f32_16x16x32_bf16 v[96:99], v[204:207], v[196:199], v[96:99]
	v_mfma_f32_16x16x32_bf16 v[32:35], v[228:231], v[196:199], v[32:35]
	v_mfma_f32_16x16x32_bf16 v[124:127], v[208:211], v[172:175], v[124:127]
	v_mfma_f32_16x16x32_bf16 v[64:67], v[232:235], v[172:175], v[64:67]
	v_mfma_f32_16x16x32_bf16 v[112:115], v[208:211], v[184:187], v[112:115]
	v_mfma_f32_16x16x32_bf16 v[56:59], v[232:235], v[184:187], v[56:59]
	v_mfma_f32_16x16x32_bf16 v[104:107], v[208:211], v[192:195], v[104:107]
	v_mfma_f32_16x16x32_bf16 v[40:43], v[232:235], v[192:195], v[40:43]
	v_mfma_f32_16x16x32_bf16 v[96:99], v[208:211], v[200:203], v[96:99]
	v_mfma_f32_16x16x32_bf16 v[32:35], v[232:235], v[200:203], v[32:35]
	s_setprio 0
	s_mov_b32 m0, s38
	s_barrier
	ds_read_b128 v[168:171], v179 offset:49152
	ds_read_b128 v[172:175], v179 offset:50176
	ds_read_b128 v[180:183], v179 offset:51200
	ds_read_b128 v[184:187], v179 offset:52224
	ds_read_b128 v[188:191], v179 offset:53248
	ds_read_b128 v[192:195], v179 offset:54272
	ds_read_b128 v[196:199], v179 offset:55296
	ds_read_b128 v[200:203], v179 offset:56320
	s_add_u32 s100, s88, 0x80
	s_addc_u32 s101, s89, 0
	global_load_lds_dwordx4 v154, s[100:101]
	s_mov_b32 m0, s39
	s_nop 0
	global_load_lds_dwordx4 v156, s[100:101]
	s_barrier
	s_waitcnt lgkmcnt(0)
	s_setprio 1
	s_waitcnt lgkmcnt(0)
	v_mfma_f32_16x16x32_bf16 v[92:95], v[128:131], v[168:171], v[92:95]
	v_mfma_f32_16x16x32_bf16 v[28:31], v[136:139], v[168:171], v[28:31]
	v_mfma_f32_16x16x32_bf16 v[84:87], v[128:131], v[180:183], v[84:87]
	v_mfma_f32_16x16x32_bf16 v[20:23], v[136:139], v[180:183], v[20:23]
	v_mfma_f32_16x16x32_bf16 v[76:79], v[128:131], v[188:191], v[76:79]
	v_mfma_f32_16x16x32_bf16 v[12:15], v[136:139], v[188:191], v[12:15]
	v_mfma_f32_16x16x32_bf16 v[52:55], v[128:131], v[196:199], v[52:55]
	v_mfma_f32_16x16x32_bf16 v[4:7], v[136:139], v[196:199], v[4:7]
	v_mfma_f32_16x16x32_bf16 v[92:95], v[132:135], v[172:175], v[92:95]
	v_mfma_f32_16x16x32_bf16 v[28:31], v[164:167], v[172:175], v[28:31]
	v_mfma_f32_16x16x32_bf16 v[84:87], v[132:135], v[184:187], v[84:87]
	v_mfma_f32_16x16x32_bf16 v[20:23], v[164:167], v[184:187], v[20:23]
	v_mfma_f32_16x16x32_bf16 v[76:79], v[132:135], v[192:195], v[76:79]
	v_mfma_f32_16x16x32_bf16 v[12:15], v[164:167], v[192:195], v[12:15]
	v_mfma_f32_16x16x32_bf16 v[52:55], v[132:135], v[200:203], v[52:55]
	v_mfma_f32_16x16x32_bf16 v[4:7], v[164:167], v[200:203], v[4:7]
	s_setprio 0
	s_barrier
	s_add_u32 s0, s0, 0x10080
	s_addc_u32 s1, s1, 0
	s_add_i32 s2, s18, s59
	s_mov_b32 m0, s2
	s_nop 0
	global_load_lds_dwordx4 v140, s[0:1]
	s_add_i32 m0, s2, 0x2000
	s_nop 0
	global_load_lds_dwordx4 v158, s[0:1]
	s_waitcnt vmcnt(6)
	s_barrier
	s_setprio 1
	v_mfma_f32_16x16x32_bf16 v[88:91], v[204:207], v[168:171], v[88:91]
	v_mfma_f32_16x16x32_bf16 v[24:27], v[228:231], v[168:171], v[24:27]
	v_mfma_f32_16x16x32_bf16 v[80:83], v[204:207], v[180:183], v[80:83]
	v_mfma_f32_16x16x32_bf16 v[16:19], v[228:231], v[180:183], v[16:19]
	v_mfma_f32_16x16x32_bf16 v[72:75], v[204:207], v[188:191], v[72:75]
	v_mfma_f32_16x16x32_bf16 v[8:11], v[228:231], v[188:191], v[8:11]
	v_mfma_f32_16x16x32_bf16 v[48:51], v[204:207], v[196:199], v[48:51]
	v_mfma_f32_16x16x32_bf16 v[0:3], v[228:231], v[196:199], v[0:3]
	v_mfma_f32_16x16x32_bf16 v[88:91], v[208:211], v[172:175], v[88:91]
	v_mfma_f32_16x16x32_bf16 v[24:27], v[232:235], v[172:175], v[24:27]
	v_mfma_f32_16x16x32_bf16 v[80:83], v[208:211], v[184:187], v[80:83]
	v_mfma_f32_16x16x32_bf16 v[16:19], v[232:235], v[184:187], v[16:19]
	v_mfma_f32_16x16x32_bf16 v[72:75], v[208:211], v[192:195], v[72:75]
	v_mfma_f32_16x16x32_bf16 v[8:11], v[232:235], v[192:195], v[8:11]
	v_mfma_f32_16x16x32_bf16 v[48:51], v[208:211], v[200:203], v[48:51]
	v_mfma_f32_16x16x32_bf16 v[0:3], v[232:235], v[200:203], v[0:3]
	s_setprio 0
	s_add_u32 s17, s17, 0x100
	s_addc_u32 s20, s20, 0
	s_add_u32 vcc_lo, vcc_lo, 0x100
	s_addc_u32 vcc_hi, vcc_hi, 0
	s_cmp_ge_i32 s21, s36
	s_mov_b32 s0, s21
	s_barrier
	s_cbranch_scc0 .LBB0_405
	s_branch .LBB0_392

.LBB0_507:
	s_add_u32 s0, s8, 0xfffc0080
	s_addc_u32 s1, s9, -1
	s_add_i32 s2, 0, 0x10000
	v_add_u32_e32 v140, s2, v168
	ds_read_b128 v[154:157], v140
	ds_read_b128 v[158:161], v140 offset:1024
	ds_read_b128 v[162:165], v140 offset:2048
	ds_read_b128 v[170:173], v140 offset:3072
	s_cmp_eq_u32 s21, 12
	s_cselect_b32 s31, s29, s1
	s_cselect_b32 s30, s28, s0
	s_cselect_b32 s1, s11, s19
	s_cselect_b32 s0, s10, s17
	s_add_i32 m0, s36, 0xc000
	ds_read_b128 v[174:177], v169
	ds_read_b128 v[178:181], v169 offset:1024
	ds_read_b128 v[182:185], v169 offset:2048
	ds_read_b128 v[186:189], v169 offset:3072
	ds_read_b128 v[190:193], v169 offset:4096
	ds_read_b128 v[194:197], v169 offset:5120
	ds_read_b128 v[198:201], v169 offset:6144
	ds_read_b128 v[202:205], v169 offset:7168
	global_load_lds_dwordx4 v138, s[8:9]
	s_add_i32 m0, s36, 0xe000
	s_nop 0
	global_load_lds_dwordx4 v136, s[8:9]
	s_waitcnt lgkmcnt(8)
	s_barrier
	s_waitcnt lgkmcnt(0)
	s_setprio 1
	s_waitcnt lgkmcnt(0)
	v_mfma_f32_16x16x32_bf16 v[124:127], v[154:157], v[174:177], v[124:127]
	v_mfma_f32_16x16x32_bf16 v[120:123], v[162:165], v[174:177], v[120:123]
	v_mfma_f32_16x16x32_bf16 v[112:115], v[154:157], v[182:185], v[112:115]
	v_mfma_f32_16x16x32_bf16 v[104:107], v[162:165], v[182:185], v[104:107]
	v_mfma_f32_16x16x32_bf16 v[96:99], v[154:157], v[190:193], v[96:99]
	v_mfma_f32_16x16x32_bf16 v[88:91], v[162:165], v[190:193], v[88:91]
	v_mfma_f32_16x16x32_bf16 v[80:83], v[154:157], v[198:201], v[80:83]
	v_mfma_f32_16x16x32_bf16 v[72:75], v[162:165], v[198:201], v[72:75]
	v_mfma_f32_16x16x32_bf16 v[124:127], v[158:161], v[178:181], v[124:127]
	v_mfma_f32_16x16x32_bf16 v[120:123], v[170:173], v[178:181], v[120:123]
	v_mfma_f32_16x16x32_bf16 v[112:115], v[158:161], v[186:189], v[112:115]
	v_mfma_f32_16x16x32_bf16 v[104:107], v[170:173], v[186:189], v[104:107]
	v_mfma_f32_16x16x32_bf16 v[96:99], v[158:161], v[194:197], v[96:99]
	v_mfma_f32_16x16x32_bf16 v[88:91], v[170:173], v[194:197], v[88:91]
	v_mfma_f32_16x16x32_bf16 v[80:83], v[158:161], v[202:205], v[80:83]
	v_mfma_f32_16x16x32_bf16 v[72:75], v[170:173], v[202:205], v[72:75]
	s_setprio 0
	s_barrier
	s_add_i32 s49, 0, 0x14000
	s_add_i32 s2, s2, s35
	v_add_u32_e32 v140, s49, v168
	s_mov_b32 m0, s2
	ds_read_b128 v[206:209], v140
	ds_read_b128 v[228:231], v140 offset:1024
	ds_read_b128 v[232:235], v140 offset:2048
	ds_read_b128 v[236:239], v140 offset:3072
	global_load_lds_dwordx4 v130, s[0:1]
	s_add_i32 m0, s2, 0x2000
	s_nop 0
	global_load_lds_dwordx4 v134, s[0:1]
	s_barrier
	s_waitcnt lgkmcnt(0)
	s_setprio 1
	s_waitcnt lgkmcnt(0)
	v_mfma_f32_16x16x32_bf16 v[116:119], v[206:209], v[174:177], v[116:119]
	v_mfma_f32_16x16x32_bf16 v[108:111], v[232:235], v[174:177], v[108:111]
	v_mfma_f32_16x16x32_bf16 v[100:103], v[206:209], v[182:185], v[100:103]
	v_mfma_f32_16x16x32_bf16 v[92:95], v[232:235], v[182:185], v[92:95]
	v_mfma_f32_16x16x32_bf16 v[84:87], v[206:209], v[190:193], v[84:87]
	v_mfma_f32_16x16x32_bf16 v[76:79], v[232:235], v[190:193], v[76:79]
	v_mfma_f32_16x16x32_bf16 v[68:71], v[206:209], v[198:201], v[68:71]
	v_mfma_f32_16x16x32_bf16 v[64:67], v[232:235], v[198:201], v[64:67]
	v_mfma_f32_16x16x32_bf16 v[116:119], v[228:231], v[178:181], v[116:119]
	v_mfma_f32_16x16x32_bf16 v[108:111], v[236:239], v[178:181], v[108:111]
	v_mfma_f32_16x16x32_bf16 v[100:103], v[228:231], v[186:189], v[100:103]
	v_mfma_f32_16x16x32_bf16 v[92:95], v[236:239], v[186:189], v[92:95]
	v_mfma_f32_16x16x32_bf16 v[84:87], v[228:231], v[194:197], v[84:87]
	v_mfma_f32_16x16x32_bf16 v[76:79], v[236:239], v[194:197], v[76:79]
	v_mfma_f32_16x16x32_bf16 v[68:71], v[228:231], v[202:205], v[68:71]
	v_mfma_f32_16x16x32_bf16 v[64:67], v[236:239], v[202:205], v[64:67]
	s_setprio 0
	s_mov_b32 m0, s36
	v_lshl_add_u64 v[240:241], s[30:31], 0, v[128:129]
	s_barrier
	ds_read_b128 v[174:177], v169 offset:16384
	ds_read_b128 v[178:181], v169 offset:17408
	ds_read_b128 v[182:185], v169 offset:18432
	ds_read_b128 v[186:189], v169 offset:19456
	ds_read_b128 v[190:193], v169 offset:20480
	ds_read_b128 v[194:197], v169 offset:21504
	ds_read_b128 v[198:201], v169 offset:22528
	ds_read_b128 v[202:205], v169 offset:23552
	global_load_lds_dwordx4 v128, s[30:31]
	v_lshl_add_u64 v[242:243], s[30:31], 0, v[132:133]
	s_mov_b32 m0, s37
	s_nop 0
	global_load_lds_dwordx4 v132, s[30:31]
	s_barrier
	s_waitcnt lgkmcnt(0)
	s_setprio 1
	s_waitcnt lgkmcnt(0)
	v_mfma_f32_16x16x32_bf16 v[60:63], v[154:157], v[174:177], v[60:63]
	v_mfma_f32_16x16x32_bf16 v[56:59], v[162:165], v[174:177], v[56:59]
	v_mfma_f32_16x16x32_bf16 v[48:51], v[154:157], v[182:185], v[48:51]
	v_mfma_f32_16x16x32_bf16 v[40:43], v[162:165], v[182:185], v[40:43]
	v_mfma_f32_16x16x32_bf16 v[32:35], v[154:157], v[190:193], v[32:35]
	v_mfma_f32_16x16x32_bf16 v[24:27], v[162:165], v[190:193], v[24:27]
	v_mfma_f32_16x16x32_bf16 v[16:19], v[154:157], v[198:201], v[16:19]
	v_mfma_f32_16x16x32_bf16 v[8:11], v[162:165], v[198:201], v[8:11]
	v_mfma_f32_16x16x32_bf16 v[60:63], v[158:161], v[178:181], v[60:63]
	v_mfma_f32_16x16x32_bf16 v[56:59], v[170:173], v[178:181], v[56:59]
	v_mfma_f32_16x16x32_bf16 v[48:51], v[158:161], v[186:189], v[48:51]
	v_mfma_f32_16x16x32_bf16 v[40:43], v[170:173], v[186:189], v[40:43]
	v_mfma_f32_16x16x32_bf16 v[32:35], v[158:161], v[194:197], v[32:35]
	v_mfma_f32_16x16x32_bf16 v[24:27], v[170:173], v[194:197], v[24:27]
	v_mfma_f32_16x16x32_bf16 v[16:19], v[158:161], v[202:205], v[16:19]
	v_mfma_f32_16x16x32_bf16 v[8:11], v[170:173], v[202:205], v[8:11]
	s_setprio 0
	s_barrier
	s_add_u32 s42, s0, 0x40000
	s_addc_u32 s43, s1, 0
	s_add_i32 s2, s49, s35
	s_mov_b32 m0, s2
	s_nop 0
	global_load_lds_dwordx4 v130, s[42:43]
	s_add_i32 m0, s2, 0x2000
	s_nop 0
	global_load_lds_dwordx4 v134, s[42:43]
	s_waitcnt vmcnt(6)
	s_barrier
	s_setprio 1
	v_mfma_f32_16x16x32_bf16 v[52:55], v[206:209], v[174:177], v[52:55]
	v_mfma_f32_16x16x32_bf16 v[44:47], v[232:235], v[174:177], v[44:47]
	v_mfma_f32_16x16x32_bf16 v[36:39], v[206:209], v[182:185], v[36:39]
	v_mfma_f32_16x16x32_bf16 v[28:31], v[232:235], v[182:185], v[28:31]
	v_mfma_f32_16x16x32_bf16 v[20:23], v[206:209], v[190:193], v[20:23]
	v_mfma_f32_16x16x32_bf16 v[12:15], v[232:235], v[190:193], v[12:15]
	v_mfma_f32_16x16x32_bf16 v[4:7], v[206:209], v[198:201], v[4:7]
	v_mfma_f32_16x16x32_bf16 v[0:3], v[232:235], v[198:201], v[0:3]
	v_mfma_f32_16x16x32_bf16 v[52:55], v[228:231], v[178:181], v[52:55]
	v_mfma_f32_16x16x32_bf16 v[44:47], v[236:239], v[178:181], v[44:47]
	v_mfma_f32_16x16x32_bf16 v[36:39], v[228:231], v[186:189], v[36:39]
	v_mfma_f32_16x16x32_bf16 v[28:31], v[236:239], v[186:189], v[28:31]
	v_mfma_f32_16x16x32_bf16 v[20:23], v[228:231], v[194:197], v[20:23]
	v_mfma_f32_16x16x32_bf16 v[12:15], v[236:239], v[194:197], v[12:15]
	v_mfma_f32_16x16x32_bf16 v[4:7], v[228:231], v[202:205], v[4:7]
	v_mfma_f32_16x16x32_bf16 v[0:3], v[236:239], v[202:205], v[0:3]
	s_setprio 0
	s_add_i32 s2, 0, 0x18000
	v_add_u32_e32 v140, s2, v168
	s_barrier
	ds_read_b128 v[154:157], v140
	ds_read_b128 v[158:161], v140 offset:1024
	ds_read_b128 v[162:165], v140 offset:2048
	ds_read_b128 v[170:173], v140 offset:3072
	s_add_u32 s30, s30, 0x40000
	s_addc_u32 s31, s31, 0
	s_mov_b32 m0, s38
	ds_read_b128 v[174:177], v169 offset:32768
	ds_read_b128 v[178:181], v169 offset:33792
	ds_read_b128 v[182:185], v169 offset:34816
	ds_read_b128 v[186:189], v169 offset:35840
	ds_read_b128 v[190:193], v169 offset:36864
	ds_read_b128 v[194:197], v169 offset:37888
	ds_read_b128 v[198:201], v169 offset:38912
	ds_read_b128 v[202:205], v169 offset:39936
	global_load_lds_dwordx4 v128, s[30:31]
	s_mov_b32 m0, s39
	s_nop 0
	global_load_lds_dwordx4 v132, s[30:31]
	s_waitcnt lgkmcnt(8)
	s_barrier
	s_waitcnt lgkmcnt(0)
	s_setprio 1
	s_waitcnt lgkmcnt(0)
	v_mfma_f32_16x16x32_bf16 v[124:127], v[154:157], v[174:177], v[124:127]
	v_mfma_f32_16x16x32_bf16 v[120:123], v[162:165], v[174:177], v[120:123]
	v_mfma_f32_16x16x32_bf16 v[112:115], v[154:157], v[182:185], v[112:115]
	v_mfma_f32_16x16x32_bf16 v[104:107], v[162:165], v[182:185], v[104:107]
	v_mfma_f32_16x16x32_bf16 v[96:99], v[154:157], v[190:193], v[96:99]
	v_mfma_f32_16x16x32_bf16 v[88:91], v[162:165], v[190:193], v[88:91]
	v_mfma_f32_16x16x32_bf16 v[80:83], v[154:157], v[198:201], v[80:83]
	v_mfma_f32_16x16x32_bf16 v[72:75], v[162:165], v[198:201], v[72:75]
	v_mfma_f32_16x16x32_bf16 v[124:127], v[158:161], v[178:181], v[124:127]
	v_mfma_f32_16x16x32_bf16 v[120:123], v[170:173], v[178:181], v[120:123]
	v_mfma_f32_16x16x32_bf16 v[112:115], v[158:161], v[186:189], v[112:115]
	v_mfma_f32_16x16x32_bf16 v[104:107], v[170:173], v[186:189], v[104:107]
	v_mfma_f32_16x16x32_bf16 v[96:99], v[158:161], v[194:197], v[96:99]
	v_mfma_f32_16x16x32_bf16 v[88:91], v[170:173], v[194:197], v[88:91]
	v_mfma_f32_16x16x32_bf16 v[80:83], v[158:161], v[202:205], v[80:83]
	v_mfma_f32_16x16x32_bf16 v[72:75], v[170:173], v[202:205], v[72:75]
	s_setprio 0
	s_barrier
	s_add_i32 s30, 0, 0x1c000
	s_add_i32 s2, s2, s35
	v_add_u32_e32 v140, s30, v168
	s_mov_b32 m0, s2
	ds_read_b128 v[206:209], v140
	ds_read_b128 v[228:231], v140 offset:1024
	ds_read_b128 v[232:235], v140 offset:2048
	ds_read_b128 v[236:239], v140 offset:3072
	s_add_u32 s100, s0, 0x80
	s_addc_u32 s101, s1, 0
	global_load_lds_dwordx4 v130, s[100:101]
	s_add_i32 m0, s2, 0x2000
	s_nop 0
	global_load_lds_dwordx4 v134, s[100:101]
	s_barrier
	s_waitcnt lgkmcnt(0)
	s_setprio 1
	s_waitcnt lgkmcnt(0)
	v_mfma_f32_16x16x32_bf16 v[116:119], v[206:209], v[174:177], v[116:119]
	v_mfma_f32_16x16x32_bf16 v[108:111], v[232:235], v[174:177], v[108:111]
	v_mfma_f32_16x16x32_bf16 v[100:103], v[206:209], v[182:185], v[100:103]
	v_mfma_f32_16x16x32_bf16 v[92:95], v[232:235], v[182:185], v[92:95]
	v_mfma_f32_16x16x32_bf16 v[84:87], v[206:209], v[190:193], v[84:87]
	v_mfma_f32_16x16x32_bf16 v[76:79], v[232:235], v[190:193], v[76:79]
	v_mfma_f32_16x16x32_bf16 v[68:71], v[206:209], v[198:201], v[68:71]
	v_mfma_f32_16x16x32_bf16 v[64:67], v[232:235], v[198:201], v[64:67]
	v_mfma_f32_16x16x32_bf16 v[116:119], v[228:231], v[178:181], v[116:119]
	v_mfma_f32_16x16x32_bf16 v[108:111], v[236:239], v[178:181], v[108:111]
	v_mfma_f32_16x16x32_bf16 v[100:103], v[228:231], v[186:189], v[100:103]
	v_mfma_f32_16x16x32_bf16 v[92:95], v[236:239], v[186:189], v[92:95]
	v_mfma_f32_16x16x32_bf16 v[84:87], v[228:231], v[194:197], v[84:87]
	v_mfma_f32_16x16x32_bf16 v[76:79], v[236:239], v[194:197], v[76:79]
	v_mfma_f32_16x16x32_bf16 v[68:71], v[228:231], v[202:205], v[68:71]
	v_mfma_f32_16x16x32_bf16 v[64:67], v[236:239], v[202:205], v[64:67]
	s_setprio 0
	s_mov_b32 m0, s44
	v_lshl_add_u64 v[166:167], v[240:241], 0, s[82:83]
	s_barrier
	ds_read_b128 v[174:177], v169 offset:49152
	ds_read_b128 v[178:181], v169 offset:50176
	ds_read_b128 v[182:185], v169 offset:51200
	ds_read_b128 v[186:189], v169 offset:52224
	ds_read_b128 v[190:193], v169 offset:53248
	ds_read_b128 v[194:197], v169 offset:54272
	ds_read_b128 v[198:201], v169 offset:55296
	ds_read_b128 v[202:205], v169 offset:56320
	global_load_lds_dwordx4 v[166:167], off
	v_lshl_add_u64 v[166:167], v[242:243], 0, s[82:83]
	s_mov_b32 m0, s45
	s_nop 0
	global_load_lds_dwordx4 v[166:167], off
	s_barrier
	s_waitcnt lgkmcnt(0)
	s_setprio 1
	s_waitcnt lgkmcnt(0)
	v_mfma_f32_16x16x32_bf16 v[60:63], v[154:157], v[174:177], v[60:63]
	v_mfma_f32_16x16x32_bf16 v[56:59], v[162:165], v[174:177], v[56:59]
	v_mfma_f32_16x16x32_bf16 v[48:51], v[154:157], v[182:185], v[48:51]
	v_mfma_f32_16x16x32_bf16 v[40:43], v[162:165], v[182:185], v[40:43]
	v_mfma_f32_16x16x32_bf16 v[32:35], v[154:157], v[190:193], v[32:35]
	v_mfma_f32_16x16x32_bf16 v[24:27], v[162:165], v[190:193], v[24:27]
	v_mfma_f32_16x16x32_bf16 v[16:19], v[154:157], v[198:201], v[16:19]
	v_mfma_f32_16x16x32_bf16 v[8:11], v[162:165], v[198:201], v[8:11]
	v_mfma_f32_16x16x32_bf16 v[60:63], v[158:161], v[178:181], v[60:63]
	v_mfma_f32_16x16x32_bf16 v[56:59], v[170:173], v[178:181], v[56:59]
	v_mfma_f32_16x16x32_bf16 v[48:51], v[158:161], v[186:189], v[48:51]
	v_mfma_f32_16x16x32_bf16 v[40:43], v[170:173], v[186:189], v[40:43]
	v_mfma_f32_16x16x32_bf16 v[32:35], v[158:161], v[194:197], v[32:35]
	v_mfma_f32_16x16x32_bf16 v[24:27], v[170:173], v[194:197], v[24:27]
	v_mfma_f32_16x16x32_bf16 v[16:19], v[158:161], v[202:205], v[16:19]
	v_mfma_f32_16x16x32_bf16 v[8:11], v[170:173], v[202:205], v[8:11]
	s_setprio 0
	s_barrier
	s_add_u32 s0, s0, 0x40080
	s_addc_u32 s1, s1, 0
	s_add_i32 s2, s30, s35
	s_mov_b32 m0, s2
	s_nop 0
	global_load_lds_dwordx4 v130, s[0:1]
	s_add_i32 m0, s2, 0x2000
	s_nop 0
	global_load_lds_dwordx4 v134, s[0:1]
	s_waitcnt vmcnt(6)
	s_barrier
	s_setprio 1
	v_mfma_f32_16x16x32_bf16 v[52:55], v[206:209], v[174:177], v[52:55]
	v_mfma_f32_16x16x32_bf16 v[44:47], v[232:235], v[174:177], v[44:47]
	v_mfma_f32_16x16x32_bf16 v[36:39], v[206:209], v[182:185], v[36:39]
	v_mfma_f32_16x16x32_bf16 v[28:31], v[232:235], v[182:185], v[28:31]
	v_mfma_f32_16x16x32_bf16 v[20:23], v[206:209], v[190:193], v[20:23]
	v_mfma_f32_16x16x32_bf16 v[12:15], v[232:235], v[190:193], v[12:15]
	v_mfma_f32_16x16x32_bf16 v[4:7], v[206:209], v[198:201], v[4:7]
	v_mfma_f32_16x16x32_bf16 v[0:3], v[232:235], v[198:201], v[0:3]
	v_mfma_f32_16x16x32_bf16 v[52:55], v[228:231], v[178:181], v[52:55]
	v_mfma_f32_16x16x32_bf16 v[44:47], v[236:239], v[178:181], v[44:47]
	v_mfma_f32_16x16x32_bf16 v[36:39], v[228:231], v[186:189], v[36:39]
	v_mfma_f32_16x16x32_bf16 v[28:31], v[236:239], v[186:189], v[28:31]
	v_mfma_f32_16x16x32_bf16 v[20:23], v[228:231], v[194:197], v[20:23]
	v_mfma_f32_16x16x32_bf16 v[12:15], v[236:239], v[194:197], v[12:15]
	v_mfma_f32_16x16x32_bf16 v[4:7], v[228:231], v[202:205], v[4:7]
	v_mfma_f32_16x16x32_bf16 v[0:3], v[236:239], v[202:205], v[0:3]
	s_setprio 0
	s_add_i32 s21, s21, 2
	s_add_u32 s17, s17, 0x100
	s_addc_u32 s19, s19, 0
	s_add_u32 s8, s8, 0x100
	s_addc_u32 s9, s9, 0
	s_cmp_gt_u32 s21, 13
	s_barrier
	s_cbranch_scc0 .LBB0_507
	v_mbcnt_lo_u32_b32 v154, -1, 0
	v_mbcnt_hi_u32_b32 v154, -1, v154
	s_lshl_b32 s19, s16, 8
	v_and_b32_e32 v140, 15, v154
	v_ashrrev_i32_e32 v154, 1, v154
	s_cmp_lt_i32 s48, 8
	v_and_b32_e32 v170, -8, v154
	s_mov_b64 s[0:1], -1
	s_cbranch_scc0 .LBB0_552
	s_ashr_i32 s2, s48, 1
	s_mov_b32 s30, 0x3e38aa3b
	s_cmp_lt_u32 s48, 2
	s_mov_b64 s[8:9], s[24:25]
	s_cbranch_scc1 .LBB0_519
	s_cmp_lt_i32 s2, 2
	s_cbranch_scc1 .LBB0_514
	s_cmp_eq_u32 s2, 2
	s_cbranch_scc0 .LBB0_513
	s_mov_b64 s[0:1], 0

	.amdhsa_kernel _Z14fwd_megakernel6Params
		.amdhsa_group_segment_fixed_size 0
		.amdhsa_private_segment_fixed_size 0
		.amdhsa_kernarg_size 544
		.amdhsa_user_sgpr_count 2
		.amdhsa_user_sgpr_dispatch_ptr 0
		.amdhsa_user_sgpr_queue_ptr 0
		.amdhsa_user_sgpr_kernarg_segment_ptr 1
		.amdhsa_user_sgpr_dispatch_id 0
		.amdhsa_user_sgpr_kernarg_preload_length 0
		.amdhsa_user_sgpr_kernarg_preload_offset 0
		.amdhsa_user_sgpr_private_segment_size 0
		.amdhsa_uses_dynamic_stack 0
		.amdhsa_enable_private_segment 0
		.amdhsa_system_sgpr_workgroup_id_x 1
		.amdhsa_system_sgpr_workgroup_id_y 0
		.amdhsa_system_sgpr_workgroup_id_z 0
		.amdhsa_system_sgpr_workgroup_info 0
		.amdhsa_system_vgpr_workitem_id 2
		.amdhsa_next_free_vgpr 254
		.amdhsa_next_free_sgpr 102
		.amdhsa_accum_offset 256
		.amdhsa_reserve_vcc 1
		.amdhsa_float_round_mode_32 0
		.amdhsa_float_round_mode_16_64 0
		.amdhsa_float_denorm_mode_32 3
		.amdhsa_float_denorm_mode_16_64 3
		.amdhsa_dx10_clamp 1
		.amdhsa_ieee_mode 1
		.amdhsa_fp16_overflow 0
		.amdhsa_tg_split 0
		.amdhsa_exception_fp_ieee_invalid_op 0
		.amdhsa_exception_fp_denorm_src 0
		.amdhsa_exception_fp_ieee_div_zero 0
		.amdhsa_exception_fp_ieee_overflow 0
		.amdhsa_exception_fp_ieee_underflow 0
		.amdhsa_exception_fp_ieee_inexact 0
		.amdhsa_exception_int_div_zero 0
	.end_amdhsa_kernel

amdhsa.kernels:
  - .agpr_count:     0
    .args:
      - .offset:         0
        .size:           288
        .value_kind:     by_value
      - .offset:         288
        .size:           4
        .value_kind:     hidden_block_count_x
      - .offset:         292
        .size:           4
        .value_kind:     hidden_block_count_y
      - .offset:         296
        .size:           4
        .value_kind:     hidden_block_count_z
      - .offset:         300
        .size:           2
        .value_kind:     hidden_group_size_x
      - .offset:         302
        .size:           2
        .value_kind:     hidden_group_size_y
      - .offset:         304
        .size:           2
        .value_kind:     hidden_group_size_z
      - .offset:         306
        .size:           2
        .value_kind:     hidden_remainder_x
      - .offset:         308
        .size:           2
        .value_kind:     hidden_remainder_y
      - .offset:         310
        .size:           2
        .value_kind:     hidden_remainder_z
      - .offset:         328
        .size:           8
        .value_kind:     hidden_global_offset_x
      - .offset:         336
        .size:           8
        .value_kind:     hidden_global_offset_y
      - .offset:         344
        .size:           8
        .value_kind:     hidden_global_offset_z
      - .offset:         352
        .size:           2
        .value_kind:     hidden_grid_dims
      - .offset:         376
        .size:           8
        .value_kind:     hidden_multigrid_sync_arg
      - .offset:         408
        .size:           4
        .value_kind:     hidden_dynamic_lds_size
    .group_segment_fixed_size: 0
    .kernarg_segment_align: 8
    .kernarg_segment_size: 544
    .language:       OpenCL C
    .language_version:
      - 2
      - 0
    .max_flat_workgroup_size: 512
    .name:           _Z14fwd_megakernel6Params
    .private_segment_fixed_size: 0
    .sgpr_count:     108
    .sgpr_spill_count: 112
    .symbol:         _Z14fwd_megakernel6Params.kd
    .uniform_work_group_size: 1
    .uses_dynamic_stack: false
    .vgpr_count:     254
    .vgpr_spill_count: 0
    .wavefront_size: 64
